# GEMM K-loops: no VALU at the head of a read segment - LDS read-address adds moved to the tail of the preceding MFMA segment / in front of the loop, leading SALU moved behind the first reads
# baseline (speedup 1.0000x reference)
; #define PG8_STAGE(bufoff, gbase, voff) do { _Pragma("unroll") for (int _i = 0; _i < 2; ++_i) \
;         __builtin_amdgcn_global_load_lds((const unsigned*)((const char*)(gbase) + (voff)[_i]), (PG8_LAS unsigned*)(lds + (bufoff) + ldsw + _i * 8192), 16, 0, 0); } while (0)
; #define PG8_LDA(dst, b, h) do { _Pragma("unroll") for (int m = 0; m < 4; ++m) _Pragma("unroll") for (int k = 0; k < 2; ++k) dst[m][k] = *(const PG8_LAS bf16x8*)(lds + PG8_SA(b, h) + aoff + m * 2048 + k * 1024); } while (0)
; #define PG8_LDB(dst, b, h) do { _Pragma("unroll") for (int n = 0; n < 2; ++n) _Pragma("unroll") for (int k = 0; k < 2; ++k) dst[n][k] = *(const PG8_LAS bf16x8*)(lds + PG8_SB(b, h) + boff + n * 2048 + k * 1024); } while (0)
; #define PG8_MMA(ai, bj, At, Bt) do { __builtin_amdgcn_s_setprio(1); _Pragma("unroll") for (int m = 0; m < 4; ++m) _Pragma("unroll") for (int n = 0; n < 2; ++n) _Pragma("unroll") for (int k = 0; k < 2; ++k) \
;         acc[ai][bj][m][n] = __builtin_amdgcn_mfma_f32_16x16x32_bf16(Bt[n][k], At[m][k], acc[ai][bj][m][n], 0, 0, 0); __builtin_amdgcn_s_setprio(0); } while (0)
; #define PG8_WAIT_L(n) asm volatile("s_waitcnt lgkmcnt(" #n ")" ::: "memory")
; template <class Epi, class Sched>
; __device__ __forceinline__ void gemm_phase(PG8_LAS unsigned char* lds, const Gemm g, const Sched& S, const Epi& E) {
;     ...
;     f32x4 acc[2][2][4][2];
; #pragma unroll
;     for (int a = 0; a < 2; ++a)
; #pragma unroll
;         for (int b = 0; b < 2; ++b)
; #pragma unroll
;             for (int m = 0; m < 4; ++m)
; #pragma unroll
;                 for (int n = 0; n < 2; ++n) acc[a][b][m][n] = (f32x4){0.f, 0.f, 0.f, 0.f};
;     ...
;         for (int t = 0; t < nt; t += 2) {
;             const bool last = (t == nt - 2);
;             const char* a1 = cA + (size_t)(t + 1) * kstep;
;             const char* a2 = last ? nA : cA + (size_t)(t + 2) * kstep; const char* b2 = last ? nB : cB + (size_t)(t + 2) * kstep;
;             const char* a3 = a2 + kstep; const char* b3 = b2 + kstep;
;             if (last && has_next) S.a_ready(nxt);
;             PG8_LDB(B0, 0, 0); PG8_SCHED; PG8_LDA(At, 0, 0); PG8_STAGE(PG8_SA(1, 1), a1 + hstep, voffA);
;             PG8_WAIT_L(8); PG8_BAR; PG8_WAIT_L(0); PG8_MMA(0, 0, At, B0); PG8_BAR; PG8_SCHED;
;             PG8_LDB(B1, 0, 1); PG8_STAGE(PG8_SB(0, 0), b2, voffB);
;             PG8_BAR; PG8_WAIT_L(0); PG8_MMA(0, 1, At, B1); PG8_BAR;
.LBB0_95:
	s_add_u32 s43, s10, 0x100
	v_mov_b32_e32 v0, 0
	s_addc_u32 s44, s11, 0
	s_mov_b32 s45, -2
	v_mov_b32_e32 v1, v0
	v_mov_b32_e32 v2, v0
	v_mov_b32_e32 v3, v0
	v_mov_b32_e32 v4, v0
	v_mov_b32_e32 v5, v0
	v_mov_b32_e32 v6, v0
	v_mov_b32_e32 v7, v0
	v_mov_b32_e32 v8, v0
	v_mov_b32_e32 v9, v0
	v_mov_b32_e32 v10, v0
	v_mov_b32_e32 v11, v0
	v_mov_b32_e32 v12, v0
	v_mov_b32_e32 v13, v0
	v_mov_b32_e32 v14, v0
	v_mov_b32_e32 v15, v0
	v_mov_b32_e32 v24, v0
	v_mov_b32_e32 v25, v0
	v_mov_b32_e32 v26, v0
	v_mov_b32_e32 v27, v0
	v_mov_b32_e32 v28, v0
	v_mov_b32_e32 v29, v0
	v_mov_b32_e32 v30, v0
	v_mov_b32_e32 v31, v0
	v_mov_b32_e32 v40, v0
	v_mov_b32_e32 v41, v0
	v_mov_b32_e32 v42, v0
	v_mov_b32_e32 v43, v0
	v_mov_b32_e32 v44, v0
	v_mov_b32_e32 v45, v0
	v_mov_b32_e32 v46, v0
	v_mov_b32_e32 v47, v0
	v_mov_b32_e32 v16, v0
	v_mov_b32_e32 v17, v0
	v_mov_b32_e32 v18, v0
	v_mov_b32_e32 v19, v0
	v_mov_b32_e32 v20, v0
	v_mov_b32_e32 v21, v0
	v_mov_b32_e32 v22, v0
	v_mov_b32_e32 v23, v0
	v_mov_b32_e32 v32, v0
	v_mov_b32_e32 v33, v0
	v_mov_b32_e32 v34, v0
	v_mov_b32_e32 v35, v0
	v_mov_b32_e32 v36, v0
	v_mov_b32_e32 v37, v0
	v_mov_b32_e32 v38, v0
	v_mov_b32_e32 v39, v0
	v_mov_b32_e32 v48, v0
	v_mov_b32_e32 v49, v0
	v_mov_b32_e32 v50, v0
	v_mov_b32_e32 v51, v0
	v_mov_b32_e32 v52, v0
	v_mov_b32_e32 v53, v0
	v_mov_b32_e32 v54, v0
	v_mov_b32_e32 v55, v0
	v_mov_b32_e32 v56, v0
	v_mov_b32_e32 v57, v0
	v_mov_b32_e32 v58, v0
	v_mov_b32_e32 v59, v0
	v_mov_b32_e32 v60, v0
	v_mov_b32_e32 v61, v0
	v_mov_b32_e32 v62, v0
	v_mov_b32_e32 v63, v0
	v_mov_b32_e32 v64, v0
	v_mov_b32_e32 v65, v0
	v_mov_b32_e32 v66, v0
	v_mov_b32_e32 v67, v0
	v_mov_b32_e32 v68, v0
	v_mov_b32_e32 v69, v0
	v_mov_b32_e32 v70, v0
	v_mov_b32_e32 v71, v0
	v_mov_b32_e32 v72, v0
	v_mov_b32_e32 v73, v0
	v_mov_b32_e32 v74, v0
	v_mov_b32_e32 v75, v0
	v_mov_b32_e32 v76, v0
	v_mov_b32_e32 v77, v0
	v_mov_b32_e32 v78, v0
	v_mov_b32_e32 v79, v0
	v_mov_b32_e32 v88, v0
	v_mov_b32_e32 v89, v0
	v_mov_b32_e32 v90, v0
	v_mov_b32_e32 v91, v0
	v_mov_b32_e32 v92, v0
	v_mov_b32_e32 v93, v0
	v_mov_b32_e32 v94, v0
	v_mov_b32_e32 v95, v0
	v_mov_b32_e32 v104, v0
	v_mov_b32_e32 v105, v0
	v_mov_b32_e32 v106, v0
	v_mov_b32_e32 v107, v0
	v_mov_b32_e32 v108, v0
	v_mov_b32_e32 v109, v0
	v_mov_b32_e32 v110, v0
	v_mov_b32_e32 v111, v0
	v_mov_b32_e32 v80, v0
	v_mov_b32_e32 v81, v0
	v_mov_b32_e32 v82, v0
	v_mov_b32_e32 v83, v0
	v_mov_b32_e32 v84, v0
	v_mov_b32_e32 v85, v0
	v_mov_b32_e32 v86, v0
	v_mov_b32_e32 v87, v0
	v_mov_b32_e32 v96, v0
	v_mov_b32_e32 v97, v0
	v_mov_b32_e32 v98, v0
	v_mov_b32_e32 v99, v0
	v_mov_b32_e32 v100, v0
	v_mov_b32_e32 v101, v0
	v_mov_b32_e32 v102, v0
	v_mov_b32_e32 v103, v0
	v_mov_b32_e32 v112, v0
	v_mov_b32_e32 v113, v0
	v_mov_b32_e32 v114, v0
	v_mov_b32_e32 v115, v0
	v_mov_b32_e32 v116, v0
	v_mov_b32_e32 v117, v0
	v_mov_b32_e32 v118, v0
	v_mov_b32_e32 v119, v0
	v_mov_b32_e32 v120, v0
	v_mov_b32_e32 v121, v0
	v_mov_b32_e32 v122, v0
	v_mov_b32_e32 v123, v0
	v_mov_b32_e32 v124, v0
	v_mov_b32_e32 v125, v0
	v_mov_b32_e32 v126, v0
	v_mov_b32_e32 v127, v0
	v_add_u32_e32 v154, 0x10000, v139
	v_add_u32_e32 v174, 0x14000, v139
.LBB0_96:
	ds_read_b128 v[142:145], v154
	ds_read_b128 v[146:149], v154 offset:1024
	ds_read_b128 v[150:153], v154 offset:2048
	ds_read_b128 v[154:157], v154 offset:3072
	s_add_u32 s10, s8, 0x100
	s_addc_u32 s11, s9, 0
	s_cmp_eq_u32 s45, 40
	s_cselect_b32 s15, s1, s11
	s_cselect_b32 s14, s0, s10
	s_cselect_b32 s13, s5, s44
	s_cselect_b32 s12, s4, s43
	s_add_i32 m0, s20, 0xc000
	ds_read_b128 v[158:161], v141
	ds_read_b128 v[162:165], v141 offset:1024
	ds_read_b128 v[166:169], v141 offset:2048
	ds_read_b128 v[170:173], v141 offset:3072
	ds_read_b128 v[178:181], v141 offset:4096
	ds_read_b128 v[182:185], v141 offset:5120
	ds_read_b128 v[186:189], v141 offset:6144
	global_load_lds_dwordx4 v134, s[8:9]
	s_add_i32 m0, s20, 0xe000
	ds_read_b128 v[190:193], v141 offset:7168
	global_load_lds_dwordx4 v136, s[8:9]
	s_waitcnt lgkmcnt(8)
	s_barrier
	s_waitcnt lgkmcnt(7)
	v_mfma_f32_16x16x32_bf16 v[124:127], v[142:145], v[158:161], v[124:127]
	v_mfma_f32_16x16x32_bf16 v[120:123], v[150:153], v[158:161], v[120:123]
	s_waitcnt lgkmcnt(5)
	v_mfma_f32_16x16x32_bf16 v[116:119], v[142:145], v[166:169], v[116:119]
	v_mfma_f32_16x16x32_bf16 v[112:115], v[150:153], v[166:169], v[112:115]
	s_waitcnt lgkmcnt(3)
	v_mfma_f32_16x16x32_bf16 v[100:103], v[142:145], v[178:181], v[100:103]
	v_mfma_f32_16x16x32_bf16 v[96:99], v[150:153], v[178:181], v[96:99]
	s_waitcnt lgkmcnt(1)
	v_mfma_f32_16x16x32_bf16 v[84:87], v[142:145], v[186:189], v[84:87]
	v_mfma_f32_16x16x32_bf16 v[80:83], v[150:153], v[186:189], v[80:83]
	v_mfma_f32_16x16x32_bf16 v[124:127], v[146:149], v[162:165], v[124:127]
	v_mfma_f32_16x16x32_bf16 v[120:123], v[154:157], v[162:165], v[120:123]
	v_mfma_f32_16x16x32_bf16 v[116:119], v[146:149], v[170:173], v[116:119]
	v_mfma_f32_16x16x32_bf16 v[112:115], v[154:157], v[170:173], v[112:115]
	v_mfma_f32_16x16x32_bf16 v[100:103], v[146:149], v[182:185], v[100:103]
	v_mfma_f32_16x16x32_bf16 v[96:99], v[154:157], v[182:185], v[96:99]
	s_waitcnt lgkmcnt(0)
	v_mfma_f32_16x16x32_bf16 v[84:87], v[146:149], v[190:193], v[84:87]
	v_mfma_f32_16x16x32_bf16 v[80:83], v[154:157], v[190:193], v[80:83]
	s_barrier
	s_add_i32 s47, 0, 0x14000
	ds_read_b128 v[194:197], v174
	ds_read_b128 v[198:201], v174 offset:1024
	s_add_u32 s98, s12, 0x80
	s_addc_u32 s99, s13, 0
	s_add_i32 m0, s18, 0x10000
	ds_read_b128 v[202:205], v174 offset:2048
	global_load_lds_dwordx4 v176, s[12:13]
	s_add_i32 m0, s18, 0x12000
	ds_read_b128 v[206:209], v174 offset:3072
	global_load_lds_dwordx4 v128, s[12:13]
	s_barrier
; #define PG8_STAGE(bufoff, gbase, voff) do { _Pragma("unroll") for (int _i = 0; _i < 2; ++_i) \
;         __builtin_amdgcn_global_load_lds((const unsigned*)((const char*)(gbase) + (voff)[_i]), (PG8_LAS unsigned*)(lds + (bufoff) + ldsw + _i * 8192), 16, 0, 0); } while (0)
; #define PG8_LDA(dst, b, h) do { _Pragma("unroll") for (int m = 0; m < 4; ++m) _Pragma("unroll") for (int k = 0; k < 2; ++k) dst[m][k] = *(const PG8_LAS bf16x8*)(lds + PG8_SA(b, h) + aoff + m * 2048 + k * 1024); } while (0)
; #define PG8_LDB(dst, b, h) do { _Pragma("unroll") for (int n = 0; n < 2; ++n) _Pragma("unroll") for (int k = 0; k < 2; ++k) dst[n][k] = *(const PG8_LAS bf16x8*)(lds + PG8_SB(b, h) + boff + n * 2048 + k * 1024); } while (0)
; #define PG8_MMA(ai, bj, At, Bt) do { __builtin_amdgcn_s_setprio(1); _Pragma("unroll") for (int m = 0; m < 4; ++m) _Pragma("unroll") for (int n = 0; n < 2; ++n) _Pragma("unroll") for (int k = 0; k < 2; ++k) \
;         acc[ai][bj][m][n] = __builtin_amdgcn_mfma_f32_16x16x32_bf16(Bt[n][k], At[m][k], acc[ai][bj][m][n], 0, 0, 0); __builtin_amdgcn_s_setprio(0); } while (0)
; #define PG8_WAIT_V(n) asm volatile("s_waitcnt vmcnt(" #n ")" ::: "memory")
; #define PG8_WAIT_L(n) asm volatile("s_waitcnt lgkmcnt(" #n ")" ::: "memory")
; #define PG8_BAR __builtin_amdgcn_s_barrier()
; #define PG8_SCHED __builtin_amdgcn_sched_barrier(0)
; template <class Epi, class Sched>
; __device__ __forceinline__ void gemm_phase(PG8_LAS unsigned char* lds, const Gemm g, const Sched& S, const Epi& E) {
;     ...
;             PG8_BAR; PG8_WAIT_L(0); PG8_MMA(0, 1, At, B1); PG8_BAR;
;             PG8_LDA(At, 0, 1); PG8_STAGE(PG8_SA(0, 0), a2, voffA);
;             PG8_BAR; PG8_WAIT_L(0); PG8_MMA(1, 0, At, B0); PG8_BAR; PG8_SCHED;
;             PG8_STAGE(PG8_SB(0, 1), b2 + hstep, voffB);
;             PG8_WAIT_V(6); PG8_BAR; PG8_MMA(1, 1, At, B1); PG8_BAR;
;             PG8_LDB(B0, 1, 0); PG8_SCHED; PG8_LDA(At, 1, 0); PG8_STAGE(PG8_SA(0, 1), a2 + hstep, voffA);
;             PG8_WAIT_L(8); PG8_BAR; PG8_WAIT_L(0); PG8_MMA(0, 0, At, B0); PG8_BAR; PG8_SCHED;
	s_waitcnt lgkmcnt(3)
	v_mfma_f32_16x16x32_bf16 v[108:111], v[194:197], v[158:161], v[108:111]
	s_waitcnt lgkmcnt(1)
	v_mfma_f32_16x16x32_bf16 v[104:107], v[202:205], v[158:161], v[104:107]
	v_mfma_f32_16x16x32_bf16 v[92:95], v[194:197], v[166:169], v[92:95]
	v_mfma_f32_16x16x32_bf16 v[88:91], v[202:205], v[166:169], v[88:91]
	v_mfma_f32_16x16x32_bf16 v[76:79], v[194:197], v[178:181], v[76:79]
	v_mfma_f32_16x16x32_bf16 v[72:75], v[202:205], v[178:181], v[72:75]
	v_mfma_f32_16x16x32_bf16 v[68:71], v[194:197], v[186:189], v[68:71]
	v_mfma_f32_16x16x32_bf16 v[64:67], v[202:205], v[186:189], v[64:67]
	v_mfma_f32_16x16x32_bf16 v[108:111], v[198:201], v[162:165], v[108:111]
	s_waitcnt lgkmcnt(0)
	v_mfma_f32_16x16x32_bf16 v[104:107], v[206:209], v[162:165], v[104:107]
	v_mfma_f32_16x16x32_bf16 v[92:95], v[198:201], v[170:173], v[92:95]
	v_mfma_f32_16x16x32_bf16 v[88:91], v[206:209], v[170:173], v[88:91]
	v_mfma_f32_16x16x32_bf16 v[76:79], v[198:201], v[182:185], v[76:79]
	v_mfma_f32_16x16x32_bf16 v[72:75], v[206:209], v[182:185], v[72:75]
	v_mfma_f32_16x16x32_bf16 v[68:71], v[198:201], v[190:193], v[68:71]
	v_mfma_f32_16x16x32_bf16 v[64:67], v[206:209], v[190:193], v[64:67]
	s_mov_b32 m0, s20
	s_add_u32 s100, s14, 0x80
	s_addc_u32 s101, s15, 0
	s_barrier
	ds_read_b128 v[158:161], v141 offset:16384
	ds_read_b128 v[162:165], v141 offset:17408
	ds_read_b128 v[166:169], v141 offset:18432
	ds_read_b128 v[170:173], v141 offset:19456
	ds_read_b128 v[178:181], v141 offset:20480
	ds_read_b128 v[182:185], v141 offset:21504
	ds_read_b128 v[186:189], v141 offset:22528
	global_load_lds_dwordx4 v132, s[14:15]
	s_mov_b32 m0, s21
	ds_read_b128 v[190:193], v141 offset:23552
	global_load_lds_dwordx4 v130, s[14:15]
	s_barrier
	s_waitcnt lgkmcnt(7)
	v_mfma_f32_16x16x32_bf16 v[60:63], v[142:145], v[158:161], v[60:63]
	v_mfma_f32_16x16x32_bf16 v[56:59], v[150:153], v[158:161], v[56:59]
	s_waitcnt lgkmcnt(5)
	v_mfma_f32_16x16x32_bf16 v[52:55], v[142:145], v[166:169], v[52:55]
	v_mfma_f32_16x16x32_bf16 v[48:51], v[150:153], v[166:169], v[48:51]
	s_waitcnt lgkmcnt(3)
	v_mfma_f32_16x16x32_bf16 v[36:39], v[142:145], v[178:181], v[36:39]
	v_mfma_f32_16x16x32_bf16 v[32:35], v[150:153], v[178:181], v[32:35]
	s_waitcnt lgkmcnt(1)
	v_mfma_f32_16x16x32_bf16 v[20:23], v[142:145], v[186:189], v[20:23]
	v_mfma_f32_16x16x32_bf16 v[16:19], v[150:153], v[186:189], v[16:19]
	v_mfma_f32_16x16x32_bf16 v[60:63], v[146:149], v[162:165], v[60:63]
	v_mfma_f32_16x16x32_bf16 v[56:59], v[154:157], v[162:165], v[56:59]
	v_mfma_f32_16x16x32_bf16 v[52:55], v[146:149], v[170:173], v[52:55]
	v_mfma_f32_16x16x32_bf16 v[48:51], v[154:157], v[170:173], v[48:51]
	v_mfma_f32_16x16x32_bf16 v[36:39], v[146:149], v[182:185], v[36:39]
	v_mfma_f32_16x16x32_bf16 v[32:35], v[154:157], v[182:185], v[32:35]
	s_waitcnt lgkmcnt(0)
	v_mfma_f32_16x16x32_bf16 v[20:23], v[146:149], v[190:193], v[20:23]
	v_mfma_f32_16x16x32_bf16 v[16:19], v[154:157], v[190:193], v[16:19]
	s_barrier
	s_add_u32 s8, s12, 0xb0000
	s_addc_u32 s9, s13, 0
	s_add_i32 m0, s18, 0x14000
	s_nop 0
	global_load_lds_dwordx4 v176, s[8:9]
	s_add_i32 m0, s18, 0x16000
	s_nop 0
	global_load_lds_dwordx4 v128, s[8:9]
	s_waitcnt vmcnt(6)
	s_barrier
	v_mfma_f32_16x16x32_bf16 v[44:47], v[194:197], v[158:161], v[44:47]
	v_mfma_f32_16x16x32_bf16 v[40:43], v[202:205], v[158:161], v[40:43]
	v_mfma_f32_16x16x32_bf16 v[28:31], v[194:197], v[166:169], v[28:31]
	v_mfma_f32_16x16x32_bf16 v[24:27], v[202:205], v[166:169], v[24:27]
	v_mfma_f32_16x16x32_bf16 v[12:15], v[194:197], v[178:181], v[12:15]
	v_mfma_f32_16x16x32_bf16 v[8:11], v[202:205], v[178:181], v[8:11]
	v_mfma_f32_16x16x32_bf16 v[4:7], v[194:197], v[186:189], v[4:7]
	v_mfma_f32_16x16x32_bf16 v[0:3], v[202:205], v[186:189], v[0:3]
	v_mfma_f32_16x16x32_bf16 v[44:47], v[198:201], v[162:165], v[44:47]
	v_mfma_f32_16x16x32_bf16 v[40:43], v[206:209], v[162:165], v[40:43]
	v_mfma_f32_16x16x32_bf16 v[28:31], v[198:201], v[170:173], v[28:31]
	v_mfma_f32_16x16x32_bf16 v[24:27], v[206:209], v[170:173], v[24:27]
	v_mfma_f32_16x16x32_bf16 v[12:15], v[198:201], v[182:185], v[12:15]
	v_mfma_f32_16x16x32_bf16 v[8:11], v[206:209], v[182:185], v[8:11]
	v_mfma_f32_16x16x32_bf16 v[4:7], v[198:201], v[190:193], v[4:7]
	v_mfma_f32_16x16x32_bf16 v[0:3], v[206:209], v[190:193], v[0:3]
	s_add_i32 s46, 0, 0x18000
	v_add_u32_e32 v154, 0x18000, v139
	s_barrier
	ds_read_b128 v[142:145], v154
	ds_read_b128 v[146:149], v154 offset:1024
	ds_read_b128 v[150:153], v154 offset:2048
	ds_read_b128 v[154:157], v154 offset:3072
	s_add_u32 s8, s14, 0xb0000
	s_addc_u32 s9, s15, 0
	s_mov_b32 m0, s22
	ds_read_b128 v[158:161], v141 offset:32768
	ds_read_b128 v[162:165], v141 offset:33792
	ds_read_b128 v[166:169], v141 offset:34816
	ds_read_b128 v[170:173], v141 offset:35840
	ds_read_b128 v[178:181], v141 offset:36864
	ds_read_b128 v[182:185], v141 offset:37888
	ds_read_b128 v[186:189], v141 offset:38912
	global_load_lds_dwordx4 v132, s[8:9]
	s_mov_b32 m0, s23
	ds_read_b128 v[190:193], v141 offset:39936
	global_load_lds_dwordx4 v130, s[8:9]
	s_waitcnt lgkmcnt(8)
	s_barrier
; #define PG8_STAGE(bufoff, gbase, voff) do { _Pragma("unroll") for (int _i = 0; _i < 2; ++_i) \
;         __builtin_amdgcn_global_load_lds((const unsigned*)((const char*)(gbase) + (voff)[_i]), (PG8_LAS unsigned*)(lds + (bufoff) + ldsw + _i * 8192), 16, 0, 0); } while (0)
; #define PG8_LDA(dst, b, h) do { _Pragma("unroll") for (int m = 0; m < 4; ++m) _Pragma("unroll") for (int k = 0; k < 2; ++k) dst[m][k] = *(const PG8_LAS bf16x8*)(lds + PG8_SA(b, h) + aoff + m * 2048 + k * 1024); } while (0)
; #define PG8_LDB(dst, b, h) do { _Pragma("unroll") for (int n = 0; n < 2; ++n) _Pragma("unroll") for (int k = 0; k < 2; ++k) dst[n][k] = *(const PG8_LAS bf16x8*)(lds + PG8_SB(b, h) + boff + n * 2048 + k * 1024); } while (0)
; #define PG8_MMA(ai, bj, At, Bt) do { __builtin_amdgcn_s_setprio(1); _Pragma("unroll") for (int m = 0; m < 4; ++m) _Pragma("unroll") for (int n = 0; n < 2; ++n) _Pragma("unroll") for (int k = 0; k < 2; ++k) \
;         acc[ai][bj][m][n] = __builtin_amdgcn_mfma_f32_16x16x32_bf16(Bt[n][k], At[m][k], acc[ai][bj][m][n], 0, 0, 0); __builtin_amdgcn_s_setprio(0); } while (0)
; #define PG8_WAIT_V(n) asm volatile("s_waitcnt vmcnt(" #n ")" ::: "memory")
; #define PG8_WAIT_L(n) asm volatile("s_waitcnt lgkmcnt(" #n ")" ::: "memory")
; #define PG8_BAR __builtin_amdgcn_s_barrier()
; #define PG8_SCHED __builtin_amdgcn_sched_barrier(0)
; template <class Epi, class Sched>
; __device__ __forceinline__ void gemm_phase(PG8_LAS unsigned char* lds, const Gemm g, const Sched& S, const Epi& E) {
;     ...
;             PG8_WAIT_L(8); PG8_BAR; PG8_WAIT_L(0); PG8_MMA(0, 0, At, B0); PG8_BAR; PG8_SCHED;
;             PG8_LDB(B1, 1, 1); PG8_STAGE(PG8_SB(1, 0), b3, voffB);
;             PG8_BAR; PG8_WAIT_L(0); PG8_MMA(0, 1, At, B1); PG8_BAR;
;             PG8_LDA(At, 1, 1); PG8_STAGE(PG8_SA(1, 0), a3, voffA);
;             PG8_BAR; PG8_WAIT_L(0); PG8_MMA(1, 0, At, B0); PG8_BAR; PG8_SCHED;
;             PG8_STAGE(PG8_SB(1, 1), b3 + hstep, voffB);
;             PG8_WAIT_V(6); PG8_BAR; PG8_MMA(1, 1, At, B1); PG8_BAR;
;         }
	s_waitcnt lgkmcnt(7)
	v_mfma_f32_16x16x32_bf16 v[124:127], v[142:145], v[158:161], v[124:127]
	v_mfma_f32_16x16x32_bf16 v[120:123], v[150:153], v[158:161], v[120:123]
	s_waitcnt lgkmcnt(5)
	v_mfma_f32_16x16x32_bf16 v[116:119], v[142:145], v[166:169], v[116:119]
	v_mfma_f32_16x16x32_bf16 v[112:115], v[150:153], v[166:169], v[112:115]
	s_waitcnt lgkmcnt(3)
	v_mfma_f32_16x16x32_bf16 v[100:103], v[142:145], v[178:181], v[100:103]
	v_mfma_f32_16x16x32_bf16 v[96:99], v[150:153], v[178:181], v[96:99]
	s_waitcnt lgkmcnt(1)
	v_mfma_f32_16x16x32_bf16 v[84:87], v[142:145], v[186:189], v[84:87]
	v_mfma_f32_16x16x32_bf16 v[80:83], v[150:153], v[186:189], v[80:83]
	v_mfma_f32_16x16x32_bf16 v[124:127], v[146:149], v[162:165], v[124:127]
	v_mfma_f32_16x16x32_bf16 v[120:123], v[154:157], v[162:165], v[120:123]
	v_mfma_f32_16x16x32_bf16 v[116:119], v[146:149], v[170:173], v[116:119]
	v_mfma_f32_16x16x32_bf16 v[112:115], v[154:157], v[170:173], v[112:115]
	v_mfma_f32_16x16x32_bf16 v[100:103], v[146:149], v[182:185], v[100:103]
	v_mfma_f32_16x16x32_bf16 v[96:99], v[154:157], v[182:185], v[96:99]
	s_waitcnt lgkmcnt(0)
	v_mfma_f32_16x16x32_bf16 v[84:87], v[146:149], v[190:193], v[84:87]
	v_mfma_f32_16x16x32_bf16 v[80:83], v[154:157], v[190:193], v[80:83]
	v_add_u32_e32 v206, 0x1c000, v139
	s_barrier
	s_add_i32 m0, s18, 0x18000
	ds_read_b128 v[194:197], v206
	ds_read_b128 v[198:201], v206 offset:1024
	ds_read_b128 v[202:205], v206 offset:2048
	global_load_lds_dwordx4 v176, s[98:99]
	s_add_i32 m0, s18, 0x1a000
	ds_read_b128 v[206:209], v206 offset:3072
	global_load_lds_dwordx4 v128, s[98:99]
	s_barrier
	s_waitcnt lgkmcnt(3)
	v_mfma_f32_16x16x32_bf16 v[108:111], v[194:197], v[158:161], v[108:111]
	s_waitcnt lgkmcnt(1)
	v_mfma_f32_16x16x32_bf16 v[104:107], v[202:205], v[158:161], v[104:107]
	v_mfma_f32_16x16x32_bf16 v[92:95], v[194:197], v[166:169], v[92:95]
	v_mfma_f32_16x16x32_bf16 v[88:91], v[202:205], v[166:169], v[88:91]
	v_mfma_f32_16x16x32_bf16 v[76:79], v[194:197], v[178:181], v[76:79]
	v_mfma_f32_16x16x32_bf16 v[72:75], v[202:205], v[178:181], v[72:75]
	v_mfma_f32_16x16x32_bf16 v[68:71], v[194:197], v[186:189], v[68:71]
	v_mfma_f32_16x16x32_bf16 v[64:67], v[202:205], v[186:189], v[64:67]
	v_mfma_f32_16x16x32_bf16 v[108:111], v[198:201], v[162:165], v[108:111]
	s_waitcnt lgkmcnt(0)
	v_mfma_f32_16x16x32_bf16 v[104:107], v[206:209], v[162:165], v[104:107]
	v_mfma_f32_16x16x32_bf16 v[92:95], v[198:201], v[170:173], v[92:95]
	v_mfma_f32_16x16x32_bf16 v[88:91], v[206:209], v[170:173], v[88:91]
	v_mfma_f32_16x16x32_bf16 v[76:79], v[198:201], v[182:185], v[76:79]
	v_mfma_f32_16x16x32_bf16 v[72:75], v[206:209], v[182:185], v[72:75]
	v_mfma_f32_16x16x32_bf16 v[68:71], v[198:201], v[190:193], v[68:71]
	v_mfma_f32_16x16x32_bf16 v[64:67], v[206:209], v[190:193], v[64:67]
	s_mov_b32 m0, s27
	s_barrier
	ds_read_b128 v[158:161], v141 offset:49152
	ds_read_b128 v[162:165], v141 offset:50176
	ds_read_b128 v[166:169], v141 offset:51200
	ds_read_b128 v[170:173], v141 offset:52224
	ds_read_b128 v[178:181], v141 offset:53248
	ds_read_b128 v[182:185], v141 offset:54272
	ds_read_b128 v[186:189], v141 offset:55296
	global_load_lds_dwordx4 v132, s[100:101]
	s_mov_b32 m0, s28
	ds_read_b128 v[190:193], v141 offset:56320
	global_load_lds_dwordx4 v130, s[100:101]
	s_barrier
	s_waitcnt lgkmcnt(7)
	v_mfma_f32_16x16x32_bf16 v[60:63], v[142:145], v[158:161], v[60:63]
	v_mfma_f32_16x16x32_bf16 v[56:59], v[150:153], v[158:161], v[56:59]
	s_waitcnt lgkmcnt(5)
	v_mfma_f32_16x16x32_bf16 v[52:55], v[142:145], v[166:169], v[52:55]
	v_mfma_f32_16x16x32_bf16 v[48:51], v[150:153], v[166:169], v[48:51]
	s_waitcnt lgkmcnt(3)
	v_mfma_f32_16x16x32_bf16 v[36:39], v[142:145], v[178:181], v[36:39]
	v_mfma_f32_16x16x32_bf16 v[32:35], v[150:153], v[178:181], v[32:35]
	s_waitcnt lgkmcnt(1)
	v_mfma_f32_16x16x32_bf16 v[20:23], v[142:145], v[186:189], v[20:23]
	v_mfma_f32_16x16x32_bf16 v[16:19], v[150:153], v[186:189], v[16:19]
	v_mfma_f32_16x16x32_bf16 v[60:63], v[146:149], v[162:165], v[60:63]
	v_mfma_f32_16x16x32_bf16 v[56:59], v[154:157], v[162:165], v[56:59]
	v_mfma_f32_16x16x32_bf16 v[52:55], v[146:149], v[170:173], v[52:55]
	v_mfma_f32_16x16x32_bf16 v[48:51], v[154:157], v[170:173], v[48:51]
	v_mfma_f32_16x16x32_bf16 v[36:39], v[146:149], v[182:185], v[36:39]
	v_mfma_f32_16x16x32_bf16 v[32:35], v[154:157], v[182:185], v[32:35]
	s_waitcnt lgkmcnt(0)
	v_mfma_f32_16x16x32_bf16 v[20:23], v[146:149], v[190:193], v[20:23]
	v_mfma_f32_16x16x32_bf16 v[16:19], v[154:157], v[190:193], v[16:19]
	s_barrier
	s_add_u32 s8, s12, 0xb0080
	s_addc_u32 s9, s13, 0
	s_add_i32 m0, s18, 0x1c000
	s_nop 0
	global_load_lds_dwordx4 v176, s[8:9]
	s_add_i32 m0, s18, 0x1e000
	s_nop 0
	global_load_lds_dwordx4 v128, s[8:9]
	s_waitcnt vmcnt(6)
	s_barrier
	v_mfma_f32_16x16x32_bf16 v[44:47], v[194:197], v[158:161], v[44:47]
	v_mfma_f32_16x16x32_bf16 v[40:43], v[202:205], v[158:161], v[40:43]
	v_mfma_f32_16x16x32_bf16 v[28:31], v[194:197], v[166:169], v[28:31]
	v_mfma_f32_16x16x32_bf16 v[24:27], v[202:205], v[166:169], v[24:27]
	v_mfma_f32_16x16x32_bf16 v[12:15], v[194:197], v[178:181], v[12:15]
	v_mfma_f32_16x16x32_bf16 v[8:11], v[202:205], v[178:181], v[8:11]
	v_mfma_f32_16x16x32_bf16 v[4:7], v[194:197], v[186:189], v[4:7]
	v_mfma_f32_16x16x32_bf16 v[0:3], v[202:205], v[186:189], v[0:3]
	v_mfma_f32_16x16x32_bf16 v[44:47], v[198:201], v[162:165], v[44:47]
	v_mfma_f32_16x16x32_bf16 v[40:43], v[206:209], v[162:165], v[40:43]
	v_mfma_f32_16x16x32_bf16 v[28:31], v[198:201], v[170:173], v[28:31]
	v_mfma_f32_16x16x32_bf16 v[24:27], v[206:209], v[170:173], v[24:27]
	v_mfma_f32_16x16x32_bf16 v[12:15], v[198:201], v[182:185], v[12:15]
	v_mfma_f32_16x16x32_bf16 v[8:11], v[206:209], v[182:185], v[8:11]
	v_mfma_f32_16x16x32_bf16 v[4:7], v[198:201], v[190:193], v[4:7]
	v_mfma_f32_16x16x32_bf16 v[0:3], v[206:209], v[190:193], v[0:3]
	s_add_i32 s45, s45, 2
	s_add_u32 s43, s43, 0x100
	s_addc_u32 s44, s44, 0
	s_cmp_gt_u32 s45, 41
	s_mov_b64 s[8:9], s[10:11]
	v_add_u32_e32 v154, 0x10000, v139
	s_barrier
; __device__ __forceinline__ unsigned cvtpk(float lo, float hi) { const f32x2 v = (f32x2){lo, hi}; const bf16v2 b = __builtin_convertvector(v, bf16v2); return __builtin_bit_cast(unsigned, b); }
; template <class Epi, class Sched>
; __device__ __forceinline__ void gemm_phase(PG8_LAS unsigned char* lds, const Gemm g, const Sched& S, const Epi& E) {
;     ...
;         if constexpr (!Epi::AFTER_DRAIN) { E(acc, cur, wr, wc, fr, fq); S.done(cur); }
;         if (!has_next) break;
; #pragma unroll
;         for (int a = 0; a < 2; ++a)
; #pragma unroll
;             for (int b = 0; b < 2; ++b)
; #pragma unroll
;                 for (int m = 0; m < 4; ++m)
; #pragma unroll
;                     for (int n = 0; n < 2; ++n) acc[a][b][m][n] = (f32x4){0.f, 0.f, 0.f, 0.f};
;         cur = nxt; cA = nA; cB = nB; ++ui;
;     __device__ __forceinline__ void operator()(const f32x4 (&acc)[2][2][4][2], const pg8::Unit& u, int wr, int wc, int fr, int fq) const {
;         const int row0 = u.pm * 256 + wr * 64 + fr, col0 = u.pn * 256 + wc * 32 + 8 * fq;
; #pragma unroll
;         for (int ai = 0; ai < 2; ++ai)
; #pragma unroll
;             for (int m = 0; m < 4; ++m) { bf16_t* rowp = O + (size_t)(row0 + ai * 128 + m * 16) * ldc + col0;
; #pragma unroll
;                 for (int bj = 0; bj < 2; ++bj) { const f32x4 v0 = acc[ai][bj][m][0], v1 = acc[ai][bj][m][1];
;                     u32x4 w; w.x = cvtpk(v0[0], v0[1]); w.y = cvtpk(v0[2], v0[3]); w.z = cvtpk(v1[0], v1[1]); w.w = cvtpk(v1[2], v1[3]);
;                     *(u32x4*)(rowp + bj * 128) = w; } }
;     }
	s_cbranch_scc0 .LBB0_96
	v_lshl_add_u32 v142, s29, 8, v138
	v_lshl_or_b32 v144, s34, 8, v140
	v_ashrrev_i32_e32 v143, 31, v142
	v_readlane_b32 s8, v253, 18
	v_cvt_pk_bf16_f32 v108, v108, v109
	v_cvt_pk_bf16_f32 v109, v110, v111
	v_cvt_pk_bf16_f32 v110, v104, v105
	v_or_b32_e32 v104, 16, v142
	v_cvt_pk_bf16_f32 v92, v92, v93
	v_cvt_pk_bf16_f32 v93, v94, v95
	v_cvt_pk_bf16_f32 v94, v88, v89
	v_or_b32_e32 v88, 32, v142
	v_cvt_pk_bf16_f32 v76, v76, v77
	v_cvt_pk_bf16_f32 v77, v78, v79
	v_cvt_pk_bf16_f32 v78, v72, v73
	v_or_b32_e32 v72, 48, v142
	v_ashrrev_i32_e32 v145, 31, v144
	v_lshlrev_b64 v[146:147], 11, v[142:143]
	v_readlane_b32 s9, v253, 19
	v_ashrrev_i32_e32 v105, 31, v104
	v_ashrrev_i32_e32 v89, 31, v88
	v_ashrrev_i32_e32 v73, 31, v72
	v_lshl_add_u64 v[146:147], s[8:9], 0, v[146:147]
	v_lshlrev_b64 v[144:145], 1, v[144:145]
	v_lshlrev_b64 v[104:105], 11, v[104:105]
	v_lshlrev_b64 v[88:89], 11, v[88:89]
	v_lshlrev_b64 v[72:73], 11, v[72:73]
	v_lshl_add_u64 v[146:147], v[146:147], 0, v[144:145]
	v_lshl_add_u64 v[104:105], s[8:9], 0, v[104:105]
	v_lshl_add_u64 v[88:89], s[8:9], 0, v[88:89]
	v_lshl_add_u64 v[72:73], s[8:9], 0, v[72:73]
	s_mov_b64 s[8:9], 0x40000
	v_cvt_pk_bf16_f32 v68, v68, v69
	v_cvt_pk_bf16_f32 v69, v70, v71
	v_cvt_pk_bf16_f32 v70, v64, v65
	v_lshl_add_u64 v[64:65], v[146:147], 0, s[8:9]
	v_cvt_pk_bf16_f32 v60, v60, v61
	v_cvt_pk_bf16_f32 v61, v62, v63
	v_cvt_pk_bf16_f32 v62, v56, v57
	v_add_co_u32_e32 v56, vcc, s2, v146
	v_cvt_pk_bf16_f32 v44, v44, v45
	v_cvt_pk_bf16_f32 v45, v46, v47
	v_cvt_pk_bf16_f32 v46, v40, v41
	v_cvt_pk_bf16_f32 v47, v42, v43
	s_mov_b64 s[8:9], 0x48000
	v_addc_co_u32_e32 v57, vcc, 0, v147, vcc
	global_store_dwordx4 v[64:65], v[44:47], off offset:256
	v_cvt_pk_bf16_f32 v28, v28, v29
	v_cvt_pk_bf16_f32 v29, v30, v31
	v_lshl_add_u64 v[44:45], v[146:147], 0, s[8:9]
	s_mov_b32 s8, 0x48000
	v_add_co_u32_e32 v46, vcc, s8, v146
	v_cvt_pk_bf16_f32 v30, v24, v25
	v_cvt_pk_bf16_f32 v31, v26, v27
	s_mov_b64 s[8:9], 0x50000
	v_addc_co_u32_e32 v47, vcc, 0, v147, vcc
	global_store_dwordx4 v[44:45], v[28:31], off offset:256
	v_cvt_pk_bf16_f32 v12, v12, v13
	v_cvt_pk_bf16_f32 v13, v14, v15
	v_lshl_add_u64 v[28:29], v[146:147], 0, s[8:9]
	s_mov_b32 s8, 0x50000
	v_add_co_u32_e32 v30, vcc, s8, v146
	v_cvt_pk_bf16_f32 v14, v8, v9
	v_cvt_pk_bf16_f32 v15, v10, v11
	s_mov_b64 s[8:9], 0x58000
	v_cvt_pk_bf16_f32 v111, v106, v107
	v_addc_co_u32_e32 v31, vcc, 0, v147, vcc
	global_store_dwordx4 v[28:29], v[12:15], off offset:256
	global_store_dwordx4 v[146:147], v[108:111], off offset:256
	v_cvt_pk_bf16_f32 v95, v90, v91
	v_lshl_add_u64 v[12:13], v[146:147], 0, s[8:9]
	s_mov_b32 s8, 0x58000
	v_lshl_add_u64 v[108:109], v[104:105], 0, v[144:145]
	v_add_co_u32_e32 v14, vcc, s8, v146
	global_store_dwordx4 v[108:109], v[92:95], off offset:256
	v_cvt_pk_bf16_f32 v79, v74, v75
	v_addc_co_u32_e32 v15, vcc, 0, v147, vcc
	v_lshl_add_u64 v[92:93], v[88:89], 0, v[144:145]
	v_cvt_pk_bf16_f32 v124, v124, v125
	v_cvt_pk_bf16_f32 v125, v126, v127
	v_cvt_pk_bf16_f32 v126, v120, v121
	v_cvt_pk_bf16_f32 v127, v122, v123
	v_cvt_pk_bf16_f32 v104, v116, v117
	v_cvt_pk_bf16_f32 v105, v118, v119
	v_cvt_pk_bf16_f32 v106, v112, v113
	v_cvt_pk_bf16_f32 v107, v114, v115
	v_cvt_pk_bf16_f32 v88, v100, v101
	v_cvt_pk_bf16_f32 v89, v102, v103
	v_cvt_pk_bf16_f32 v90, v96, v97
	v_cvt_pk_bf16_f32 v91, v98, v99
	global_store_dwordx4 v[92:93], v[76:79], off offset:256
	v_cvt_pk_bf16_f32 v74, v80, v81
	v_cvt_pk_bf16_f32 v75, v82, v83
	v_lshl_add_u64 v[76:77], v[72:73], 0, v[144:145]
	v_cvt_pk_bf16_f32 v72, v84, v85
	v_cvt_pk_bf16_f32 v73, v86, v87
	v_cvt_pk_bf16_f32 v71, v66, v67
	v_cvt_pk_bf16_f32 v63, v58, v59
	v_cvt_pk_bf16_f32 v40, v52, v53
	v_cvt_pk_bf16_f32 v41, v54, v55
	v_cvt_pk_bf16_f32 v42, v48, v49
	v_cvt_pk_bf16_f32 v43, v50, v51
	v_cvt_pk_bf16_f32 v24, v36, v37
	v_cvt_pk_bf16_f32 v25, v38, v39
	v_cvt_pk_bf16_f32 v26, v32, v33
	v_cvt_pk_bf16_f32 v27, v34, v35
	v_cvt_pk_bf16_f32 v8, v20, v21
	v_cvt_pk_bf16_f32 v9, v22, v23
	v_cvt_pk_bf16_f32 v10, v16, v17
	v_cvt_pk_bf16_f32 v11, v18, v19
	v_cvt_pk_bf16_f32 v4, v4, v5
	v_cvt_pk_bf16_f32 v5, v6, v7
	v_cvt_pk_bf16_f32 v6, v0, v1
	v_cvt_pk_bf16_f32 v7, v2, v3
	s_and_b64 vcc, exec, s[38:39]
	s_mov_b32 s34, s40
	s_mov_b32 s29, s41
	s_mov_b64 s[10:11], s[4:5]
	s_mov_b64 s[8:9], s[0:1]
	global_store_dwordx4 v[146:147], v[124:127], off
	global_store_dwordx4 v[108:109], v[104:107], off
	global_store_dwordx4 v[92:93], v[88:91], off
	global_store_dwordx4 v[76:77], v[72:75], off
	global_store_dwordx4 v[76:77], v[68:71], off offset:256
	global_store_dwordx4 v[56:57], v[60:63], off
	global_store_dwordx4 v[46:47], v[40:43], off
	global_store_dwordx4 v[30:31], v[24:27], off
	global_store_dwordx4 v[14:15], v[8:11], off
	global_store_dwordx4 v[12:13], v[4:7], off offset:256
	s_cbranch_vccz .LBB0_89
	s_waitcnt vmcnt(0)
	s_cmpk_gt_u32 s17, 0xff
	v_readlane_b32 s2, v254, 59
	s_cbranch_scc1 .LBB0_100
	s_barrier

; #define PG8_STAGE(bufoff, gbase, voff) do { _Pragma("unroll") for (int _i = 0; _i < 2; ++_i) \
;         __builtin_amdgcn_global_load_lds((const unsigned*)((const char*)(gbase) + (voff)[_i]), (PG8_LAS unsigned*)(lds + (bufoff) + ldsw + _i * 8192), 16, 0, 0); } while (0)
; #define PG8_LDA(dst, b, h) do { _Pragma("unroll") for (int m = 0; m < 4; ++m) _Pragma("unroll") for (int k = 0; k < 2; ++k) dst[m][k] = *(const PG8_LAS bf16x8*)(lds + PG8_SA(b, h) + aoff + m * 2048 + k * 1024); } while (0)
; #define PG8_LDB(dst, b, h) do { _Pragma("unroll") for (int n = 0; n < 2; ++n) _Pragma("unroll") for (int k = 0; k < 2; ++k) dst[n][k] = *(const PG8_LAS bf16x8*)(lds + PG8_SB(b, h) + boff + n * 2048 + k * 1024); } while (0)
; #define PG8_WAIT_L(n) asm volatile("s_waitcnt lgkmcnt(" #n ")" ::: "memory")
; #define PG8_BAR __builtin_amdgcn_s_barrier()
; #define PG8_SCHED __builtin_amdgcn_sched_barrier(0)
; template <class Epi, class Sched>
; __device__ __forceinline__ void gemm_phase(PG8_LAS unsigned char* lds, const Gemm g, const Sched& S, const Epi& E) {
;     ...
;         const bool has_next = S.next(ui + 1, nxt);
;         const char* nA = has_next ? (const char*)g.A + (size_t)nxt.pm * tstep : cA; const char* nB = has_next ? (const char*)g.Bt + (size_t)nxt.pn * tstep : cB;
;         for (int t = 0; t < nt; t += 2) {
;             const bool last = (t == nt - 2);
;             const char* a1 = cA + (size_t)(t + 1) * kstep;
;             const char* a2 = last ? nA : cA + (size_t)(t + 2) * kstep; const char* b2 = last ? nB : cB + (size_t)(t + 2) * kstep;
;             const char* a3 = a2 + kstep; const char* b3 = b2 + kstep;
;             if (last && has_next) S.a_ready(nxt);
;             PG8_LDB(B0, 0, 0); PG8_SCHED; PG8_LDA(At, 0, 0); PG8_STAGE(PG8_SA(1, 1), a1 + hstep, voffA);
;             PG8_WAIT_L(8); PG8_BAR; PG8_WAIT_L(0); PG8_MMA(0, 0, At, B0); PG8_BAR; PG8_SCHED;
;     ...
; #pragma unroll
;         for (int a = 0; a < 2; ++a)
; #pragma unroll
;             for (int b = 0; b < 2; ++b)
; #pragma unroll
;                 for (int m = 0; m < 4; ++m)
; #pragma unroll
;                     for (int n = 0; n < 2; ++n) acc[a][b][m][n] = (f32x4){0.f, 0.f, 0.f, 0.f};
;         cur = nxt; cA = nA; cB = nB; ++ui;
.LBB0_113:
	v_mov_b64_e32 v[0:1], 0x580
	s_ashr_i32 s5, s4, 31
	v_cmp_lt_i64_e32 vcc, s[6:7], v[0:1]
	s_lshl_b64 s[6:7], s[4:5], 19
	s_add_u32 s6, s94, s6
	s_addc_u32 s7, s95, s7
	s_and_b64 s[8:9], vcc, exec
	s_cselect_b32 s5, s7, s13
	s_cselect_b32 s40, s6, s12
	s_ashr_i32 s1, s0, 31
	s_lshl_b64 s[8:9], s[0:1], 19
	v_readlane_b32 s16, v253, 12
	v_readlane_b32 s17, v253, 13
	s_add_u32 s8, s16, s8
	s_addc_u32 s9, s17, s9
	s_and_b64 s[16:17], vcc, exec
	s_cselect_b32 s1, s9, s15
	s_cselect_b32 s41, s8, s14
	s_add_u32 s12, s12, 0x40080
	s_addc_u32 s13, s13, 0
	s_add_u32 s43, s14, 0x100
	v_mov_b32_e32 v0, 0
	s_addc_u32 s44, s15, 0
	s_mov_b32 s45, -2
	v_mov_b32_e32 v1, v0
	v_mov_b32_e32 v2, v0
	v_mov_b32_e32 v3, v0
	v_mov_b32_e32 v8, v0
	v_mov_b32_e32 v9, v0
	v_mov_b32_e32 v10, v0
	v_mov_b32_e32 v11, v0
	v_mov_b32_e32 v16, v0
	v_mov_b32_e32 v17, v0
	v_mov_b32_e32 v18, v0
	v_mov_b32_e32 v19, v0
	v_mov_b32_e32 v24, v0
	v_mov_b32_e32 v25, v0
	v_mov_b32_e32 v26, v0
	v_mov_b32_e32 v27, v0
	v_mov_b32_e32 v32, v0
	v_mov_b32_e32 v33, v0
	v_mov_b32_e32 v34, v0
	v_mov_b32_e32 v35, v0
	v_mov_b32_e32 v40, v0
	v_mov_b32_e32 v41, v0
	v_mov_b32_e32 v42, v0
	v_mov_b32_e32 v43, v0
	v_mov_b32_e32 v48, v0
	v_mov_b32_e32 v49, v0
	v_mov_b32_e32 v50, v0
	v_mov_b32_e32 v51, v0
	v_mov_b32_e32 v56, v0
	v_mov_b32_e32 v57, v0
	v_mov_b32_e32 v58, v0
	v_mov_b32_e32 v59, v0
	v_mov_b32_e32 v4, v0
	v_mov_b32_e32 v5, v0
	v_mov_b32_e32 v6, v0
	v_mov_b32_e32 v7, v0
	v_mov_b32_e32 v12, v0
	v_mov_b32_e32 v13, v0
	v_mov_b32_e32 v14, v0
	v_mov_b32_e32 v15, v0
	v_mov_b32_e32 v20, v0
	v_mov_b32_e32 v21, v0
	v_mov_b32_e32 v22, v0
	v_mov_b32_e32 v23, v0
	v_mov_b32_e32 v28, v0
	v_mov_b32_e32 v29, v0
	v_mov_b32_e32 v30, v0
	v_mov_b32_e32 v31, v0
	v_mov_b32_e32 v36, v0
	v_mov_b32_e32 v37, v0
	v_mov_b32_e32 v38, v0
	v_mov_b32_e32 v39, v0
	v_mov_b32_e32 v44, v0
	v_mov_b32_e32 v45, v0
	v_mov_b32_e32 v46, v0
	v_mov_b32_e32 v47, v0
	v_mov_b32_e32 v52, v0
	v_mov_b32_e32 v53, v0
	v_mov_b32_e32 v54, v0
	v_mov_b32_e32 v55, v0
	v_mov_b32_e32 v60, v0
	v_mov_b32_e32 v61, v0
	v_mov_b32_e32 v62, v0
	v_mov_b32_e32 v63, v0
	v_mov_b32_e32 v64, v0
	v_mov_b32_e32 v65, v0
	v_mov_b32_e32 v66, v0
	v_mov_b32_e32 v67, v0
	v_mov_b32_e32 v72, v0
	v_mov_b32_e32 v73, v0
	v_mov_b32_e32 v74, v0
	v_mov_b32_e32 v75, v0
	v_mov_b32_e32 v80, v0
	v_mov_b32_e32 v81, v0
	v_mov_b32_e32 v82, v0
	v_mov_b32_e32 v83, v0
	v_mov_b32_e32 v88, v0
	v_mov_b32_e32 v89, v0
	v_mov_b32_e32 v90, v0
	v_mov_b32_e32 v91, v0
	v_mov_b32_e32 v96, v0
	v_mov_b32_e32 v97, v0
	v_mov_b32_e32 v98, v0
	v_mov_b32_e32 v99, v0
	v_mov_b32_e32 v104, v0
	v_mov_b32_e32 v105, v0
	v_mov_b32_e32 v106, v0
	v_mov_b32_e32 v107, v0
	v_mov_b32_e32 v112, v0
	v_mov_b32_e32 v113, v0
	v_mov_b32_e32 v114, v0
	v_mov_b32_e32 v115, v0
	v_mov_b32_e32 v120, v0
	v_mov_b32_e32 v121, v0
	v_mov_b32_e32 v122, v0
	v_mov_b32_e32 v123, v0
	v_mov_b32_e32 v68, v0
	v_mov_b32_e32 v69, v0
	v_mov_b32_e32 v70, v0
	v_mov_b32_e32 v71, v0
	v_mov_b32_e32 v76, v0
	v_mov_b32_e32 v77, v0
	v_mov_b32_e32 v78, v0
	v_mov_b32_e32 v79, v0
	v_mov_b32_e32 v84, v0
	v_mov_b32_e32 v85, v0
	v_mov_b32_e32 v86, v0
	v_mov_b32_e32 v87, v0
	v_mov_b32_e32 v92, v0
	v_mov_b32_e32 v93, v0
	v_mov_b32_e32 v94, v0
	v_mov_b32_e32 v95, v0
	v_mov_b32_e32 v100, v0
	v_mov_b32_e32 v101, v0
	v_mov_b32_e32 v102, v0
	v_mov_b32_e32 v103, v0
	v_mov_b32_e32 v108, v0
	v_mov_b32_e32 v109, v0
	v_mov_b32_e32 v110, v0
	v_mov_b32_e32 v111, v0
	v_mov_b32_e32 v116, v0
	v_mov_b32_e32 v117, v0
	v_mov_b32_e32 v118, v0
	v_mov_b32_e32 v119, v0
	v_mov_b32_e32 v124, v0
	v_mov_b32_e32 v125, v0
	v_mov_b32_e32 v126, v0
	v_mov_b32_e32 v127, v0
	v_add_u32_e32 v154, 0x10000, v143
	v_add_u32_e32 v174, 0x14000, v143
.LBB0_114:
	ds_read_b128 v[138:141], v154
	ds_read_b128 v[146:149], v154 offset:1024
	ds_read_b128 v[150:153], v154 offset:2048
	ds_read_b128 v[154:157], v154 offset:3072
	s_add_u32 s14, s12, 0xfffc0080
	s_addc_u32 s15, s13, -1
	s_cmp_eq_u32 s45, 12
	s_cselect_b32 s17, s5, s15
	s_cselect_b32 s16, s40, s14
	s_cselect_b32 s15, s1, s44
	s_cselect_b32 s14, s41, s43
	s_add_i32 m0, s11, 0xc000
	ds_read_b128 v[158:161], v145
	ds_read_b128 v[162:165], v145 offset:1024
	ds_read_b128 v[166:169], v145 offset:2048
	ds_read_b128 v[170:173], v145 offset:3072
	ds_read_b128 v[178:181], v145 offset:4096
	ds_read_b128 v[182:185], v145 offset:5120
	ds_read_b128 v[186:189], v145 offset:6144
	global_load_lds_dwordx4 v134, s[12:13]
	s_add_i32 m0, s11, 0xe000
	ds_read_b128 v[190:193], v145 offset:7168
	global_load_lds_dwordx4 v136, s[12:13]
	s_waitcnt lgkmcnt(8)
	s_barrier
	s_waitcnt lgkmcnt(7)
	v_mfma_f32_16x16x32_bf16 v[124:127], v[138:141], v[158:161], v[124:127]
	v_mfma_f32_16x16x32_bf16 v[116:119], v[150:153], v[158:161], v[116:119]
	s_waitcnt lgkmcnt(5)
	v_mfma_f32_16x16x32_bf16 v[108:111], v[138:141], v[166:169], v[108:111]
	v_mfma_f32_16x16x32_bf16 v[100:103], v[150:153], v[166:169], v[100:103]
	s_waitcnt lgkmcnt(3)
	v_mfma_f32_16x16x32_bf16 v[92:95], v[138:141], v[178:181], v[92:95]
	v_mfma_f32_16x16x32_bf16 v[84:87], v[150:153], v[178:181], v[84:87]
	s_waitcnt lgkmcnt(1)
	v_mfma_f32_16x16x32_bf16 v[76:79], v[138:141], v[186:189], v[76:79]
	v_mfma_f32_16x16x32_bf16 v[68:71], v[150:153], v[186:189], v[68:71]
	v_mfma_f32_16x16x32_bf16 v[124:127], v[146:149], v[162:165], v[124:127]
	v_mfma_f32_16x16x32_bf16 v[116:119], v[154:157], v[162:165], v[116:119]
	v_mfma_f32_16x16x32_bf16 v[108:111], v[146:149], v[170:173], v[108:111]
	v_mfma_f32_16x16x32_bf16 v[100:103], v[154:157], v[170:173], v[100:103]
	v_mfma_f32_16x16x32_bf16 v[92:95], v[146:149], v[182:185], v[92:95]
	v_mfma_f32_16x16x32_bf16 v[84:87], v[154:157], v[182:185], v[84:87]
	s_waitcnt lgkmcnt(0)
	v_mfma_f32_16x16x32_bf16 v[76:79], v[146:149], v[190:193], v[76:79]
	v_mfma_f32_16x16x32_bf16 v[68:71], v[154:157], v[190:193], v[68:71]
	s_barrier
; #define PG8_STAGE(bufoff, gbase, voff) do { _Pragma("unroll") for (int _i = 0; _i < 2; ++_i) \
;         __builtin_amdgcn_global_load_lds((const unsigned*)((const char*)(gbase) + (voff)[_i]), (PG8_LAS unsigned*)(lds + (bufoff) + ldsw + _i * 8192), 16, 0, 0); } while (0)
; #define PG8_LDA(dst, b, h) do { _Pragma("unroll") for (int m = 0; m < 4; ++m) _Pragma("unroll") for (int k = 0; k < 2; ++k) dst[m][k] = *(const PG8_LAS bf16x8*)(lds + PG8_SA(b, h) + aoff + m * 2048 + k * 1024); } while (0)
; #define PG8_LDB(dst, b, h) do { _Pragma("unroll") for (int n = 0; n < 2; ++n) _Pragma("unroll") for (int k = 0; k < 2; ++k) dst[n][k] = *(const PG8_LAS bf16x8*)(lds + PG8_SB(b, h) + boff + n * 2048 + k * 1024); } while (0)
; #define PG8_MMA(ai, bj, At, Bt) do { __builtin_amdgcn_s_setprio(1); _Pragma("unroll") for (int m = 0; m < 4; ++m) _Pragma("unroll") for (int n = 0; n < 2; ++n) _Pragma("unroll") for (int k = 0; k < 2; ++k) \
;         acc[ai][bj][m][n] = __builtin_amdgcn_mfma_f32_16x16x32_bf16(Bt[n][k], At[m][k], acc[ai][bj][m][n], 0, 0, 0); __builtin_amdgcn_s_setprio(0); } while (0)
; #define PG8_WAIT_V(n) asm volatile("s_waitcnt vmcnt(" #n ")" ::: "memory")
; #define PG8_WAIT_L(n) asm volatile("s_waitcnt lgkmcnt(" #n ")" ::: "memory")
; #define PG8_BAR __builtin_amdgcn_s_barrier()
; #define PG8_SCHED __builtin_amdgcn_sched_barrier(0)
; template <class Epi, class Sched>
; __device__ __forceinline__ void gemm_phase(PG8_LAS unsigned char* lds, const Gemm g, const Sched& S, const Epi& E) {
;     ...
;             PG8_LDB(B1, 0, 1); PG8_STAGE(PG8_SB(0, 0), b2, voffB);
;             PG8_BAR; PG8_WAIT_L(0); PG8_MMA(0, 1, At, B1); PG8_BAR;
;             PG8_LDA(At, 0, 1); PG8_STAGE(PG8_SA(0, 0), a2, voffA);
;             PG8_BAR; PG8_WAIT_L(0); PG8_MMA(1, 0, At, B0); PG8_BAR; PG8_SCHED;
;             PG8_STAGE(PG8_SB(0, 1), b2 + hstep, voffB);
;             PG8_WAIT_V(6); PG8_BAR; PG8_MMA(1, 1, At, B1); PG8_BAR;
;             PG8_LDB(B0, 1, 0); PG8_SCHED; PG8_LDA(At, 1, 0); PG8_STAGE(PG8_SA(0, 1), a2 + hstep, voffA);
;             PG8_WAIT_L(8); PG8_BAR; PG8_WAIT_L(0); PG8_MMA(0, 0, At, B0); PG8_BAR; PG8_SCHED;
	s_add_i32 s48, 0, 0x14000
	ds_read_b128 v[194:197], v174
	ds_read_b128 v[198:201], v174 offset:1024
	s_add_u32 s98, s14, 0x80
	s_addc_u32 s99, s15, 0
	s_add_i32 m0, s20, 0x10000
	ds_read_b128 v[202:205], v174 offset:2048
	global_load_lds_dwordx4 v176, s[14:15]
	s_add_i32 m0, s20, 0x12000
	ds_read_b128 v[206:209], v174 offset:3072
	global_load_lds_dwordx4 v128, s[14:15]
	s_barrier
	s_waitcnt lgkmcnt(3)
	v_mfma_f32_16x16x32_bf16 v[120:123], v[194:197], v[158:161], v[120:123]
	s_waitcnt lgkmcnt(1)
	v_mfma_f32_16x16x32_bf16 v[112:115], v[202:205], v[158:161], v[112:115]
	v_mfma_f32_16x16x32_bf16 v[104:107], v[194:197], v[166:169], v[104:107]
	v_mfma_f32_16x16x32_bf16 v[96:99], v[202:205], v[166:169], v[96:99]
	v_mfma_f32_16x16x32_bf16 v[88:91], v[194:197], v[178:181], v[88:91]
	v_mfma_f32_16x16x32_bf16 v[80:83], v[202:205], v[178:181], v[80:83]
	v_mfma_f32_16x16x32_bf16 v[72:75], v[194:197], v[186:189], v[72:75]
	v_mfma_f32_16x16x32_bf16 v[64:67], v[202:205], v[186:189], v[64:67]
	v_mfma_f32_16x16x32_bf16 v[120:123], v[198:201], v[162:165], v[120:123]
	s_waitcnt lgkmcnt(0)
	v_mfma_f32_16x16x32_bf16 v[112:115], v[206:209], v[162:165], v[112:115]
	v_mfma_f32_16x16x32_bf16 v[104:107], v[198:201], v[170:173], v[104:107]
	v_mfma_f32_16x16x32_bf16 v[96:99], v[206:209], v[170:173], v[96:99]
	v_mfma_f32_16x16x32_bf16 v[88:91], v[198:201], v[182:185], v[88:91]
	v_mfma_f32_16x16x32_bf16 v[80:83], v[206:209], v[182:185], v[80:83]
	v_mfma_f32_16x16x32_bf16 v[72:75], v[198:201], v[190:193], v[72:75]
	v_mfma_f32_16x16x32_bf16 v[64:67], v[206:209], v[190:193], v[64:67]
	s_mov_b32 m0, s11
	s_add_u32 s100, s16, 0x80
	s_addc_u32 s101, s17, 0
	s_barrier
	ds_read_b128 v[158:161], v145 offset:16384
	ds_read_b128 v[162:165], v145 offset:17408
	ds_read_b128 v[166:169], v145 offset:18432
	ds_read_b128 v[170:173], v145 offset:19456
	ds_read_b128 v[178:181], v145 offset:20480
	ds_read_b128 v[182:185], v145 offset:21504
	ds_read_b128 v[186:189], v145 offset:22528
	global_load_lds_dwordx4 v132, s[16:17]
	s_mov_b32 m0, s22
	ds_read_b128 v[190:193], v145 offset:23552
	global_load_lds_dwordx4 v130, s[16:17]
	s_barrier
	s_waitcnt lgkmcnt(7)
	v_mfma_f32_16x16x32_bf16 v[60:63], v[138:141], v[158:161], v[60:63]
	v_mfma_f32_16x16x32_bf16 v[52:55], v[150:153], v[158:161], v[52:55]
	s_waitcnt lgkmcnt(5)
	v_mfma_f32_16x16x32_bf16 v[44:47], v[138:141], v[166:169], v[44:47]
	v_mfma_f32_16x16x32_bf16 v[36:39], v[150:153], v[166:169], v[36:39]
	s_waitcnt lgkmcnt(3)
	v_mfma_f32_16x16x32_bf16 v[28:31], v[138:141], v[178:181], v[28:31]
	v_mfma_f32_16x16x32_bf16 v[20:23], v[150:153], v[178:181], v[20:23]
	s_waitcnt lgkmcnt(1)
	v_mfma_f32_16x16x32_bf16 v[12:15], v[138:141], v[186:189], v[12:15]
	v_mfma_f32_16x16x32_bf16 v[4:7], v[150:153], v[186:189], v[4:7]
	v_mfma_f32_16x16x32_bf16 v[60:63], v[146:149], v[162:165], v[60:63]
	v_mfma_f32_16x16x32_bf16 v[52:55], v[154:157], v[162:165], v[52:55]
	v_mfma_f32_16x16x32_bf16 v[44:47], v[146:149], v[170:173], v[44:47]
	v_mfma_f32_16x16x32_bf16 v[36:39], v[154:157], v[170:173], v[36:39]
	v_mfma_f32_16x16x32_bf16 v[28:31], v[146:149], v[182:185], v[28:31]
	v_mfma_f32_16x16x32_bf16 v[20:23], v[154:157], v[182:185], v[20:23]
	s_waitcnt lgkmcnt(0)
	v_mfma_f32_16x16x32_bf16 v[12:15], v[146:149], v[190:193], v[12:15]
	v_mfma_f32_16x16x32_bf16 v[4:7], v[154:157], v[190:193], v[4:7]
	s_barrier
	s_add_u32 s46, s14, 0x40000
	s_addc_u32 s47, s15, 0
	s_add_i32 m0, s20, 0x14000
	s_nop 0
	global_load_lds_dwordx4 v176, s[46:47]
	s_add_i32 m0, s20, 0x16000
	s_nop 0
	global_load_lds_dwordx4 v128, s[46:47]
	s_waitcnt vmcnt(6)
	s_barrier
	v_mfma_f32_16x16x32_bf16 v[56:59], v[194:197], v[158:161], v[56:59]
	v_mfma_f32_16x16x32_bf16 v[48:51], v[202:205], v[158:161], v[48:51]
	v_mfma_f32_16x16x32_bf16 v[40:43], v[194:197], v[166:169], v[40:43]
	v_mfma_f32_16x16x32_bf16 v[32:35], v[202:205], v[166:169], v[32:35]
	v_mfma_f32_16x16x32_bf16 v[24:27], v[194:197], v[178:181], v[24:27]
	v_mfma_f32_16x16x32_bf16 v[16:19], v[202:205], v[178:181], v[16:19]
	v_mfma_f32_16x16x32_bf16 v[8:11], v[194:197], v[186:189], v[8:11]
	v_mfma_f32_16x16x32_bf16 v[0:3], v[202:205], v[186:189], v[0:3]
	v_mfma_f32_16x16x32_bf16 v[56:59], v[198:201], v[162:165], v[56:59]
	v_mfma_f32_16x16x32_bf16 v[48:51], v[206:209], v[162:165], v[48:51]
	v_mfma_f32_16x16x32_bf16 v[40:43], v[198:201], v[170:173], v[40:43]
	v_mfma_f32_16x16x32_bf16 v[32:35], v[206:209], v[170:173], v[32:35]
	v_mfma_f32_16x16x32_bf16 v[24:27], v[198:201], v[182:185], v[24:27]
	v_mfma_f32_16x16x32_bf16 v[16:19], v[206:209], v[182:185], v[16:19]
	v_mfma_f32_16x16x32_bf16 v[8:11], v[198:201], v[190:193], v[8:11]
	v_mfma_f32_16x16x32_bf16 v[0:3], v[206:209], v[190:193], v[0:3]
	v_add_u32_e32 v154, 0x18000, v143
	s_barrier
	ds_read_b128 v[138:141], v154
	ds_read_b128 v[146:149], v154 offset:1024
	ds_read_b128 v[150:153], v154 offset:2048
	ds_read_b128 v[154:157], v154 offset:3072
	s_add_u32 s16, s16, 0x40000
	s_addc_u32 s17, s17, 0
	s_mov_b32 m0, s23
	ds_read_b128 v[158:161], v145 offset:32768
	ds_read_b128 v[162:165], v145 offset:33792
	ds_read_b128 v[166:169], v145 offset:34816
	ds_read_b128 v[170:173], v145 offset:35840
	ds_read_b128 v[178:181], v145 offset:36864
	ds_read_b128 v[182:185], v145 offset:37888
	ds_read_b128 v[186:189], v145 offset:38912
	global_load_lds_dwordx4 v132, s[16:17]
	s_mov_b32 m0, s26
	ds_read_b128 v[190:193], v145 offset:39936
	global_load_lds_dwordx4 v130, s[16:17]
	s_waitcnt lgkmcnt(8)
	s_barrier
; #define PG8_STAGE(bufoff, gbase, voff) do { _Pragma("unroll") for (int _i = 0; _i < 2; ++_i) \
;         __builtin_amdgcn_global_load_lds((const unsigned*)((const char*)(gbase) + (voff)[_i]), (PG8_LAS unsigned*)(lds + (bufoff) + ldsw + _i * 8192), 16, 0, 0); } while (0)
; #define PG8_LDA(dst, b, h) do { _Pragma("unroll") for (int m = 0; m < 4; ++m) _Pragma("unroll") for (int k = 0; k < 2; ++k) dst[m][k] = *(const PG8_LAS bf16x8*)(lds + PG8_SA(b, h) + aoff + m * 2048 + k * 1024); } while (0)
; #define PG8_LDB(dst, b, h) do { _Pragma("unroll") for (int n = 0; n < 2; ++n) _Pragma("unroll") for (int k = 0; k < 2; ++k) dst[n][k] = *(const PG8_LAS bf16x8*)(lds + PG8_SB(b, h) + boff + n * 2048 + k * 1024); } while (0)
; #define PG8_MMA(ai, bj, At, Bt) do { __builtin_amdgcn_s_setprio(1); _Pragma("unroll") for (int m = 0; m < 4; ++m) _Pragma("unroll") for (int n = 0; n < 2; ++n) _Pragma("unroll") for (int k = 0; k < 2; ++k) \
;         acc[ai][bj][m][n] = __builtin_amdgcn_mfma_f32_16x16x32_bf16(Bt[n][k], At[m][k], acc[ai][bj][m][n], 0, 0, 0); __builtin_amdgcn_s_setprio(0); } while (0)
; #define PG8_WAIT_V(n) asm volatile("s_waitcnt vmcnt(" #n ")" ::: "memory")
; #define PG8_WAIT_L(n) asm volatile("s_waitcnt lgkmcnt(" #n ")" ::: "memory")
; #define PG8_BAR __builtin_amdgcn_s_barrier()
; #define PG8_SCHED __builtin_amdgcn_sched_barrier(0)
; template <class Epi, class Sched>
; __device__ __forceinline__ void gemm_phase(PG8_LAS unsigned char* lds, const Gemm g, const Sched& S, const Epi& E) {
;     ...
;             PG8_WAIT_L(8); PG8_BAR; PG8_WAIT_L(0); PG8_MMA(0, 0, At, B0); PG8_BAR; PG8_SCHED;
;             PG8_LDB(B1, 1, 1); PG8_STAGE(PG8_SB(1, 0), b3, voffB);
;             PG8_BAR; PG8_WAIT_L(0); PG8_MMA(0, 1, At, B1); PG8_BAR;
;             PG8_LDA(At, 1, 1); PG8_STAGE(PG8_SA(1, 0), a3, voffA);
;             PG8_BAR; PG8_WAIT_L(0); PG8_MMA(1, 0, At, B0); PG8_BAR; PG8_SCHED;
;             PG8_STAGE(PG8_SB(1, 1), b3 + hstep, voffB);
;             PG8_WAIT_V(6); PG8_BAR; PG8_MMA(1, 1, At, B1); PG8_BAR;
;         }
	s_waitcnt lgkmcnt(7)
	v_mfma_f32_16x16x32_bf16 v[124:127], v[138:141], v[158:161], v[124:127]
	v_mfma_f32_16x16x32_bf16 v[116:119], v[150:153], v[158:161], v[116:119]
	s_waitcnt lgkmcnt(5)
	v_mfma_f32_16x16x32_bf16 v[108:111], v[138:141], v[166:169], v[108:111]
	v_mfma_f32_16x16x32_bf16 v[100:103], v[150:153], v[166:169], v[100:103]
	s_waitcnt lgkmcnt(3)
	v_mfma_f32_16x16x32_bf16 v[92:95], v[138:141], v[178:181], v[92:95]
	v_mfma_f32_16x16x32_bf16 v[84:87], v[150:153], v[178:181], v[84:87]
	s_waitcnt lgkmcnt(1)
	v_mfma_f32_16x16x32_bf16 v[76:79], v[138:141], v[186:189], v[76:79]
	v_mfma_f32_16x16x32_bf16 v[68:71], v[150:153], v[186:189], v[68:71]
	v_mfma_f32_16x16x32_bf16 v[124:127], v[146:149], v[162:165], v[124:127]
	v_mfma_f32_16x16x32_bf16 v[116:119], v[154:157], v[162:165], v[116:119]
	v_mfma_f32_16x16x32_bf16 v[108:111], v[146:149], v[170:173], v[108:111]
	v_mfma_f32_16x16x32_bf16 v[100:103], v[154:157], v[170:173], v[100:103]
	v_mfma_f32_16x16x32_bf16 v[92:95], v[146:149], v[182:185], v[92:95]
	v_mfma_f32_16x16x32_bf16 v[84:87], v[154:157], v[182:185], v[84:87]
	s_waitcnt lgkmcnt(0)
	v_mfma_f32_16x16x32_bf16 v[76:79], v[146:149], v[190:193], v[76:79]
	v_mfma_f32_16x16x32_bf16 v[68:71], v[154:157], v[190:193], v[68:71]
	v_add_u32_e32 v206, 0x1c000, v143
	s_barrier
	s_add_i32 m0, s20, 0x18000
	ds_read_b128 v[194:197], v206
	ds_read_b128 v[198:201], v206 offset:1024
	ds_read_b128 v[202:205], v206 offset:2048
	global_load_lds_dwordx4 v176, s[98:99]
	s_add_i32 m0, s20, 0x1a000
	ds_read_b128 v[206:209], v206 offset:3072
	global_load_lds_dwordx4 v128, s[98:99]
	s_barrier
	s_waitcnt lgkmcnt(3)
	v_mfma_f32_16x16x32_bf16 v[120:123], v[194:197], v[158:161], v[120:123]
	s_waitcnt lgkmcnt(1)
	v_mfma_f32_16x16x32_bf16 v[112:115], v[202:205], v[158:161], v[112:115]
	v_mfma_f32_16x16x32_bf16 v[104:107], v[194:197], v[166:169], v[104:107]
	v_mfma_f32_16x16x32_bf16 v[96:99], v[202:205], v[166:169], v[96:99]
	v_mfma_f32_16x16x32_bf16 v[88:91], v[194:197], v[178:181], v[88:91]
	v_mfma_f32_16x16x32_bf16 v[80:83], v[202:205], v[178:181], v[80:83]
	v_mfma_f32_16x16x32_bf16 v[72:75], v[194:197], v[186:189], v[72:75]
	v_mfma_f32_16x16x32_bf16 v[64:67], v[202:205], v[186:189], v[64:67]
	v_mfma_f32_16x16x32_bf16 v[120:123], v[198:201], v[162:165], v[120:123]
	s_waitcnt lgkmcnt(0)
	v_mfma_f32_16x16x32_bf16 v[112:115], v[206:209], v[162:165], v[112:115]
	v_mfma_f32_16x16x32_bf16 v[104:107], v[198:201], v[170:173], v[104:107]
	v_mfma_f32_16x16x32_bf16 v[96:99], v[206:209], v[170:173], v[96:99]
	v_mfma_f32_16x16x32_bf16 v[88:91], v[198:201], v[182:185], v[88:91]
	v_mfma_f32_16x16x32_bf16 v[80:83], v[206:209], v[182:185], v[80:83]
	v_mfma_f32_16x16x32_bf16 v[72:75], v[198:201], v[190:193], v[72:75]
	v_mfma_f32_16x16x32_bf16 v[64:67], v[206:209], v[190:193], v[64:67]
	s_mov_b32 m0, s28
	s_barrier
	ds_read_b128 v[158:161], v145 offset:49152
	ds_read_b128 v[162:165], v145 offset:50176
	ds_read_b128 v[166:169], v145 offset:51200
	ds_read_b128 v[170:173], v145 offset:52224
	ds_read_b128 v[178:181], v145 offset:53248
	ds_read_b128 v[182:185], v145 offset:54272
	ds_read_b128 v[186:189], v145 offset:55296
	global_load_lds_dwordx4 v132, s[100:101]
	s_mov_b32 m0, s29
	ds_read_b128 v[190:193], v145 offset:56320
	global_load_lds_dwordx4 v130, s[100:101]
	s_barrier
	s_waitcnt lgkmcnt(7)
	v_mfma_f32_16x16x32_bf16 v[60:63], v[138:141], v[158:161], v[60:63]
	v_mfma_f32_16x16x32_bf16 v[52:55], v[150:153], v[158:161], v[52:55]
	s_waitcnt lgkmcnt(5)
	v_mfma_f32_16x16x32_bf16 v[44:47], v[138:141], v[166:169], v[44:47]
	v_mfma_f32_16x16x32_bf16 v[36:39], v[150:153], v[166:169], v[36:39]
	s_waitcnt lgkmcnt(3)
	v_mfma_f32_16x16x32_bf16 v[28:31], v[138:141], v[178:181], v[28:31]
	v_mfma_f32_16x16x32_bf16 v[20:23], v[150:153], v[178:181], v[20:23]
	s_waitcnt lgkmcnt(1)
	v_mfma_f32_16x16x32_bf16 v[12:15], v[138:141], v[186:189], v[12:15]
	v_mfma_f32_16x16x32_bf16 v[4:7], v[150:153], v[186:189], v[4:7]
	v_mfma_f32_16x16x32_bf16 v[60:63], v[146:149], v[162:165], v[60:63]
	v_mfma_f32_16x16x32_bf16 v[52:55], v[154:157], v[162:165], v[52:55]
	v_mfma_f32_16x16x32_bf16 v[44:47], v[146:149], v[170:173], v[44:47]
	v_mfma_f32_16x16x32_bf16 v[36:39], v[154:157], v[170:173], v[36:39]
	v_mfma_f32_16x16x32_bf16 v[28:31], v[146:149], v[182:185], v[28:31]
	v_mfma_f32_16x16x32_bf16 v[20:23], v[154:157], v[182:185], v[20:23]
	s_waitcnt lgkmcnt(0)
	v_mfma_f32_16x16x32_bf16 v[12:15], v[146:149], v[190:193], v[12:15]
	v_mfma_f32_16x16x32_bf16 v[4:7], v[154:157], v[190:193], v[4:7]
	s_barrier
	s_add_u32 s14, s14, 0x40080
	s_addc_u32 s15, s15, 0
	s_add_i32 m0, s20, 0x1c000
	s_nop 0
	global_load_lds_dwordx4 v176, s[14:15]
	s_add_i32 m0, s20, 0x1e000
	s_nop 0
	global_load_lds_dwordx4 v128, s[14:15]
	s_waitcnt vmcnt(6)
	s_barrier
	v_mfma_f32_16x16x32_bf16 v[56:59], v[194:197], v[158:161], v[56:59]
	v_mfma_f32_16x16x32_bf16 v[48:51], v[202:205], v[158:161], v[48:51]
	v_mfma_f32_16x16x32_bf16 v[40:43], v[194:197], v[166:169], v[40:43]
	v_mfma_f32_16x16x32_bf16 v[32:35], v[202:205], v[166:169], v[32:35]
	v_mfma_f32_16x16x32_bf16 v[24:27], v[194:197], v[178:181], v[24:27]
	v_mfma_f32_16x16x32_bf16 v[16:19], v[202:205], v[178:181], v[16:19]
	v_mfma_f32_16x16x32_bf16 v[8:11], v[194:197], v[186:189], v[8:11]
	v_mfma_f32_16x16x32_bf16 v[0:3], v[202:205], v[186:189], v[0:3]
	v_mfma_f32_16x16x32_bf16 v[56:59], v[198:201], v[162:165], v[56:59]
	v_mfma_f32_16x16x32_bf16 v[48:51], v[206:209], v[162:165], v[48:51]
	v_mfma_f32_16x16x32_bf16 v[40:43], v[198:201], v[170:173], v[40:43]
	v_mfma_f32_16x16x32_bf16 v[32:35], v[206:209], v[170:173], v[32:35]
	v_mfma_f32_16x16x32_bf16 v[24:27], v[198:201], v[182:185], v[24:27]
	v_mfma_f32_16x16x32_bf16 v[16:19], v[206:209], v[182:185], v[16:19]
	v_mfma_f32_16x16x32_bf16 v[8:11], v[198:201], v[190:193], v[8:11]
	v_mfma_f32_16x16x32_bf16 v[0:3], v[206:209], v[190:193], v[0:3]
	s_add_i32 s45, s45, 2
	s_add_u32 s12, s12, 0x100
	s_addc_u32 s13, s13, 0
	s_add_u32 s43, s43, 0x100
	s_addc_u32 s44, s44, 0
	s_cmp_gt_u32 s45, 13
	v_add_u32_e32 v154, 0x10000, v143
	s_barrier
; __device__ __forceinline__ unsigned cvtpk(float lo, float hi) { const f32x2 v = (f32x2){lo, hi}; const bf16v2 b = __builtin_convertvector(v, bf16v2); return __builtin_bit_cast(unsigned, b); }
; __device__ __forceinline__ float siluf_(float x) { return x * sigmoidf_(x); }
;     __device__ __forceinline__ void operator()(const f32x4 (&acc)[2][2][4][2], const pg8::Unit& u, int wr, int wc, int fr, int fq) const {
;         const int row0 = u.pm * 256 + wr * 64 + fr, col0 = u.pn * 128 + wc * 32 + 8 * fq;
; #pragma unroll
;         for (int ai = 0; ai < 2; ++ai)
; #pragma unroll
;             for (int m = 0; m < 4; ++m) { bf16_t* rowp = O + (size_t)(row0 + ai * 128 + m * 16) * ldc + col0;
;                 const f32x4 g0 = acc[ai][0][m][0], g1 = acc[ai][0][m][1], u0 = acc[ai][1][m][0], u1 = acc[ai][1][m][1];
;                 u32x4 w; w.x = cvtpk(siluf_(g0[0]) * u0[0], siluf_(g0[1]) * u0[1]); w.y = cvtpk(siluf_(g0[2]) * u0[2], siluf_(g0[3]) * u0[3]);
;                 w.z = cvtpk(siluf_(g1[0]) * u1[0], siluf_(g1[1]) * u1[1]); w.w = cvtpk(siluf_(g1[2]) * u1[2], siluf_(g1[3]) * u1[3]);
;                 *(u32x4*)rowp = w; }
	s_cbranch_scc0 .LBB0_114
	v_mul_f32_e32 v147, 0xbfb8aa3b, v124
	v_exp_f32_e32 v147, v147
	v_readlane_b32 s12, v253, 16
	v_lshl_add_u32 v146, s10, 8, v142
	v_lshl_or_b32 v140, s34, 7, v144
	v_add_f32_e32 v147, 1.0, v147
	v_rcp_f32_e32 v150, v147
	v_mul_f32_e32 v147, 0xbfb8aa3b, v125
	v_exp_f32_e32 v147, v147
	v_readlane_b32 s13, v253, 17
	v_ashrrev_i32_e32 v141, 31, v140
	v_lshlrev_b64 v[140:141], 1, v[140:141]
	v_add_f32_e32 v147, 1.0, v147
	v_rcp_f32_e32 v151, v147
	v_mov_b64_e32 v[138:139], s[12:13]
	v_mad_i64_i32 v[148:149], s[12:13], v146, s81, v[138:139]
	v_pk_mul_f32 v[124:125], v[124:125], v[150:151]
	v_lshl_add_u64 v[148:149], v[148:149], 0, v[140:141]
	v_pk_mul_f32 v[120:121], v[124:125], v[120:121]
	s_and_b64 vcc, exec, s[38:39]
	v_cvt_pk_bf16_f32 v120, v120, v121
	v_mul_f32_e32 v121, 0xbfb8aa3b, v126
	v_exp_f32_e32 v121, v121
	s_mov_b32 s34, s0
	s_mov_b32 s10, s4
	s_mov_b64 s[14:15], s[8:9]
	v_add_f32_e32 v121, 1.0, v121
	v_rcp_f32_e32 v124, v121
	v_mul_f32_e32 v121, 0xbfb8aa3b, v127
	v_exp_f32_e32 v121, v121
	s_nop 0
	v_add_f32_e32 v121, 1.0, v121
	v_rcp_f32_e32 v125, v121
	s_nop 0
	v_pk_mul_f32 v[124:125], v[126:127], v[124:125]
	s_nop 0
	v_pk_mul_f32 v[122:123], v[124:125], v[122:123]
	s_nop 0
	v_cvt_pk_bf16_f32 v121, v122, v123
	v_mul_f32_e32 v122, 0xbfb8aa3b, v116
	v_mul_f32_e32 v123, 0xbfb8aa3b, v117
	v_exp_f32_e32 v122, v122
	v_exp_f32_e32 v123, v123
	v_add_f32_e32 v122, 1.0, v122
	v_add_f32_e32 v123, 1.0, v123
	v_rcp_f32_e32 v122, v122
	v_rcp_f32_e32 v123, v123
	s_nop 0
	v_pk_mul_f32 v[116:117], v[116:117], v[122:123]
	s_nop 0
	v_pk_mul_f32 v[112:113], v[116:117], v[112:113]
	s_nop 0
	v_cvt_pk_bf16_f32 v122, v112, v113
	v_mul_f32_e32 v112, 0xbfb8aa3b, v118
	v_mul_f32_e32 v113, 0xbfb8aa3b, v119
	v_exp_f32_e32 v112, v112
	v_exp_f32_e32 v113, v113
	v_add_f32_e32 v112, 1.0, v112
	v_add_f32_e32 v113, 1.0, v113
	v_rcp_f32_e32 v112, v112
	v_rcp_f32_e32 v113, v113
	s_nop 0
	v_pk_mul_f32 v[112:113], v[118:119], v[112:113]
	s_nop 0
	v_pk_mul_f32 v[112:113], v[112:113], v[114:115]
	v_mul_f32_e32 v114, 0xbfb8aa3b, v108
	v_mul_f32_e32 v115, 0xbfb8aa3b, v109
	v_exp_f32_e32 v114, v114
	v_exp_f32_e32 v115, v115
	v_cvt_pk_bf16_f32 v123, v112, v113
	v_or_b32_e32 v112, 16, v146
	v_add_f32_e32 v114, 1.0, v114
	v_add_f32_e32 v115, 1.0, v115
	v_rcp_f32_e32 v114, v114
	v_rcp_f32_e32 v115, v115
	v_mad_i64_i32 v[112:113], s[12:13], v112, s81, v[138:139]
	v_lshl_add_u64 v[112:113], v[112:113], 0, v[140:141]
	v_pk_mul_f32 v[108:109], v[108:109], v[114:115]
	global_store_dwordx4 v[148:149], v[120:123], off
	v_pk_mul_f32 v[104:105], v[108:109], v[104:105]
	s_nop 0
	v_cvt_pk_bf16_f32 v104, v104, v105
	v_mul_f32_e32 v105, 0xbfb8aa3b, v110
	v_exp_f32_e32 v105, v105
	s_nop 0
	v_add_f32_e32 v105, 1.0, v105
	v_rcp_f32_e32 v108, v105
	v_mul_f32_e32 v105, 0xbfb8aa3b, v111
	v_exp_f32_e32 v105, v105
	s_nop 0
	v_add_f32_e32 v105, 1.0, v105
	v_rcp_f32_e32 v109, v105
	s_nop 0
	v_pk_mul_f32 v[108:109], v[110:111], v[108:109]
	s_nop 0
	v_pk_mul_f32 v[106:107], v[108:109], v[106:107]
	s_nop 0
	v_cvt_pk_bf16_f32 v105, v106, v107
	v_mul_f32_e32 v106, 0xbfb8aa3b, v100
	v_mul_f32_e32 v107, 0xbfb8aa3b, v101
	v_exp_f32_e32 v106, v106
	v_exp_f32_e32 v107, v107
	v_add_f32_e32 v106, 1.0, v106
	v_add_f32_e32 v107, 1.0, v107
	v_rcp_f32_e32 v106, v106
	v_rcp_f32_e32 v107, v107
	s_nop 0
	v_pk_mul_f32 v[100:101], v[100:101], v[106:107]
	s_nop 0
	v_pk_mul_f32 v[96:97], v[100:101], v[96:97]
	s_nop 0
	v_cvt_pk_bf16_f32 v106, v96, v97
	v_mul_f32_e32 v96, 0xbfb8aa3b, v102
	v_mul_f32_e32 v97, 0xbfb8aa3b, v103
	v_exp_f32_e32 v96, v96
	v_exp_f32_e32 v97, v97
	v_add_f32_e32 v96, 1.0, v96
	v_add_f32_e32 v97, 1.0, v97
	v_rcp_f32_e32 v96, v96
	v_rcp_f32_e32 v97, v97
	s_nop 0
	v_pk_mul_f32 v[96:97], v[102:103], v[96:97]
	s_nop 0
	v_pk_mul_f32 v[96:97], v[96:97], v[98:99]
	v_mul_f32_e32 v98, 0xbfb8aa3b, v92
	v_mul_f32_e32 v99, 0xbfb8aa3b, v93
	v_exp_f32_e32 v98, v98
	v_exp_f32_e32 v99, v99
	v_cvt_pk_bf16_f32 v107, v96, v97
	v_or_b32_e32 v96, 32, v146
	v_add_f32_e32 v98, 1.0, v98
	v_add_f32_e32 v99, 1.0, v99
	v_rcp_f32_e32 v98, v98
	v_rcp_f32_e32 v99, v99
	v_mad_i64_i32 v[96:97], s[12:13], v96, s81, v[138:139]
	v_lshl_add_u64 v[96:97], v[96:97], 0, v[140:141]
	v_pk_mul_f32 v[92:93], v[92:93], v[98:99]
	global_store_dwordx4 v[112:113], v[104:107], off
	v_pk_mul_f32 v[88:89], v[92:93], v[88:89]
	s_nop 0
	v_cvt_pk_bf16_f32 v88, v88, v89
	v_mul_f32_e32 v89, 0xbfb8aa3b, v94
	v_exp_f32_e32 v89, v89
	s_nop 0
	v_add_f32_e32 v89, 1.0, v89
	v_rcp_f32_e32 v92, v89
	v_mul_f32_e32 v89, 0xbfb8aa3b, v95
	v_exp_f32_e32 v89, v89
	s_nop 0
	v_add_f32_e32 v89, 1.0, v89
	v_rcp_f32_e32 v93, v89
	s_nop 0
	v_pk_mul_f32 v[92:93], v[94:95], v[92:93]
	s_nop 0
	v_pk_mul_f32 v[90:91], v[92:93], v[90:91]
	s_nop 0
	v_cvt_pk_bf16_f32 v89, v90, v91
	v_mul_f32_e32 v90, 0xbfb8aa3b, v84
	v_mul_f32_e32 v91, 0xbfb8aa3b, v85
	v_exp_f32_e32 v90, v90
	v_exp_f32_e32 v91, v91
	v_add_f32_e32 v90, 1.0, v90
	v_add_f32_e32 v91, 1.0, v91
	v_rcp_f32_e32 v90, v90
	v_rcp_f32_e32 v91, v91
	s_nop 0
	v_pk_mul_f32 v[84:85], v[84:85], v[90:91]
	s_nop 0
	v_pk_mul_f32 v[80:81], v[84:85], v[80:81]
	s_nop 0
	v_cvt_pk_bf16_f32 v90, v80, v81
	v_mul_f32_e32 v80, 0xbfb8aa3b, v86
	v_mul_f32_e32 v81, 0xbfb8aa3b, v87
	v_exp_f32_e32 v80, v80
	v_exp_f32_e32 v81, v81
	v_add_f32_e32 v80, 1.0, v80
	v_add_f32_e32 v81, 1.0, v81
	v_rcp_f32_e32 v80, v80
	v_rcp_f32_e32 v81, v81
	s_nop 0
	v_pk_mul_f32 v[80:81], v[86:87], v[80:81]
	s_nop 0
	v_pk_mul_f32 v[80:81], v[80:81], v[82:83]
	v_mul_f32_e32 v82, 0xbfb8aa3b, v76
	v_mul_f32_e32 v83, 0xbfb8aa3b, v77
	v_exp_f32_e32 v82, v82
	v_exp_f32_e32 v83, v83
	v_cvt_pk_bf16_f32 v91, v80, v81
	v_or_b32_e32 v80, 48, v146
; __device__ __forceinline__ unsigned cvtpk(float lo, float hi) { const f32x2 v = (f32x2){lo, hi}; const bf16v2 b = __builtin_convertvector(v, bf16v2); return __builtin_bit_cast(unsigned, b); }
; __device__ __forceinline__ float siluf_(float x) { return x * sigmoidf_(x); }
;     __device__ __forceinline__ void operator()(const f32x4 (&acc)[2][2][4][2], const pg8::Unit& u, int wr, int wc, int fr, int fq) const {
;         const int row0 = u.pm * 256 + wr * 64 + fr, col0 = u.pn * 128 + wc * 32 + 8 * fq;
; #pragma unroll
;         for (int ai = 0; ai < 2; ++ai)
; #pragma unroll
;             for (int m = 0; m < 4; ++m) { bf16_t* rowp = O + (size_t)(row0 + ai * 128 + m * 16) * ldc + col0;
;                 const f32x4 g0 = acc[ai][0][m][0], g1 = acc[ai][0][m][1], u0 = acc[ai][1][m][0], u1 = acc[ai][1][m][1];
;                 u32x4 w; w.x = cvtpk(siluf_(g0[0]) * u0[0], siluf_(g0[1]) * u0[1]); w.y = cvtpk(siluf_(g0[2]) * u0[2], siluf_(g0[3]) * u0[3]);
;                 w.z = cvtpk(siluf_(g1[0]) * u1[0], siluf_(g1[1]) * u1[1]); w.w = cvtpk(siluf_(g1[2]) * u1[2], siluf_(g1[3]) * u1[3]);
;                 *(u32x4*)rowp = w; }
	v_add_f32_e32 v82, 1.0, v82
	v_add_f32_e32 v83, 1.0, v83
	v_rcp_f32_e32 v82, v82
	v_rcp_f32_e32 v83, v83
	v_mad_i64_i32 v[80:81], s[12:13], v80, s81, v[138:139]
	v_lshl_add_u64 v[80:81], v[80:81], 0, v[140:141]
	v_pk_mul_f32 v[76:77], v[76:77], v[82:83]
	global_store_dwordx4 v[96:97], v[88:91], off
	v_pk_mul_f32 v[72:73], v[76:77], v[72:73]
	s_nop 0
	v_cvt_pk_bf16_f32 v72, v72, v73
	v_mul_f32_e32 v73, 0xbfb8aa3b, v78
	v_exp_f32_e32 v73, v73
	s_nop 0
	v_add_f32_e32 v73, 1.0, v73
	v_rcp_f32_e32 v76, v73
	v_mul_f32_e32 v73, 0xbfb8aa3b, v79
	v_exp_f32_e32 v73, v73
	s_nop 0
	v_add_f32_e32 v73, 1.0, v73
	v_rcp_f32_e32 v77, v73
	s_nop 0
	v_pk_mul_f32 v[76:77], v[78:79], v[76:77]
	s_nop 0
	v_pk_mul_f32 v[74:75], v[76:77], v[74:75]
	s_nop 0
	v_cvt_pk_bf16_f32 v73, v74, v75
	v_mul_f32_e32 v74, 0xbfb8aa3b, v68
	v_mul_f32_e32 v75, 0xbfb8aa3b, v69
	v_exp_f32_e32 v74, v74
	v_exp_f32_e32 v75, v75
	v_add_f32_e32 v74, 1.0, v74
	v_add_f32_e32 v75, 1.0, v75
	v_rcp_f32_e32 v74, v74
	v_rcp_f32_e32 v75, v75
	s_nop 0
	v_pk_mul_f32 v[68:69], v[68:69], v[74:75]
	s_nop 0
	v_pk_mul_f32 v[64:65], v[68:69], v[64:65]
	s_nop 0
	v_cvt_pk_bf16_f32 v74, v64, v65
	v_mul_f32_e32 v64, 0xbfb8aa3b, v70
	v_mul_f32_e32 v65, 0xbfb8aa3b, v71
	v_exp_f32_e32 v64, v64
	v_exp_f32_e32 v65, v65
	v_add_f32_e32 v64, 1.0, v64
	v_add_f32_e32 v65, 1.0, v65
	v_rcp_f32_e32 v64, v64
	v_rcp_f32_e32 v65, v65
	s_nop 0
	v_pk_mul_f32 v[64:65], v[70:71], v[64:65]
	s_nop 0
	v_pk_mul_f32 v[64:65], v[64:65], v[66:67]
	v_mul_f32_e32 v66, 0xbfb8aa3b, v60
	v_mul_f32_e32 v67, 0xbfb8aa3b, v61
	v_exp_f32_e32 v66, v66
	v_exp_f32_e32 v67, v67
	v_cvt_pk_bf16_f32 v75, v64, v65
	v_add_u32_e32 v64, 0x80, v146
	v_add_f32_e32 v66, 1.0, v66
	v_add_f32_e32 v67, 1.0, v67
	v_rcp_f32_e32 v66, v66
	v_rcp_f32_e32 v67, v67
	v_mad_i64_i32 v[64:65], s[12:13], v64, s81, v[138:139]
	v_lshl_add_u64 v[64:65], v[64:65], 0, v[140:141]
	v_pk_mul_f32 v[60:61], v[60:61], v[66:67]
	global_store_dwordx4 v[80:81], v[72:75], off
	v_pk_mul_f32 v[56:57], v[60:61], v[56:57]
	s_nop 0
	v_cvt_pk_bf16_f32 v56, v56, v57
	v_mul_f32_e32 v57, 0xbfb8aa3b, v62
	v_exp_f32_e32 v57, v57
	s_nop 0
	v_add_f32_e32 v57, 1.0, v57
	v_rcp_f32_e32 v60, v57
	v_mul_f32_e32 v57, 0xbfb8aa3b, v63
	v_exp_f32_e32 v57, v57
	s_nop 0
	v_add_f32_e32 v57, 1.0, v57
	v_rcp_f32_e32 v61, v57
	s_nop 0
	v_pk_mul_f32 v[60:61], v[62:63], v[60:61]
	s_nop 0
	v_pk_mul_f32 v[58:59], v[60:61], v[58:59]
	s_nop 0
	v_cvt_pk_bf16_f32 v57, v58, v59
	v_mul_f32_e32 v58, 0xbfb8aa3b, v52
	v_mul_f32_e32 v59, 0xbfb8aa3b, v53
	v_exp_f32_e32 v58, v58
	v_exp_f32_e32 v59, v59
	v_add_f32_e32 v58, 1.0, v58
	v_add_f32_e32 v59, 1.0, v59
	v_rcp_f32_e32 v58, v58
	v_rcp_f32_e32 v59, v59
	s_nop 0
	v_pk_mul_f32 v[52:53], v[52:53], v[58:59]
	s_nop 0
	v_pk_mul_f32 v[48:49], v[52:53], v[48:49]
	s_nop 0
	v_cvt_pk_bf16_f32 v58, v48, v49
	v_mul_f32_e32 v48, 0xbfb8aa3b, v54
	v_mul_f32_e32 v49, 0xbfb8aa3b, v55
	v_exp_f32_e32 v48, v48
	v_exp_f32_e32 v49, v49
	v_add_f32_e32 v48, 1.0, v48
	v_add_f32_e32 v49, 1.0, v49
	v_rcp_f32_e32 v48, v48
	v_rcp_f32_e32 v49, v49
	s_nop 0
	v_pk_mul_f32 v[48:49], v[54:55], v[48:49]
	s_nop 0
	v_pk_mul_f32 v[48:49], v[48:49], v[50:51]
	v_mul_f32_e32 v50, 0xbfb8aa3b, v44
	v_mul_f32_e32 v51, 0xbfb8aa3b, v45
	v_exp_f32_e32 v50, v50
	v_exp_f32_e32 v51, v51
	v_cvt_pk_bf16_f32 v59, v48, v49
	v_add_u32_e32 v48, 0x90, v146
	v_add_f32_e32 v50, 1.0, v50
	v_add_f32_e32 v51, 1.0, v51
	v_rcp_f32_e32 v50, v50
	v_rcp_f32_e32 v51, v51
	v_mad_i64_i32 v[48:49], s[12:13], v48, s81, v[138:139]
	v_lshl_add_u64 v[48:49], v[48:49], 0, v[140:141]
	v_pk_mul_f32 v[44:45], v[44:45], v[50:51]
	global_store_dwordx4 v[64:65], v[56:59], off
	v_pk_mul_f32 v[40:41], v[44:45], v[40:41]
	s_nop 0
	v_cvt_pk_bf16_f32 v40, v40, v41
	v_mul_f32_e32 v41, 0xbfb8aa3b, v46
	v_exp_f32_e32 v41, v41
	s_nop 0
	v_add_f32_e32 v41, 1.0, v41
	v_rcp_f32_e32 v44, v41
	v_mul_f32_e32 v41, 0xbfb8aa3b, v47
	v_exp_f32_e32 v41, v41
	s_nop 0
	v_add_f32_e32 v41, 1.0, v41
	v_rcp_f32_e32 v45, v41
	s_nop 0
	v_pk_mul_f32 v[44:45], v[46:47], v[44:45]
	s_nop 0
	v_pk_mul_f32 v[42:43], v[44:45], v[42:43]
	s_nop 0
	v_cvt_pk_bf16_f32 v41, v42, v43
	v_mul_f32_e32 v42, 0xbfb8aa3b, v36
	v_mul_f32_e32 v43, 0xbfb8aa3b, v37
; __device__ __forceinline__ unsigned cvtpk(float lo, float hi) { const f32x2 v = (f32x2){lo, hi}; const bf16v2 b = __builtin_convertvector(v, bf16v2); return __builtin_bit_cast(unsigned, b); }
; __device__ __forceinline__ float siluf_(float x) { return x * sigmoidf_(x); }
; #define PG8_WAIT_V(n) asm volatile("s_waitcnt vmcnt(" #n ")" ::: "memory")
; #define PG8_BAR __builtin_amdgcn_s_barrier()
; template <class Epi, class Sched>
; __device__ __forceinline__ void gemm_phase(PG8_LAS unsigned char* lds, const Gemm g, const Sched& S, const Epi& E) {
;     ...
;         if constexpr (!Epi::AFTER_DRAIN) { E(acc, cur, wr, wc, fr, fq); S.done(cur); }
;         if (!has_next) break;
; #pragma unroll
;         for (int a = 0; a < 2; ++a)
; #pragma unroll
;             for (int b = 0; b < 2; ++b)
; #pragma unroll
;                 for (int m = 0; m < 4; ++m)
; #pragma unroll
;                     for (int n = 0; n < 2; ++n) acc[a][b][m][n] = (f32x4){0.f, 0.f, 0.f, 0.f};
;         cur = nxt; cA = nA; cB = nB; ++ui;
;     }
;     PG8_WAIT_V(0);
;     if (wr == 0) PG8_BAR;
;     PG8_BAR;
;     __device__ __forceinline__ void operator()(const f32x4 (&acc)[2][2][4][2], const pg8::Unit& u, int wr, int wc, int fr, int fq) const {
;         const int row0 = u.pm * 256 + wr * 64 + fr, col0 = u.pn * 128 + wc * 32 + 8 * fq;
; #pragma unroll
;         for (int ai = 0; ai < 2; ++ai)
; #pragma unroll
;             for (int m = 0; m < 4; ++m) { bf16_t* rowp = O + (size_t)(row0 + ai * 128 + m * 16) * ldc + col0;
;                 const f32x4 g0 = acc[ai][0][m][0], g1 = acc[ai][0][m][1], u0 = acc[ai][1][m][0], u1 = acc[ai][1][m][1];
;                 u32x4 w; w.x = cvtpk(siluf_(g0[0]) * u0[0], siluf_(g0[1]) * u0[1]); w.y = cvtpk(siluf_(g0[2]) * u0[2], siluf_(g0[3]) * u0[3]);
;                 w.z = cvtpk(siluf_(g1[0]) * u1[0], siluf_(g1[1]) * u1[1]); w.w = cvtpk(siluf_(g1[2]) * u1[2], siluf_(g1[3]) * u1[3]);
;                 *(u32x4*)rowp = w; }
	v_exp_f32_e32 v42, v42
	v_exp_f32_e32 v43, v43
	v_add_f32_e32 v42, 1.0, v42
	v_add_f32_e32 v43, 1.0, v43
	v_rcp_f32_e32 v42, v42
	v_rcp_f32_e32 v43, v43
	s_nop 0
	v_pk_mul_f32 v[36:37], v[36:37], v[42:43]
	s_nop 0
	v_pk_mul_f32 v[32:33], v[36:37], v[32:33]
	s_nop 0
	v_cvt_pk_bf16_f32 v42, v32, v33
	v_mul_f32_e32 v32, 0xbfb8aa3b, v38
	v_mul_f32_e32 v33, 0xbfb8aa3b, v39
	v_exp_f32_e32 v32, v32
	v_exp_f32_e32 v33, v33
	v_add_f32_e32 v32, 1.0, v32
	v_add_f32_e32 v33, 1.0, v33
	v_rcp_f32_e32 v32, v32
	v_rcp_f32_e32 v33, v33
	s_nop 0
	v_pk_mul_f32 v[32:33], v[38:39], v[32:33]
	s_nop 0
	v_pk_mul_f32 v[32:33], v[32:33], v[34:35]
	v_mul_f32_e32 v34, 0xbfb8aa3b, v28
	v_mul_f32_e32 v35, 0xbfb8aa3b, v29
	v_exp_f32_e32 v34, v34
	v_exp_f32_e32 v35, v35
	v_cvt_pk_bf16_f32 v43, v32, v33
	v_add_u32_e32 v32, 0xa0, v146
	v_add_f32_e32 v34, 1.0, v34
	v_add_f32_e32 v35, 1.0, v35
	v_rcp_f32_e32 v34, v34
	v_rcp_f32_e32 v35, v35
	v_mad_i64_i32 v[32:33], s[12:13], v32, s81, v[138:139]
	v_lshl_add_u64 v[32:33], v[32:33], 0, v[140:141]
	v_pk_mul_f32 v[28:29], v[28:29], v[34:35]
	global_store_dwordx4 v[48:49], v[40:43], off
	v_pk_mul_f32 v[24:25], v[28:29], v[24:25]
	s_nop 0
	v_cvt_pk_bf16_f32 v24, v24, v25
	v_mul_f32_e32 v25, 0xbfb8aa3b, v30
	v_exp_f32_e32 v25, v25
	s_nop 0
	v_add_f32_e32 v25, 1.0, v25
	v_rcp_f32_e32 v28, v25
	v_mul_f32_e32 v25, 0xbfb8aa3b, v31
	v_exp_f32_e32 v25, v25
	s_nop 0
	v_add_f32_e32 v25, 1.0, v25
	v_rcp_f32_e32 v29, v25
	s_nop 0
	v_pk_mul_f32 v[28:29], v[30:31], v[28:29]
	s_nop 0
	v_pk_mul_f32 v[26:27], v[28:29], v[26:27]
	s_nop 0
	v_cvt_pk_bf16_f32 v25, v26, v27
	v_mul_f32_e32 v26, 0xbfb8aa3b, v20
	v_mul_f32_e32 v27, 0xbfb8aa3b, v21
	v_exp_f32_e32 v26, v26
	v_exp_f32_e32 v27, v27
	v_add_f32_e32 v26, 1.0, v26
	v_add_f32_e32 v27, 1.0, v27
	v_rcp_f32_e32 v26, v26
	v_rcp_f32_e32 v27, v27
	s_nop 0
	v_pk_mul_f32 v[20:21], v[20:21], v[26:27]
	s_nop 0
	v_pk_mul_f32 v[16:17], v[20:21], v[16:17]
	s_nop 0
	v_cvt_pk_bf16_f32 v26, v16, v17
	v_mul_f32_e32 v16, 0xbfb8aa3b, v22
	v_mul_f32_e32 v17, 0xbfb8aa3b, v23
	v_exp_f32_e32 v16, v16
	v_exp_f32_e32 v17, v17
	v_add_f32_e32 v16, 1.0, v16
	v_add_f32_e32 v17, 1.0, v17
	v_rcp_f32_e32 v16, v16
	v_rcp_f32_e32 v17, v17
	s_nop 0
	v_pk_mul_f32 v[16:17], v[22:23], v[16:17]
	s_nop 0
	v_pk_mul_f32 v[16:17], v[16:17], v[18:19]
	v_mul_f32_e32 v18, 0xbfb8aa3b, v12
	v_mul_f32_e32 v19, 0xbfb8aa3b, v13
	v_exp_f32_e32 v18, v18
	v_exp_f32_e32 v19, v19
	v_cvt_pk_bf16_f32 v27, v16, v17
	v_add_u32_e32 v16, 0xb0, v146
	v_add_f32_e32 v18, 1.0, v18
	v_add_f32_e32 v19, 1.0, v19
	v_rcp_f32_e32 v18, v18
	v_rcp_f32_e32 v19, v19
	v_mad_i64_i32 v[16:17], s[12:13], v16, s81, v[138:139]
	v_lshl_add_u64 v[16:17], v[16:17], 0, v[140:141]
	v_pk_mul_f32 v[12:13], v[12:13], v[18:19]
	s_mov_b64 s[12:13], s[6:7]
	v_pk_mul_f32 v[8:9], v[12:13], v[8:9]
	global_store_dwordx4 v[32:33], v[24:27], off
	v_cvt_pk_bf16_f32 v8, v8, v9
	v_mul_f32_e32 v9, 0xbfb8aa3b, v14
	v_exp_f32_e32 v9, v9
	s_nop 0
	v_add_f32_e32 v9, 1.0, v9
	v_rcp_f32_e32 v12, v9
	v_mul_f32_e32 v9, 0xbfb8aa3b, v15
	v_exp_f32_e32 v9, v9
	s_nop 0
	v_add_f32_e32 v9, 1.0, v9
	v_rcp_f32_e32 v13, v9
	s_nop 0
	v_pk_mul_f32 v[12:13], v[14:15], v[12:13]
	s_nop 0
	v_pk_mul_f32 v[10:11], v[12:13], v[10:11]
	s_nop 0
	v_cvt_pk_bf16_f32 v9, v10, v11
	v_mul_f32_e32 v10, 0xbfb8aa3b, v4
	v_mul_f32_e32 v11, 0xbfb8aa3b, v5
	v_exp_f32_e32 v10, v10
	v_exp_f32_e32 v11, v11
	v_add_f32_e32 v10, 1.0, v10
	v_add_f32_e32 v11, 1.0, v11
	v_rcp_f32_e32 v10, v10
	v_rcp_f32_e32 v11, v11
	s_nop 0
	v_pk_mul_f32 v[4:5], v[4:5], v[10:11]
	s_nop 0
	v_pk_mul_f32 v[0:1], v[4:5], v[0:1]
	s_nop 0
	v_cvt_pk_bf16_f32 v10, v0, v1
	v_mul_f32_e32 v0, 0xbfb8aa3b, v6
	v_mul_f32_e32 v1, 0xbfb8aa3b, v7
	v_exp_f32_e32 v0, v0
	v_exp_f32_e32 v1, v1
	v_add_f32_e32 v0, 1.0, v0
	v_add_f32_e32 v1, 1.0, v1
	v_rcp_f32_e32 v0, v0
	v_rcp_f32_e32 v1, v1
	s_nop 0
	v_pk_mul_f32 v[0:1], v[6:7], v[0:1]
	s_nop 0
	v_pk_mul_f32 v[0:1], v[0:1], v[2:3]
	s_nop 0
	v_cvt_pk_bf16_f32 v11, v0, v1
	global_store_dwordx4 v[16:17], v[8:11], off
	s_cbranch_vccz .LBB0_111
	s_waitcnt vmcnt(0)
	v_readlane_b32 s22, v255, 14
	s_cmpk_gt_u32 s19, 0xff
	v_readlane_b32 s23, v255, 15
	s_mov_b64 s[28:29], s[54:55]
	s_cbranch_scc1 .LBB0_118
	s_barrier

; #define PG8_STAGE(bufoff, gbase, voff) do { _Pragma("unroll") for (int _i = 0; _i < 2; ++_i) \
;         __builtin_amdgcn_global_load_lds((const unsigned*)((const char*)(gbase) + (voff)[_i]), (PG8_LAS unsigned*)(lds + (bufoff) + ldsw + _i * 8192), 16, 0, 0); } while (0)
; #define PG8_LDA(dst, b, h) do { _Pragma("unroll") for (int m = 0; m < 4; ++m) _Pragma("unroll") for (int k = 0; k < 2; ++k) dst[m][k] = *(const PG8_LAS bf16x8*)(lds + PG8_SA(b, h) + aoff + m * 2048 + k * 1024); } while (0)
; #define PG8_LDB(dst, b, h) do { _Pragma("unroll") for (int n = 0; n < 2; ++n) _Pragma("unroll") for (int k = 0; k < 2; ++k) dst[n][k] = *(const PG8_LAS bf16x8*)(lds + PG8_SB(b, h) + boff + n * 2048 + k * 1024); } while (0)
; #define PG8_WAIT_L(n) asm volatile("s_waitcnt lgkmcnt(" #n ")" ::: "memory")
; #define PG8_BAR __builtin_amdgcn_s_barrier()
; #define PG8_SCHED __builtin_amdgcn_sched_barrier(0)
; template <class Epi, class Sched>
; __device__ __forceinline__ void gemm_phase(PG8_LAS unsigned char* lds, const Gemm g, const Sched& S, const Epi& E) {
;     ...
;         const bool has_next = S.next(ui + 1, nxt);
;         const char* nA = has_next ? (const char*)g.A + (size_t)nxt.pm * tstep : cA; const char* nB = has_next ? (const char*)g.Bt + (size_t)nxt.pn * tstep : cB;
;         for (int t = 0; t < nt; t += 2) {
;             const bool last = (t == nt - 2);
;             const char* a1 = cA + (size_t)(t + 1) * kstep;
;             const char* a2 = last ? nA : cA + (size_t)(t + 2) * kstep; const char* b2 = last ? nB : cB + (size_t)(t + 2) * kstep;
;             const char* a3 = a2 + kstep; const char* b3 = b2 + kstep;
;             if (last && has_next) S.a_ready(nxt);
;             PG8_LDB(B0, 0, 0); PG8_SCHED; PG8_LDA(At, 0, 0); PG8_STAGE(PG8_SA(1, 1), a1 + hstep, voffA);
;             PG8_WAIT_L(8); PG8_BAR; PG8_WAIT_L(0); PG8_MMA(0, 0, At, B0); PG8_BAR; PG8_SCHED;
;     ...
; #pragma unroll
;         for (int a = 0; a < 2; ++a)
; #pragma unroll
;             for (int b = 0; b < 2; ++b)
; #pragma unroll
;                 for (int m = 0; m < 4; ++m)
; #pragma unroll
;                     for (int n = 0; n < 2; ++n) acc[a][b][m][n] = (f32x4){0.f, 0.f, 0.f, 0.f};
;         cur = nxt; cA = nA; cB = nB; ++ui;
.LBB0_136:
	v_mov_b64_e32 v[0:1], 0x100
	s_ashr_i32 s7, s6, 31
	v_cmp_lt_i64_e32 vcc, s[8:9], v[0:1]
	s_lshl_b64 s[8:9], s[6:7], 19
	s_add_u32 s8, s94, s8
	s_addc_u32 s9, s95, s9
	s_and_b64 s[10:11], vcc, exec
	s_cselect_b32 s7, s9, s13
	s_cselect_b32 s40, s8, s12
	s_ashr_i32 s5, s4, 31
	s_lshl_b64 s[10:11], s[4:5], 19
	v_readlane_b32 s16, v253, 10
	v_readlane_b32 s17, v253, 11
	s_add_u32 s10, s16, s10
	s_addc_u32 s11, s17, s11
	s_and_b64 s[16:17], vcc, exec
	s_cselect_b32 s5, s11, s15
	s_cselect_b32 s41, s10, s14
	s_add_u32 s12, s12, 0x40080
	s_addc_u32 s13, s13, 0
	s_add_u32 s43, s14, 0x100
	v_mov_b32_e32 v0, 0
	s_addc_u32 s44, s15, 0
	s_mov_b32 s45, -2
	v_mov_b32_e32 v1, v0
	v_mov_b32_e32 v2, v0
	v_mov_b32_e32 v3, v0
	v_mov_b32_e32 v4, v0
	v_mov_b32_e32 v5, v0
	v_mov_b32_e32 v6, v0
	v_mov_b32_e32 v7, v0
	v_mov_b32_e32 v8, v0
	v_mov_b32_e32 v9, v0
	v_mov_b32_e32 v10, v0
	v_mov_b32_e32 v11, v0
	v_mov_b32_e32 v12, v0
	v_mov_b32_e32 v13, v0
	v_mov_b32_e32 v14, v0
	v_mov_b32_e32 v15, v0
	v_mov_b32_e32 v24, v0
	v_mov_b32_e32 v25, v0
	v_mov_b32_e32 v26, v0
	v_mov_b32_e32 v27, v0
	v_mov_b32_e32 v28, v0
	v_mov_b32_e32 v29, v0
	v_mov_b32_e32 v30, v0
	v_mov_b32_e32 v31, v0
	v_mov_b32_e32 v40, v0
	v_mov_b32_e32 v41, v0
	v_mov_b32_e32 v42, v0
	v_mov_b32_e32 v43, v0
	v_mov_b32_e32 v44, v0
	v_mov_b32_e32 v45, v0
	v_mov_b32_e32 v46, v0
	v_mov_b32_e32 v47, v0
	v_mov_b32_e32 v16, v0
	v_mov_b32_e32 v17, v0
	v_mov_b32_e32 v18, v0
	v_mov_b32_e32 v19, v0
	v_mov_b32_e32 v20, v0
	v_mov_b32_e32 v21, v0
	v_mov_b32_e32 v22, v0
	v_mov_b32_e32 v23, v0
	v_mov_b32_e32 v32, v0
	v_mov_b32_e32 v33, v0
	v_mov_b32_e32 v34, v0
	v_mov_b32_e32 v35, v0
	v_mov_b32_e32 v36, v0
	v_mov_b32_e32 v37, v0
	v_mov_b32_e32 v38, v0
	v_mov_b32_e32 v39, v0
	v_mov_b32_e32 v48, v0
	v_mov_b32_e32 v49, v0
	v_mov_b32_e32 v50, v0
	v_mov_b32_e32 v51, v0
	v_mov_b32_e32 v52, v0
	v_mov_b32_e32 v53, v0
	v_mov_b32_e32 v54, v0
	v_mov_b32_e32 v55, v0
	v_mov_b32_e32 v56, v0
	v_mov_b32_e32 v57, v0
	v_mov_b32_e32 v58, v0
	v_mov_b32_e32 v59, v0
	v_mov_b32_e32 v60, v0
	v_mov_b32_e32 v61, v0
	v_mov_b32_e32 v62, v0
	v_mov_b32_e32 v63, v0
	v_mov_b32_e32 v64, v0
	v_mov_b32_e32 v65, v0
	v_mov_b32_e32 v66, v0
	v_mov_b32_e32 v67, v0
	v_mov_b32_e32 v68, v0
	v_mov_b32_e32 v69, v0
	v_mov_b32_e32 v70, v0
	v_mov_b32_e32 v71, v0
	v_mov_b32_e32 v72, v0
	v_mov_b32_e32 v73, v0
	v_mov_b32_e32 v74, v0
	v_mov_b32_e32 v75, v0
	v_mov_b32_e32 v76, v0
	v_mov_b32_e32 v77, v0
	v_mov_b32_e32 v78, v0
	v_mov_b32_e32 v79, v0
	v_mov_b32_e32 v88, v0
	v_mov_b32_e32 v89, v0
	v_mov_b32_e32 v90, v0
	v_mov_b32_e32 v91, v0
	v_mov_b32_e32 v92, v0
	v_mov_b32_e32 v93, v0
	v_mov_b32_e32 v94, v0
	v_mov_b32_e32 v95, v0
	v_mov_b32_e32 v104, v0
	v_mov_b32_e32 v105, v0
	v_mov_b32_e32 v106, v0
	v_mov_b32_e32 v107, v0
	v_mov_b32_e32 v108, v0
	v_mov_b32_e32 v109, v0
	v_mov_b32_e32 v110, v0
	v_mov_b32_e32 v111, v0
	v_mov_b32_e32 v80, v0
	v_mov_b32_e32 v81, v0
	v_mov_b32_e32 v82, v0
	v_mov_b32_e32 v83, v0
	v_mov_b32_e32 v84, v0
	v_mov_b32_e32 v85, v0
	v_mov_b32_e32 v86, v0
	v_mov_b32_e32 v87, v0
	v_mov_b32_e32 v96, v0
	v_mov_b32_e32 v97, v0
	v_mov_b32_e32 v98, v0
	v_mov_b32_e32 v99, v0
	v_mov_b32_e32 v100, v0
	v_mov_b32_e32 v101, v0
	v_mov_b32_e32 v102, v0
	v_mov_b32_e32 v103, v0
	v_mov_b32_e32 v112, v0
	v_mov_b32_e32 v113, v0
	v_mov_b32_e32 v114, v0
	v_mov_b32_e32 v115, v0
	v_mov_b32_e32 v116, v0
	v_mov_b32_e32 v117, v0
	v_mov_b32_e32 v118, v0
	v_mov_b32_e32 v119, v0
	v_mov_b32_e32 v120, v0
	v_mov_b32_e32 v121, v0
	v_mov_b32_e32 v122, v0
	v_mov_b32_e32 v123, v0
	v_mov_b32_e32 v124, v0
	v_mov_b32_e32 v125, v0
	v_mov_b32_e32 v126, v0
	v_mov_b32_e32 v127, v0
	v_add_u32_e32 v154, 0x10000, v139
	v_add_u32_e32 v174, 0x14000, v139
.LBB0_137:
	ds_read_b128 v[142:145], v154
	ds_read_b128 v[146:149], v154 offset:1024
	ds_read_b128 v[150:153], v154 offset:2048
	ds_read_b128 v[154:157], v154 offset:3072
	s_add_u32 s14, s12, 0xfffc0080
	s_addc_u32 s15, s13, -1
	s_cmp_eq_u32 s45, 12
	s_cselect_b32 s17, s7, s15
	s_cselect_b32 s16, s40, s14
	s_cselect_b32 s15, s5, s44
	s_cselect_b32 s14, s41, s43
	s_add_i32 m0, s1, 0xc000
	ds_read_b128 v[158:161], v141
	ds_read_b128 v[162:165], v141 offset:1024
	ds_read_b128 v[166:169], v141 offset:2048
	ds_read_b128 v[170:173], v141 offset:3072
	ds_read_b128 v[178:181], v141 offset:4096
	ds_read_b128 v[182:185], v141 offset:5120
	ds_read_b128 v[186:189], v141 offset:6144
	global_load_lds_dwordx4 v134, s[12:13]
	s_add_i32 m0, s1, 0xe000
	ds_read_b128 v[190:193], v141 offset:7168
	global_load_lds_dwordx4 v136, s[12:13]
	s_waitcnt lgkmcnt(8)
	s_barrier
	s_waitcnt lgkmcnt(7)
	v_mfma_f32_16x16x32_bf16 v[124:127], v[142:145], v[158:161], v[124:127]
	v_mfma_f32_16x16x32_bf16 v[120:123], v[150:153], v[158:161], v[120:123]
	s_waitcnt lgkmcnt(5)
	v_mfma_f32_16x16x32_bf16 v[116:119], v[142:145], v[166:169], v[116:119]
	v_mfma_f32_16x16x32_bf16 v[112:115], v[150:153], v[166:169], v[112:115]
	s_waitcnt lgkmcnt(3)
	v_mfma_f32_16x16x32_bf16 v[100:103], v[142:145], v[178:181], v[100:103]
	v_mfma_f32_16x16x32_bf16 v[96:99], v[150:153], v[178:181], v[96:99]
	s_waitcnt lgkmcnt(1)
	v_mfma_f32_16x16x32_bf16 v[84:87], v[142:145], v[186:189], v[84:87]
	v_mfma_f32_16x16x32_bf16 v[80:83], v[150:153], v[186:189], v[80:83]
	v_mfma_f32_16x16x32_bf16 v[124:127], v[146:149], v[162:165], v[124:127]
	v_mfma_f32_16x16x32_bf16 v[120:123], v[154:157], v[162:165], v[120:123]
	v_mfma_f32_16x16x32_bf16 v[116:119], v[146:149], v[170:173], v[116:119]
	v_mfma_f32_16x16x32_bf16 v[112:115], v[154:157], v[170:173], v[112:115]
	v_mfma_f32_16x16x32_bf16 v[100:103], v[146:149], v[182:185], v[100:103]
	v_mfma_f32_16x16x32_bf16 v[96:99], v[154:157], v[182:185], v[96:99]
	s_waitcnt lgkmcnt(0)
	v_mfma_f32_16x16x32_bf16 v[84:87], v[146:149], v[190:193], v[84:87]
	v_mfma_f32_16x16x32_bf16 v[80:83], v[154:157], v[190:193], v[80:83]
	s_barrier
; #define PG8_STAGE(bufoff, gbase, voff) do { _Pragma("unroll") for (int _i = 0; _i < 2; ++_i) \
;         __builtin_amdgcn_global_load_lds((const unsigned*)((const char*)(gbase) + (voff)[_i]), (PG8_LAS unsigned*)(lds + (bufoff) + ldsw + _i * 8192), 16, 0, 0); } while (0)
; #define PG8_LDA(dst, b, h) do { _Pragma("unroll") for (int m = 0; m < 4; ++m) _Pragma("unroll") for (int k = 0; k < 2; ++k) dst[m][k] = *(const PG8_LAS bf16x8*)(lds + PG8_SA(b, h) + aoff + m * 2048 + k * 1024); } while (0)
; #define PG8_LDB(dst, b, h) do { _Pragma("unroll") for (int n = 0; n < 2; ++n) _Pragma("unroll") for (int k = 0; k < 2; ++k) dst[n][k] = *(const PG8_LAS bf16x8*)(lds + PG8_SB(b, h) + boff + n * 2048 + k * 1024); } while (0)
; #define PG8_MMA(ai, bj, At, Bt) do { __builtin_amdgcn_s_setprio(1); _Pragma("unroll") for (int m = 0; m < 4; ++m) _Pragma("unroll") for (int n = 0; n < 2; ++n) _Pragma("unroll") for (int k = 0; k < 2; ++k) \
;         acc[ai][bj][m][n] = __builtin_amdgcn_mfma_f32_16x16x32_bf16(Bt[n][k], At[m][k], acc[ai][bj][m][n], 0, 0, 0); __builtin_amdgcn_s_setprio(0); } while (0)
; #define PG8_WAIT_V(n) asm volatile("s_waitcnt vmcnt(" #n ")" ::: "memory")
; #define PG8_WAIT_L(n) asm volatile("s_waitcnt lgkmcnt(" #n ")" ::: "memory")
; #define PG8_BAR __builtin_amdgcn_s_barrier()
; #define PG8_SCHED __builtin_amdgcn_sched_barrier(0)
; template <class Epi, class Sched>
; __device__ __forceinline__ void gemm_phase(PG8_LAS unsigned char* lds, const Gemm g, const Sched& S, const Epi& E) {
;     ...
;             PG8_LDB(B1, 0, 1); PG8_STAGE(PG8_SB(0, 0), b2, voffB);
;             PG8_BAR; PG8_WAIT_L(0); PG8_MMA(0, 1, At, B1); PG8_BAR;
;             PG8_LDA(At, 0, 1); PG8_STAGE(PG8_SA(0, 0), a2, voffA);
;             PG8_BAR; PG8_WAIT_L(0); PG8_MMA(1, 0, At, B0); PG8_BAR; PG8_SCHED;
;             PG8_STAGE(PG8_SB(0, 1), b2 + hstep, voffB);
;             PG8_WAIT_V(6); PG8_BAR; PG8_MMA(1, 1, At, B1); PG8_BAR;
;             PG8_LDB(B0, 1, 0); PG8_SCHED; PG8_LDA(At, 1, 0); PG8_STAGE(PG8_SA(0, 1), a2 + hstep, voffA);
;             PG8_WAIT_L(8); PG8_BAR; PG8_WAIT_L(0); PG8_MMA(0, 0, At, B0); PG8_BAR; PG8_SCHED;
	s_add_i32 s48, 0, 0x14000
	ds_read_b128 v[194:197], v174
	ds_read_b128 v[198:201], v174 offset:1024
	s_add_u32 s98, s14, 0x80
	s_addc_u32 s99, s15, 0
	s_add_i32 m0, s20, 0x10000
	ds_read_b128 v[202:205], v174 offset:2048
	global_load_lds_dwordx4 v176, s[14:15]
	s_add_i32 m0, s20, 0x12000
	ds_read_b128 v[206:209], v174 offset:3072
	global_load_lds_dwordx4 v128, s[14:15]
	s_barrier
	s_waitcnt lgkmcnt(3)
	v_mfma_f32_16x16x32_bf16 v[108:111], v[194:197], v[158:161], v[108:111]
	s_waitcnt lgkmcnt(1)
	v_mfma_f32_16x16x32_bf16 v[104:107], v[202:205], v[158:161], v[104:107]
	v_mfma_f32_16x16x32_bf16 v[92:95], v[194:197], v[166:169], v[92:95]
	v_mfma_f32_16x16x32_bf16 v[88:91], v[202:205], v[166:169], v[88:91]
	v_mfma_f32_16x16x32_bf16 v[76:79], v[194:197], v[178:181], v[76:79]
	v_mfma_f32_16x16x32_bf16 v[72:75], v[202:205], v[178:181], v[72:75]
	v_mfma_f32_16x16x32_bf16 v[68:71], v[194:197], v[186:189], v[68:71]
	v_mfma_f32_16x16x32_bf16 v[64:67], v[202:205], v[186:189], v[64:67]
	v_mfma_f32_16x16x32_bf16 v[108:111], v[198:201], v[162:165], v[108:111]
	s_waitcnt lgkmcnt(0)
	v_mfma_f32_16x16x32_bf16 v[104:107], v[206:209], v[162:165], v[104:107]
	v_mfma_f32_16x16x32_bf16 v[92:95], v[198:201], v[170:173], v[92:95]
	v_mfma_f32_16x16x32_bf16 v[88:91], v[206:209], v[170:173], v[88:91]
	v_mfma_f32_16x16x32_bf16 v[76:79], v[198:201], v[182:185], v[76:79]
	v_mfma_f32_16x16x32_bf16 v[72:75], v[206:209], v[182:185], v[72:75]
	v_mfma_f32_16x16x32_bf16 v[68:71], v[198:201], v[190:193], v[68:71]
	v_mfma_f32_16x16x32_bf16 v[64:67], v[206:209], v[190:193], v[64:67]
	s_mov_b32 m0, s1
	s_add_u32 s100, s16, 0x80
	s_addc_u32 s101, s17, 0
	s_barrier
	ds_read_b128 v[158:161], v141 offset:16384
	ds_read_b128 v[162:165], v141 offset:17408
	ds_read_b128 v[166:169], v141 offset:18432
	ds_read_b128 v[170:173], v141 offset:19456
	ds_read_b128 v[178:181], v141 offset:20480
	ds_read_b128 v[182:185], v141 offset:21504
	ds_read_b128 v[186:189], v141 offset:22528
	global_load_lds_dwordx4 v132, s[16:17]
	s_mov_b32 m0, s22
	ds_read_b128 v[190:193], v141 offset:23552
	global_load_lds_dwordx4 v130, s[16:17]
	s_barrier
	s_waitcnt lgkmcnt(7)
	v_mfma_f32_16x16x32_bf16 v[60:63], v[142:145], v[158:161], v[60:63]
	v_mfma_f32_16x16x32_bf16 v[56:59], v[150:153], v[158:161], v[56:59]
	s_waitcnt lgkmcnt(5)
	v_mfma_f32_16x16x32_bf16 v[52:55], v[142:145], v[166:169], v[52:55]
	v_mfma_f32_16x16x32_bf16 v[48:51], v[150:153], v[166:169], v[48:51]
	s_waitcnt lgkmcnt(3)
	v_mfma_f32_16x16x32_bf16 v[36:39], v[142:145], v[178:181], v[36:39]
	v_mfma_f32_16x16x32_bf16 v[32:35], v[150:153], v[178:181], v[32:35]
	s_waitcnt lgkmcnt(1)
	v_mfma_f32_16x16x32_bf16 v[20:23], v[142:145], v[186:189], v[20:23]
	v_mfma_f32_16x16x32_bf16 v[16:19], v[150:153], v[186:189], v[16:19]
	v_mfma_f32_16x16x32_bf16 v[60:63], v[146:149], v[162:165], v[60:63]
	v_mfma_f32_16x16x32_bf16 v[56:59], v[154:157], v[162:165], v[56:59]
	v_mfma_f32_16x16x32_bf16 v[52:55], v[146:149], v[170:173], v[52:55]
	v_mfma_f32_16x16x32_bf16 v[48:51], v[154:157], v[170:173], v[48:51]
	v_mfma_f32_16x16x32_bf16 v[36:39], v[146:149], v[182:185], v[36:39]
	v_mfma_f32_16x16x32_bf16 v[32:35], v[154:157], v[182:185], v[32:35]
	s_waitcnt lgkmcnt(0)
	v_mfma_f32_16x16x32_bf16 v[20:23], v[146:149], v[190:193], v[20:23]
	v_mfma_f32_16x16x32_bf16 v[16:19], v[154:157], v[190:193], v[16:19]
	s_barrier
	s_add_u32 s46, s14, 0x40000
	s_addc_u32 s47, s15, 0
	s_add_i32 m0, s20, 0x14000
	s_nop 0
	global_load_lds_dwordx4 v176, s[46:47]
	s_add_i32 m0, s20, 0x16000
	s_nop 0
	global_load_lds_dwordx4 v128, s[46:47]
	s_waitcnt vmcnt(6)
	s_barrier
	v_mfma_f32_16x16x32_bf16 v[44:47], v[194:197], v[158:161], v[44:47]
	v_mfma_f32_16x16x32_bf16 v[40:43], v[202:205], v[158:161], v[40:43]
	v_mfma_f32_16x16x32_bf16 v[28:31], v[194:197], v[166:169], v[28:31]
	v_mfma_f32_16x16x32_bf16 v[24:27], v[202:205], v[166:169], v[24:27]
	v_mfma_f32_16x16x32_bf16 v[12:15], v[194:197], v[178:181], v[12:15]
	v_mfma_f32_16x16x32_bf16 v[8:11], v[202:205], v[178:181], v[8:11]
	v_mfma_f32_16x16x32_bf16 v[4:7], v[194:197], v[186:189], v[4:7]
	v_mfma_f32_16x16x32_bf16 v[0:3], v[202:205], v[186:189], v[0:3]
	v_mfma_f32_16x16x32_bf16 v[44:47], v[198:201], v[162:165], v[44:47]
	v_mfma_f32_16x16x32_bf16 v[40:43], v[206:209], v[162:165], v[40:43]
	v_mfma_f32_16x16x32_bf16 v[28:31], v[198:201], v[170:173], v[28:31]
	v_mfma_f32_16x16x32_bf16 v[24:27], v[206:209], v[170:173], v[24:27]
	v_mfma_f32_16x16x32_bf16 v[12:15], v[198:201], v[182:185], v[12:15]
	v_mfma_f32_16x16x32_bf16 v[8:11], v[206:209], v[182:185], v[8:11]
	v_mfma_f32_16x16x32_bf16 v[4:7], v[198:201], v[190:193], v[4:7]
	v_mfma_f32_16x16x32_bf16 v[0:3], v[206:209], v[190:193], v[0:3]
	v_add_u32_e32 v154, 0x18000, v139
	s_barrier
	ds_read_b128 v[142:145], v154
	ds_read_b128 v[146:149], v154 offset:1024
	ds_read_b128 v[150:153], v154 offset:2048
	ds_read_b128 v[154:157], v154 offset:3072
	s_add_u32 s16, s16, 0x40000
	s_addc_u32 s17, s17, 0
	s_mov_b32 m0, s23
	ds_read_b128 v[158:161], v141 offset:32768
	ds_read_b128 v[162:165], v141 offset:33792
	ds_read_b128 v[166:169], v141 offset:34816
	ds_read_b128 v[170:173], v141 offset:35840
	ds_read_b128 v[178:181], v141 offset:36864
	ds_read_b128 v[182:185], v141 offset:37888
	ds_read_b128 v[186:189], v141 offset:38912
	global_load_lds_dwordx4 v132, s[16:17]
	s_mov_b32 m0, s26
	ds_read_b128 v[190:193], v141 offset:39936
	global_load_lds_dwordx4 v130, s[16:17]
	s_waitcnt lgkmcnt(8)
	s_barrier
; #define PG8_STAGE(bufoff, gbase, voff) do { _Pragma("unroll") for (int _i = 0; _i < 2; ++_i) \
;         __builtin_amdgcn_global_load_lds((const unsigned*)((const char*)(gbase) + (voff)[_i]), (PG8_LAS unsigned*)(lds + (bufoff) + ldsw + _i * 8192), 16, 0, 0); } while (0)
; #define PG8_LDA(dst, b, h) do { _Pragma("unroll") for (int m = 0; m < 4; ++m) _Pragma("unroll") for (int k = 0; k < 2; ++k) dst[m][k] = *(const PG8_LAS bf16x8*)(lds + PG8_SA(b, h) + aoff + m * 2048 + k * 1024); } while (0)
; #define PG8_LDB(dst, b, h) do { _Pragma("unroll") for (int n = 0; n < 2; ++n) _Pragma("unroll") for (int k = 0; k < 2; ++k) dst[n][k] = *(const PG8_LAS bf16x8*)(lds + PG8_SB(b, h) + boff + n * 2048 + k * 1024); } while (0)
; #define PG8_MMA(ai, bj, At, Bt) do { __builtin_amdgcn_s_setprio(1); _Pragma("unroll") for (int m = 0; m < 4; ++m) _Pragma("unroll") for (int n = 0; n < 2; ++n) _Pragma("unroll") for (int k = 0; k < 2; ++k) \
;         acc[ai][bj][m][n] = __builtin_amdgcn_mfma_f32_16x16x32_bf16(Bt[n][k], At[m][k], acc[ai][bj][m][n], 0, 0, 0); __builtin_amdgcn_s_setprio(0); } while (0)
; #define PG8_WAIT_V(n) asm volatile("s_waitcnt vmcnt(" #n ")" ::: "memory")
; #define PG8_WAIT_L(n) asm volatile("s_waitcnt lgkmcnt(" #n ")" ::: "memory")
; #define PG8_BAR __builtin_amdgcn_s_barrier()
; #define PG8_SCHED __builtin_amdgcn_sched_barrier(0)
; template <class Epi, class Sched>
; __device__ __forceinline__ void gemm_phase(PG8_LAS unsigned char* lds, const Gemm g, const Sched& S, const Epi& E) {
;     ...
;             PG8_WAIT_L(8); PG8_BAR; PG8_WAIT_L(0); PG8_MMA(0, 0, At, B0); PG8_BAR; PG8_SCHED;
;             PG8_LDB(B1, 1, 1); PG8_STAGE(PG8_SB(1, 0), b3, voffB);
;             PG8_BAR; PG8_WAIT_L(0); PG8_MMA(0, 1, At, B1); PG8_BAR;
;             PG8_LDA(At, 1, 1); PG8_STAGE(PG8_SA(1, 0), a3, voffA);
;             PG8_BAR; PG8_WAIT_L(0); PG8_MMA(1, 0, At, B0); PG8_BAR; PG8_SCHED;
;             PG8_STAGE(PG8_SB(1, 1), b3 + hstep, voffB);
;             PG8_WAIT_V(6); PG8_BAR; PG8_MMA(1, 1, At, B1); PG8_BAR;
;         }
	s_waitcnt lgkmcnt(7)
	v_mfma_f32_16x16x32_bf16 v[124:127], v[142:145], v[158:161], v[124:127]
	v_mfma_f32_16x16x32_bf16 v[120:123], v[150:153], v[158:161], v[120:123]
	s_waitcnt lgkmcnt(5)
	v_mfma_f32_16x16x32_bf16 v[116:119], v[142:145], v[166:169], v[116:119]
	v_mfma_f32_16x16x32_bf16 v[112:115], v[150:153], v[166:169], v[112:115]
	s_waitcnt lgkmcnt(3)
	v_mfma_f32_16x16x32_bf16 v[100:103], v[142:145], v[178:181], v[100:103]
	v_mfma_f32_16x16x32_bf16 v[96:99], v[150:153], v[178:181], v[96:99]
	s_waitcnt lgkmcnt(1)
	v_mfma_f32_16x16x32_bf16 v[84:87], v[142:145], v[186:189], v[84:87]
	v_mfma_f32_16x16x32_bf16 v[80:83], v[150:153], v[186:189], v[80:83]
	v_mfma_f32_16x16x32_bf16 v[124:127], v[146:149], v[162:165], v[124:127]
	v_mfma_f32_16x16x32_bf16 v[120:123], v[154:157], v[162:165], v[120:123]
	v_mfma_f32_16x16x32_bf16 v[116:119], v[146:149], v[170:173], v[116:119]
	v_mfma_f32_16x16x32_bf16 v[112:115], v[154:157], v[170:173], v[112:115]
	v_mfma_f32_16x16x32_bf16 v[100:103], v[146:149], v[182:185], v[100:103]
	v_mfma_f32_16x16x32_bf16 v[96:99], v[154:157], v[182:185], v[96:99]
	s_waitcnt lgkmcnt(0)
	v_mfma_f32_16x16x32_bf16 v[84:87], v[146:149], v[190:193], v[84:87]
	v_mfma_f32_16x16x32_bf16 v[80:83], v[154:157], v[190:193], v[80:83]
	v_add_u32_e32 v206, 0x1c000, v139
	s_barrier
	s_add_i32 m0, s20, 0x18000
	ds_read_b128 v[194:197], v206
	ds_read_b128 v[198:201], v206 offset:1024
	ds_read_b128 v[202:205], v206 offset:2048
	global_load_lds_dwordx4 v176, s[98:99]
	s_add_i32 m0, s20, 0x1a000
	ds_read_b128 v[206:209], v206 offset:3072
	global_load_lds_dwordx4 v128, s[98:99]
	s_barrier
	s_waitcnt lgkmcnt(3)
	v_mfma_f32_16x16x32_bf16 v[108:111], v[194:197], v[158:161], v[108:111]
	s_waitcnt lgkmcnt(1)
	v_mfma_f32_16x16x32_bf16 v[104:107], v[202:205], v[158:161], v[104:107]
	v_mfma_f32_16x16x32_bf16 v[92:95], v[194:197], v[166:169], v[92:95]
	v_mfma_f32_16x16x32_bf16 v[88:91], v[202:205], v[166:169], v[88:91]
	v_mfma_f32_16x16x32_bf16 v[76:79], v[194:197], v[178:181], v[76:79]
	v_mfma_f32_16x16x32_bf16 v[72:75], v[202:205], v[178:181], v[72:75]
	v_mfma_f32_16x16x32_bf16 v[68:71], v[194:197], v[186:189], v[68:71]
	v_mfma_f32_16x16x32_bf16 v[64:67], v[202:205], v[186:189], v[64:67]
	v_mfma_f32_16x16x32_bf16 v[108:111], v[198:201], v[162:165], v[108:111]
	s_waitcnt lgkmcnt(0)
	v_mfma_f32_16x16x32_bf16 v[104:107], v[206:209], v[162:165], v[104:107]
	v_mfma_f32_16x16x32_bf16 v[92:95], v[198:201], v[170:173], v[92:95]
	v_mfma_f32_16x16x32_bf16 v[88:91], v[206:209], v[170:173], v[88:91]
	v_mfma_f32_16x16x32_bf16 v[76:79], v[198:201], v[182:185], v[76:79]
	v_mfma_f32_16x16x32_bf16 v[72:75], v[206:209], v[182:185], v[72:75]
	v_mfma_f32_16x16x32_bf16 v[68:71], v[198:201], v[190:193], v[68:71]
	v_mfma_f32_16x16x32_bf16 v[64:67], v[206:209], v[190:193], v[64:67]
	s_mov_b32 m0, s28
	s_barrier
	ds_read_b128 v[158:161], v141 offset:49152
	ds_read_b128 v[162:165], v141 offset:50176
	ds_read_b128 v[166:169], v141 offset:51200
	ds_read_b128 v[170:173], v141 offset:52224
	ds_read_b128 v[178:181], v141 offset:53248
	ds_read_b128 v[182:185], v141 offset:54272
	ds_read_b128 v[186:189], v141 offset:55296
	global_load_lds_dwordx4 v132, s[100:101]
	s_mov_b32 m0, s29
	ds_read_b128 v[190:193], v141 offset:56320
	global_load_lds_dwordx4 v130, s[100:101]
	s_barrier
	s_waitcnt lgkmcnt(7)
	v_mfma_f32_16x16x32_bf16 v[60:63], v[142:145], v[158:161], v[60:63]
	v_mfma_f32_16x16x32_bf16 v[56:59], v[150:153], v[158:161], v[56:59]
	s_waitcnt lgkmcnt(5)
	v_mfma_f32_16x16x32_bf16 v[52:55], v[142:145], v[166:169], v[52:55]
	v_mfma_f32_16x16x32_bf16 v[48:51], v[150:153], v[166:169], v[48:51]
	s_waitcnt lgkmcnt(3)
	v_mfma_f32_16x16x32_bf16 v[36:39], v[142:145], v[178:181], v[36:39]
	v_mfma_f32_16x16x32_bf16 v[32:35], v[150:153], v[178:181], v[32:35]
	s_waitcnt lgkmcnt(1)
	v_mfma_f32_16x16x32_bf16 v[20:23], v[142:145], v[186:189], v[20:23]
	v_mfma_f32_16x16x32_bf16 v[16:19], v[150:153], v[186:189], v[16:19]
	v_mfma_f32_16x16x32_bf16 v[60:63], v[146:149], v[162:165], v[60:63]
	v_mfma_f32_16x16x32_bf16 v[56:59], v[154:157], v[162:165], v[56:59]
	v_mfma_f32_16x16x32_bf16 v[52:55], v[146:149], v[170:173], v[52:55]
	v_mfma_f32_16x16x32_bf16 v[48:51], v[154:157], v[170:173], v[48:51]
	v_mfma_f32_16x16x32_bf16 v[36:39], v[146:149], v[182:185], v[36:39]
	v_mfma_f32_16x16x32_bf16 v[32:35], v[154:157], v[182:185], v[32:35]
	s_waitcnt lgkmcnt(0)
	v_mfma_f32_16x16x32_bf16 v[20:23], v[146:149], v[190:193], v[20:23]
	v_mfma_f32_16x16x32_bf16 v[16:19], v[154:157], v[190:193], v[16:19]
	s_barrier
	s_add_u32 s14, s14, 0x40080
	s_addc_u32 s15, s15, 0
	s_add_i32 m0, s20, 0x1c000
	s_nop 0
	global_load_lds_dwordx4 v176, s[14:15]
	s_add_i32 m0, s20, 0x1e000
	s_nop 0
	global_load_lds_dwordx4 v128, s[14:15]
	s_waitcnt vmcnt(6)
	s_barrier
	v_mfma_f32_16x16x32_bf16 v[44:47], v[194:197], v[158:161], v[44:47]
	v_mfma_f32_16x16x32_bf16 v[40:43], v[202:205], v[158:161], v[40:43]
	v_mfma_f32_16x16x32_bf16 v[28:31], v[194:197], v[166:169], v[28:31]
	v_mfma_f32_16x16x32_bf16 v[24:27], v[202:205], v[166:169], v[24:27]
	v_mfma_f32_16x16x32_bf16 v[12:15], v[194:197], v[178:181], v[12:15]
	v_mfma_f32_16x16x32_bf16 v[8:11], v[202:205], v[178:181], v[8:11]
	v_mfma_f32_16x16x32_bf16 v[4:7], v[194:197], v[186:189], v[4:7]
	v_mfma_f32_16x16x32_bf16 v[0:3], v[202:205], v[186:189], v[0:3]
	v_mfma_f32_16x16x32_bf16 v[44:47], v[198:201], v[162:165], v[44:47]
	v_mfma_f32_16x16x32_bf16 v[40:43], v[206:209], v[162:165], v[40:43]
	v_mfma_f32_16x16x32_bf16 v[28:31], v[198:201], v[170:173], v[28:31]
	v_mfma_f32_16x16x32_bf16 v[24:27], v[206:209], v[170:173], v[24:27]
	v_mfma_f32_16x16x32_bf16 v[12:15], v[198:201], v[182:185], v[12:15]
	v_mfma_f32_16x16x32_bf16 v[8:11], v[206:209], v[182:185], v[8:11]
	v_mfma_f32_16x16x32_bf16 v[4:7], v[198:201], v[190:193], v[4:7]
	v_mfma_f32_16x16x32_bf16 v[0:3], v[206:209], v[190:193], v[0:3]
	s_add_i32 s45, s45, 2
	s_add_u32 s12, s12, 0x100
	s_addc_u32 s13, s13, 0
	s_add_u32 s43, s43, 0x100
	s_addc_u32 s44, s44, 0
	s_cmp_gt_u32 s45, 13
	v_add_u32_e32 v154, 0x10000, v139
	s_barrier
; __device__ __forceinline__ unsigned cvtpk(float lo, float hi) { const f32x2 v = (f32x2){lo, hi}; const bf16v2 b = __builtin_convertvector(v, bf16v2); return __builtin_bit_cast(unsigned, b); }
; #define PG8_WAIT_V(n) asm volatile("s_waitcnt vmcnt(" #n ")" ::: "memory")
; #define PG8_BAR __builtin_amdgcn_s_barrier()
; template <class Epi, class Sched>
; __device__ __forceinline__ void gemm_phase(PG8_LAS unsigned char* lds, const Gemm g, const Sched& S, const Epi& E) {
;     ...
;         if constexpr (!Epi::AFTER_DRAIN) { E(acc, cur, wr, wc, fr, fq); S.done(cur); }
;         if (!has_next) break;
; #pragma unroll
;         for (int a = 0; a < 2; ++a)
; #pragma unroll
;             for (int b = 0; b < 2; ++b)
; #pragma unroll
;                 for (int m = 0; m < 4; ++m)
; #pragma unroll
;                     for (int n = 0; n < 2; ++n) acc[a][b][m][n] = (f32x4){0.f, 0.f, 0.f, 0.f};
;         cur = nxt; cA = nA; cB = nB; ++ui;
;     }
;     PG8_WAIT_V(0);
;     if (wr == 0) PG8_BAR;
;     PG8_BAR;
;     __device__ __forceinline__ void operator()(const f32x4 (&acc)[2][2][4][2], const pg8::Unit& u, int wr, int wc, int fr, int fq) const {
;         const int row0 = u.pm * 256 + wr * 64 + fr, col0 = u.pn * 256 + wc * 32 + 8 * fq;
; #pragma unroll
;         for (int ai = 0; ai < 2; ++ai)
; #pragma unroll
;             for (int m = 0; m < 4; ++m) { bf16_t* rowp = O + (size_t)(row0 + ai * 128 + m * 16) * ldc + col0;
; #pragma unroll
;                 for (int bj = 0; bj < 2; ++bj) { const f32x4 v0 = acc[ai][bj][m][0], v1 = acc[ai][bj][m][1];
;                     u32x4 w; w.x = cvtpk(v0[0], v0[1]); w.y = cvtpk(v0[2], v0[3]); w.z = cvtpk(v1[0], v1[1]); w.w = cvtpk(v1[2], v1[3]);
;                     *(u32x4*)(rowp + bj * 128) = w; } }
;     }
	s_cbranch_scc0 .LBB0_137
	v_lshl_add_u32 v142, s0, 8, v138
	v_lshl_or_b32 v144, s34, 8, v140
	v_ashrrev_i32_e32 v143, 31, v142
	v_readlane_b32 s12, v253, 18
	v_ashrrev_i32_e32 v145, 31, v144
	v_lshlrev_b64 v[146:147], 11, v[142:143]
	v_readlane_b32 s13, v253, 19
	v_cvt_pk_bf16_f32 v108, v108, v109
	v_cvt_pk_bf16_f32 v109, v110, v111
	v_cvt_pk_bf16_f32 v110, v104, v105
	v_or_b32_e32 v104, 16, v142
	v_cvt_pk_bf16_f32 v92, v92, v93
	v_cvt_pk_bf16_f32 v93, v94, v95
	v_cvt_pk_bf16_f32 v94, v88, v89
	v_or_b32_e32 v88, 32, v142
	v_cvt_pk_bf16_f32 v76, v76, v77
	v_cvt_pk_bf16_f32 v77, v78, v79
	v_cvt_pk_bf16_f32 v78, v72, v73
	v_or_b32_e32 v72, 48, v142
	v_lshl_add_u64 v[146:147], s[12:13], 0, v[146:147]
	v_lshlrev_b64 v[144:145], 1, v[144:145]
	v_ashrrev_i32_e32 v105, 31, v104
	v_ashrrev_i32_e32 v89, 31, v88
	v_ashrrev_i32_e32 v73, 31, v72
	v_lshl_add_u64 v[146:147], v[146:147], 0, v[144:145]
	v_lshlrev_b64 v[104:105], 11, v[104:105]
	v_lshlrev_b64 v[88:89], 11, v[88:89]
	v_lshlrev_b64 v[72:73], 11, v[72:73]
	v_lshl_add_u64 v[104:105], s[12:13], 0, v[104:105]
	v_lshl_add_u64 v[88:89], s[12:13], 0, v[88:89]
	v_lshl_add_u64 v[72:73], s[12:13], 0, v[72:73]
	s_mov_b64 s[12:13], 0x40000
	v_cvt_pk_bf16_f32 v60, v60, v61
	v_cvt_pk_bf16_f32 v61, v62, v63
	v_cvt_pk_bf16_f32 v62, v56, v57
	v_add_co_u32_e32 v56, vcc, s2, v146
	v_cvt_pk_bf16_f32 v68, v68, v69
	v_cvt_pk_bf16_f32 v69, v70, v71
	v_cvt_pk_bf16_f32 v70, v64, v65
	v_lshl_add_u64 v[64:65], v[146:147], 0, s[12:13]
	v_addc_co_u32_e32 v57, vcc, 0, v147, vcc
	v_cvt_pk_bf16_f32 v44, v44, v45
	v_cvt_pk_bf16_f32 v45, v46, v47
	v_cvt_pk_bf16_f32 v46, v40, v41
	v_cvt_pk_bf16_f32 v47, v42, v43
	s_mov_b32 s0, 0x48000
	global_store_dwordx4 v[64:65], v[44:47], off offset:256
	s_mov_b64 s[12:13], 0x48000
	v_cvt_pk_bf16_f32 v28, v28, v29
	v_add_co_u32_e32 v46, vcc, s0, v146
	v_lshl_add_u64 v[44:45], v[146:147], 0, s[12:13]
	s_nop 0
	v_addc_co_u32_e32 v47, vcc, 0, v147, vcc
	v_cvt_pk_bf16_f32 v29, v30, v31
	v_cvt_pk_bf16_f32 v30, v24, v25
	v_cvt_pk_bf16_f32 v31, v26, v27
	s_mov_b32 s0, 0x50000
	global_store_dwordx4 v[44:45], v[28:31], off offset:256
	s_mov_b64 s[12:13], 0x50000
	v_cvt_pk_bf16_f32 v111, v106, v107
	v_add_co_u32_e32 v30, vcc, s0, v146
	v_lshl_add_u64 v[28:29], v[146:147], 0, s[12:13]
	s_nop 0
	v_addc_co_u32_e32 v31, vcc, 0, v147, vcc
	v_cvt_pk_bf16_f32 v12, v12, v13
	v_cvt_pk_bf16_f32 v13, v14, v15
	v_cvt_pk_bf16_f32 v14, v8, v9
	v_cvt_pk_bf16_f32 v15, v10, v11
	s_mov_b32 s0, 0x58000
	global_store_dwordx4 v[146:147], v[108:111], off offset:256
	v_cvt_pk_bf16_f32 v95, v90, v91
	global_store_dwordx4 v[28:29], v[12:15], off offset:256
	v_lshl_add_u64 v[108:109], v[104:105], 0, v[144:145]
	global_store_dwordx4 v[108:109], v[92:95], off offset:256
	v_add_co_u32_e32 v14, vcc, s0, v146
	s_nop 0
	v_lshl_add_u64 v[92:93], v[88:89], 0, v[144:145]
	v_cvt_pk_bf16_f32 v79, v74, v75
	s_mov_b64 s[12:13], 0x58000
	v_addc_co_u32_e32 v15, vcc, 0, v147, vcc
	v_cvt_pk_bf16_f32 v124, v124, v125
	v_cvt_pk_bf16_f32 v125, v126, v127
	v_cvt_pk_bf16_f32 v126, v120, v121
	v_cvt_pk_bf16_f32 v127, v122, v123
	v_cvt_pk_bf16_f32 v104, v116, v117
	v_cvt_pk_bf16_f32 v105, v118, v119
	v_cvt_pk_bf16_f32 v106, v112, v113
	v_cvt_pk_bf16_f32 v107, v114, v115
	v_cvt_pk_bf16_f32 v88, v100, v101
	v_cvt_pk_bf16_f32 v89, v102, v103
	v_cvt_pk_bf16_f32 v90, v96, v97
	v_cvt_pk_bf16_f32 v91, v98, v99
	global_store_dwordx4 v[92:93], v[76:79], off offset:256
	v_cvt_pk_bf16_f32 v74, v80, v81
	v_cvt_pk_bf16_f32 v75, v82, v83
	v_lshl_add_u64 v[76:77], v[72:73], 0, v[144:145]
	v_cvt_pk_bf16_f32 v72, v84, v85
	v_cvt_pk_bf16_f32 v73, v86, v87
	v_cvt_pk_bf16_f32 v71, v66, v67
	v_cvt_pk_bf16_f32 v63, v58, v59
	v_cvt_pk_bf16_f32 v40, v52, v53
	v_cvt_pk_bf16_f32 v41, v54, v55
	v_cvt_pk_bf16_f32 v42, v48, v49
	v_cvt_pk_bf16_f32 v43, v50, v51
	v_cvt_pk_bf16_f32 v24, v36, v37
	v_cvt_pk_bf16_f32 v25, v38, v39
	v_cvt_pk_bf16_f32 v26, v32, v33
	v_cvt_pk_bf16_f32 v27, v34, v35
	v_lshl_add_u64 v[12:13], v[146:147], 0, s[12:13]
	v_cvt_pk_bf16_f32 v8, v20, v21
	v_cvt_pk_bf16_f32 v9, v22, v23
	v_cvt_pk_bf16_f32 v10, v16, v17
	v_cvt_pk_bf16_f32 v11, v18, v19
	v_cvt_pk_bf16_f32 v4, v4, v5
	v_cvt_pk_bf16_f32 v5, v6, v7
	v_cvt_pk_bf16_f32 v6, v0, v1
	v_cvt_pk_bf16_f32 v7, v2, v3
	s_and_b64 vcc, exec, s[38:39]
	s_mov_b32 s34, s4
	s_mov_b32 s0, s6
	s_mov_b64 s[14:15], s[10:11]
	s_mov_b64 s[12:13], s[8:9]
	global_store_dwordx4 v[146:147], v[124:127], off
	global_store_dwordx4 v[108:109], v[104:107], off
	global_store_dwordx4 v[92:93], v[88:91], off
	global_store_dwordx4 v[76:77], v[72:75], off
	global_store_dwordx4 v[76:77], v[68:71], off offset:256
	global_store_dwordx4 v[56:57], v[60:63], off
	global_store_dwordx4 v[46:47], v[40:43], off
	global_store_dwordx4 v[30:31], v[24:27], off
	global_store_dwordx4 v[14:15], v[8:11], off
	global_store_dwordx4 v[12:13], v[4:7], off offset:256
	s_cbranch_vccz .LBB0_134
	s_waitcnt vmcnt(0)
	v_readlane_b32 s22, v255, 14
	s_cmpk_gt_u32 s19, 0xff
	v_readlane_b32 s23, v255, 15
	s_mov_b64 s[28:29], s[54:55]
	s_cbranch_scc1 .LBB0_141
	s_barrier

; #define PG8_STAGE(bufoff, gbase, voff) do { _Pragma("unroll") for (int _i = 0; _i < 2; ++_i) \
;         __builtin_amdgcn_global_load_lds((const unsigned*)((const char*)(gbase) + (voff)[_i]), (PG8_LAS unsigned*)(lds + (bufoff) + ldsw + _i * 8192), 16, 0, 0); } while (0)
; #define PG8_LDA(dst, b, h) do { _Pragma("unroll") for (int m = 0; m < 4; ++m) _Pragma("unroll") for (int k = 0; k < 2; ++k) dst[m][k] = *(const PG8_LAS bf16x8*)(lds + PG8_SA(b, h) + aoff + m * 2048 + k * 1024); } while (0)
; #define PG8_LDB(dst, b, h) do { _Pragma("unroll") for (int n = 0; n < 2; ++n) _Pragma("unroll") for (int k = 0; k < 2; ++k) dst[n][k] = *(const PG8_LAS bf16x8*)(lds + PG8_SB(b, h) + boff + n * 2048 + k * 1024); } while (0)
; #define PG8_WAIT_L(n) asm volatile("s_waitcnt lgkmcnt(" #n ")" ::: "memory")
; #define PG8_BAR __builtin_amdgcn_s_barrier()
; #define PG8_SCHED __builtin_amdgcn_sched_barrier(0)
; template <class Epi, class Sched>
; __device__ __forceinline__ void gemm_phase(PG8_LAS unsigned char* lds, const Gemm g, const Sched& S, const Epi& E) {
;     ...
;         const bool has_next = S.next(ui + 1, nxt);
;         const char* nA = has_next ? (const char*)g.A + (size_t)nxt.pm * tstep : cA; const char* nB = has_next ? (const char*)g.Bt + (size_t)nxt.pn * tstep : cB;
;         for (int t = 0; t < nt; t += 2) {
;             const bool last = (t == nt - 2);
;             const char* a1 = cA + (size_t)(t + 1) * kstep;
;             const char* a2 = last ? nA : cA + (size_t)(t + 2) * kstep; const char* b2 = last ? nB : cB + (size_t)(t + 2) * kstep;
;             const char* a3 = a2 + kstep; const char* b3 = b2 + kstep;
;             if (last && has_next) S.a_ready(nxt);
;             PG8_LDB(B0, 0, 0); PG8_SCHED; PG8_LDA(At, 0, 0); PG8_STAGE(PG8_SA(1, 1), a1 + hstep, voffA);
;             PG8_WAIT_L(8); PG8_BAR; PG8_WAIT_L(0); PG8_MMA(0, 0, At, B0); PG8_BAR; PG8_SCHED;
;     ...
; #pragma unroll
;         for (int a = 0; a < 2; ++a)
; #pragma unroll
;             for (int b = 0; b < 2; ++b)
; #pragma unroll
;                 for (int m = 0; m < 4; ++m)
; #pragma unroll
;                     for (int n = 0; n < 2; ++n) acc[a][b][m][n] = (f32x4){0.f, 0.f, 0.f, 0.f};
;         cur = nxt; cA = nA; cB = nB; ++ui;
.LBB0_357:
	v_mov_b64_e32 v[0:1], 0x2c0
	s_ashr_i32 s7, s6, 31
	v_cmp_lt_i64_e32 vcc, s[8:9], v[0:1]
	s_lshl_b64 s[8:9], s[6:7], 19
	s_add_u32 s8, s94, s8
	s_addc_u32 s9, s95, s9
	s_and_b64 s[10:11], vcc, exec
	s_cselect_b32 s7, s9, s13
	s_cselect_b32 s40, s8, s12
	s_ashr_i32 s5, s4, 31
	s_lshl_b64 s[10:11], s[4:5], 19
	s_add_u32 s10, s92, s10
	s_addc_u32 s11, s93, s11
	s_and_b64 s[16:17], vcc, exec
	s_cselect_b32 s5, s11, s15
	s_cselect_b32 s41, s10, s14
	s_add_u32 s12, s12, 0x40080
	s_addc_u32 s13, s13, 0
	s_add_u32 s43, s14, 0x100
	v_mov_b32_e32 v0, 0
	s_addc_u32 s44, s15, 0
	s_mov_b32 s45, -2
	v_mov_b32_e32 v1, v0
	v_mov_b32_e32 v2, v0
	v_mov_b32_e32 v3, v0
	v_mov_b32_e32 v4, v0
	v_mov_b32_e32 v5, v0
	v_mov_b32_e32 v6, v0
	v_mov_b32_e32 v7, v0
	v_mov_b32_e32 v8, v0
	v_mov_b32_e32 v9, v0
	v_mov_b32_e32 v10, v0
	v_mov_b32_e32 v11, v0
	v_mov_b32_e32 v12, v0
	v_mov_b32_e32 v13, v0
	v_mov_b32_e32 v14, v0
	v_mov_b32_e32 v15, v0
	v_mov_b32_e32 v24, v0
	v_mov_b32_e32 v25, v0
	v_mov_b32_e32 v26, v0
	v_mov_b32_e32 v27, v0
	v_mov_b32_e32 v28, v0
	v_mov_b32_e32 v29, v0
	v_mov_b32_e32 v30, v0
	v_mov_b32_e32 v31, v0
	v_mov_b32_e32 v40, v0
	v_mov_b32_e32 v41, v0
	v_mov_b32_e32 v42, v0
	v_mov_b32_e32 v43, v0
	v_mov_b32_e32 v44, v0
	v_mov_b32_e32 v45, v0
	v_mov_b32_e32 v46, v0
	v_mov_b32_e32 v47, v0
	v_mov_b32_e32 v16, v0
	v_mov_b32_e32 v17, v0
	v_mov_b32_e32 v18, v0
	v_mov_b32_e32 v19, v0
	v_mov_b32_e32 v20, v0
	v_mov_b32_e32 v21, v0
	v_mov_b32_e32 v22, v0
	v_mov_b32_e32 v23, v0
	v_mov_b32_e32 v32, v0
	v_mov_b32_e32 v33, v0
	v_mov_b32_e32 v34, v0
	v_mov_b32_e32 v35, v0
	v_mov_b32_e32 v36, v0
	v_mov_b32_e32 v37, v0
	v_mov_b32_e32 v38, v0
	v_mov_b32_e32 v39, v0
	v_mov_b32_e32 v48, v0
	v_mov_b32_e32 v49, v0
	v_mov_b32_e32 v50, v0
	v_mov_b32_e32 v51, v0
	v_mov_b32_e32 v52, v0
	v_mov_b32_e32 v53, v0
	v_mov_b32_e32 v54, v0
	v_mov_b32_e32 v55, v0
	v_mov_b32_e32 v56, v0
	v_mov_b32_e32 v57, v0
	v_mov_b32_e32 v58, v0
	v_mov_b32_e32 v59, v0
	v_mov_b32_e32 v60, v0
	v_mov_b32_e32 v61, v0
	v_mov_b32_e32 v62, v0
	v_mov_b32_e32 v63, v0
	v_mov_b32_e32 v64, v0
	v_mov_b32_e32 v65, v0
	v_mov_b32_e32 v66, v0
	v_mov_b32_e32 v67, v0
	v_mov_b32_e32 v68, v0
	v_mov_b32_e32 v69, v0
	v_mov_b32_e32 v70, v0
	v_mov_b32_e32 v71, v0
	v_mov_b32_e32 v72, v0
	v_mov_b32_e32 v73, v0
	v_mov_b32_e32 v74, v0
	v_mov_b32_e32 v75, v0
	v_mov_b32_e32 v76, v0
	v_mov_b32_e32 v77, v0
	v_mov_b32_e32 v78, v0
	v_mov_b32_e32 v79, v0
	v_mov_b32_e32 v88, v0
	v_mov_b32_e32 v89, v0
	v_mov_b32_e32 v90, v0
	v_mov_b32_e32 v91, v0
	v_mov_b32_e32 v92, v0
	v_mov_b32_e32 v93, v0
	v_mov_b32_e32 v94, v0
	v_mov_b32_e32 v95, v0
	v_mov_b32_e32 v104, v0
	v_mov_b32_e32 v105, v0
	v_mov_b32_e32 v106, v0
	v_mov_b32_e32 v107, v0
	v_mov_b32_e32 v108, v0
	v_mov_b32_e32 v109, v0
	v_mov_b32_e32 v110, v0
	v_mov_b32_e32 v111, v0
	v_mov_b32_e32 v80, v0
	v_mov_b32_e32 v81, v0
	v_mov_b32_e32 v82, v0
	v_mov_b32_e32 v83, v0
	v_mov_b32_e32 v84, v0
	v_mov_b32_e32 v85, v0
	v_mov_b32_e32 v86, v0
	v_mov_b32_e32 v87, v0
	v_mov_b32_e32 v96, v0
	v_mov_b32_e32 v97, v0
	v_mov_b32_e32 v98, v0
	v_mov_b32_e32 v99, v0
	v_mov_b32_e32 v100, v0
	v_mov_b32_e32 v101, v0
	v_mov_b32_e32 v102, v0
	v_mov_b32_e32 v103, v0
	v_mov_b32_e32 v112, v0
	v_mov_b32_e32 v113, v0
	v_mov_b32_e32 v114, v0
	v_mov_b32_e32 v115, v0
	v_mov_b32_e32 v116, v0
	v_mov_b32_e32 v117, v0
	v_mov_b32_e32 v118, v0
	v_mov_b32_e32 v119, v0
	v_mov_b32_e32 v120, v0
	v_mov_b32_e32 v121, v0
	v_mov_b32_e32 v122, v0
	v_mov_b32_e32 v123, v0
	v_mov_b32_e32 v124, v0
	v_mov_b32_e32 v125, v0
	v_mov_b32_e32 v126, v0
	v_mov_b32_e32 v127, v0
	v_add_u32_e32 v154, 0x10000, v139
	v_add_u32_e32 v174, 0x14000, v139
.LBB0_358:
	ds_read_b128 v[142:145], v154
	ds_read_b128 v[146:149], v154 offset:1024
	ds_read_b128 v[150:153], v154 offset:2048
	ds_read_b128 v[154:157], v154 offset:3072
	s_add_u32 s14, s12, 0xfffc0080
	s_addc_u32 s15, s13, -1
	s_cmp_eq_u32 s45, 12
	s_cselect_b32 s17, s7, s15
	s_cselect_b32 s16, s40, s14
	s_cselect_b32 s15, s5, s44
	s_cselect_b32 s14, s41, s43
	s_add_i32 m0, s1, 0xc000
	ds_read_b128 v[158:161], v141
	ds_read_b128 v[162:165], v141 offset:1024
	ds_read_b128 v[166:169], v141 offset:2048
	ds_read_b128 v[170:173], v141 offset:3072
	ds_read_b128 v[182:185], v141 offset:4096
	ds_read_b128 v[190:193], v141 offset:5120
	ds_read_b128 v[194:197], v141 offset:6144
	global_load_lds_dwordx4 v134, s[12:13]
	s_add_i32 m0, s1, 0xe000
	ds_read_b128 v[198:201], v141 offset:7168
	global_load_lds_dwordx4 v136, s[12:13]
	s_waitcnt lgkmcnt(8)
	s_barrier
	s_waitcnt lgkmcnt(7)
	v_mfma_f32_16x16x32_bf16 v[124:127], v[142:145], v[158:161], v[124:127]
	v_mfma_f32_16x16x32_bf16 v[120:123], v[150:153], v[158:161], v[120:123]
	s_waitcnt lgkmcnt(5)
	v_mfma_f32_16x16x32_bf16 v[116:119], v[142:145], v[166:169], v[116:119]
	v_mfma_f32_16x16x32_bf16 v[112:115], v[150:153], v[166:169], v[112:115]
	s_waitcnt lgkmcnt(3)
	v_mfma_f32_16x16x32_bf16 v[100:103], v[142:145], v[182:185], v[100:103]
	v_mfma_f32_16x16x32_bf16 v[96:99], v[150:153], v[182:185], v[96:99]
	s_waitcnt lgkmcnt(1)
	v_mfma_f32_16x16x32_bf16 v[84:87], v[142:145], v[194:197], v[84:87]
	v_mfma_f32_16x16x32_bf16 v[80:83], v[150:153], v[194:197], v[80:83]
	v_mfma_f32_16x16x32_bf16 v[124:127], v[146:149], v[162:165], v[124:127]
	v_mfma_f32_16x16x32_bf16 v[120:123], v[154:157], v[162:165], v[120:123]
	v_mfma_f32_16x16x32_bf16 v[116:119], v[146:149], v[170:173], v[116:119]
	v_mfma_f32_16x16x32_bf16 v[112:115], v[154:157], v[170:173], v[112:115]
	v_mfma_f32_16x16x32_bf16 v[100:103], v[146:149], v[190:193], v[100:103]
	v_mfma_f32_16x16x32_bf16 v[96:99], v[154:157], v[190:193], v[96:99]
	s_waitcnt lgkmcnt(0)
	v_mfma_f32_16x16x32_bf16 v[84:87], v[146:149], v[198:201], v[84:87]
	v_mfma_f32_16x16x32_bf16 v[80:83], v[154:157], v[198:201], v[80:83]
	s_barrier
; #define PG8_STAGE(bufoff, gbase, voff) do { _Pragma("unroll") for (int _i = 0; _i < 2; ++_i) \
;         __builtin_amdgcn_global_load_lds((const unsigned*)((const char*)(gbase) + (voff)[_i]), (PG8_LAS unsigned*)(lds + (bufoff) + ldsw + _i * 8192), 16, 0, 0); } while (0)
; #define PG8_LDA(dst, b, h) do { _Pragma("unroll") for (int m = 0; m < 4; ++m) _Pragma("unroll") for (int k = 0; k < 2; ++k) dst[m][k] = *(const PG8_LAS bf16x8*)(lds + PG8_SA(b, h) + aoff + m * 2048 + k * 1024); } while (0)
; #define PG8_LDB(dst, b, h) do { _Pragma("unroll") for (int n = 0; n < 2; ++n) _Pragma("unroll") for (int k = 0; k < 2; ++k) dst[n][k] = *(const PG8_LAS bf16x8*)(lds + PG8_SB(b, h) + boff + n * 2048 + k * 1024); } while (0)
; #define PG8_MMA(ai, bj, At, Bt) do { __builtin_amdgcn_s_setprio(1); _Pragma("unroll") for (int m = 0; m < 4; ++m) _Pragma("unroll") for (int n = 0; n < 2; ++n) _Pragma("unroll") for (int k = 0; k < 2; ++k) \
;         acc[ai][bj][m][n] = __builtin_amdgcn_mfma_f32_16x16x32_bf16(Bt[n][k], At[m][k], acc[ai][bj][m][n], 0, 0, 0); __builtin_amdgcn_s_setprio(0); } while (0)
; #define PG8_WAIT_V(n) asm volatile("s_waitcnt vmcnt(" #n ")" ::: "memory")
; #define PG8_WAIT_L(n) asm volatile("s_waitcnt lgkmcnt(" #n ")" ::: "memory")
; #define PG8_BAR __builtin_amdgcn_s_barrier()
; #define PG8_SCHED __builtin_amdgcn_sched_barrier(0)
; template <class Epi, class Sched>
; __device__ __forceinline__ void gemm_phase(PG8_LAS unsigned char* lds, const Gemm g, const Sched& S, const Epi& E) {
;     ...
;             PG8_LDB(B1, 0, 1); PG8_STAGE(PG8_SB(0, 0), b2, voffB);
;             PG8_BAR; PG8_WAIT_L(0); PG8_MMA(0, 1, At, B1); PG8_BAR;
;             PG8_LDA(At, 0, 1); PG8_STAGE(PG8_SA(0, 0), a2, voffA);
;             PG8_BAR; PG8_WAIT_L(0); PG8_MMA(1, 0, At, B0); PG8_BAR; PG8_SCHED;
;             PG8_STAGE(PG8_SB(0, 1), b2 + hstep, voffB);
;             PG8_WAIT_V(6); PG8_BAR; PG8_MMA(1, 1, At, B1); PG8_BAR;
;             PG8_LDB(B0, 1, 0); PG8_SCHED; PG8_LDA(At, 1, 0); PG8_STAGE(PG8_SA(0, 1), a2 + hstep, voffA);
;             PG8_WAIT_L(8); PG8_BAR; PG8_WAIT_L(0); PG8_MMA(0, 0, At, B0); PG8_BAR; PG8_SCHED;
	s_add_i32 s48, 0, 0x14000
	ds_read_b128 v[202:205], v174
	ds_read_b128 v[206:209], v174 offset:1024
	s_add_u32 s98, s14, 0x80
	s_addc_u32 s99, s15, 0
	s_add_i32 m0, s20, 0x10000
	ds_read_b128 v[210:213], v174 offset:2048
	global_load_lds_dwordx4 v176, s[14:15]
	s_add_i32 m0, s20, 0x12000
	ds_read_b128 v[214:217], v174 offset:3072
	global_load_lds_dwordx4 v128, s[14:15]
	s_barrier
	s_waitcnt lgkmcnt(3)
	v_mfma_f32_16x16x32_bf16 v[108:111], v[202:205], v[158:161], v[108:111]
	s_waitcnt lgkmcnt(1)
	v_mfma_f32_16x16x32_bf16 v[104:107], v[210:213], v[158:161], v[104:107]
	v_mfma_f32_16x16x32_bf16 v[92:95], v[202:205], v[166:169], v[92:95]
	v_mfma_f32_16x16x32_bf16 v[88:91], v[210:213], v[166:169], v[88:91]
	v_mfma_f32_16x16x32_bf16 v[76:79], v[202:205], v[182:185], v[76:79]
	v_mfma_f32_16x16x32_bf16 v[72:75], v[210:213], v[182:185], v[72:75]
	v_mfma_f32_16x16x32_bf16 v[68:71], v[202:205], v[194:197], v[68:71]
	v_mfma_f32_16x16x32_bf16 v[64:67], v[210:213], v[194:197], v[64:67]
	v_mfma_f32_16x16x32_bf16 v[108:111], v[206:209], v[162:165], v[108:111]
	s_waitcnt lgkmcnt(0)
	v_mfma_f32_16x16x32_bf16 v[104:107], v[214:217], v[162:165], v[104:107]
	v_mfma_f32_16x16x32_bf16 v[92:95], v[206:209], v[170:173], v[92:95]
	v_mfma_f32_16x16x32_bf16 v[88:91], v[214:217], v[170:173], v[88:91]
	v_mfma_f32_16x16x32_bf16 v[76:79], v[206:209], v[190:193], v[76:79]
	v_mfma_f32_16x16x32_bf16 v[72:75], v[214:217], v[190:193], v[72:75]
	v_mfma_f32_16x16x32_bf16 v[68:71], v[206:209], v[198:201], v[68:71]
	v_mfma_f32_16x16x32_bf16 v[64:67], v[214:217], v[198:201], v[64:67]
	s_mov_b32 m0, s1
	s_add_u32 s100, s16, 0x80
	s_addc_u32 s101, s17, 0
	s_barrier
	ds_read_b128 v[158:161], v141 offset:16384
	ds_read_b128 v[162:165], v141 offset:17408
	ds_read_b128 v[166:169], v141 offset:18432
	ds_read_b128 v[170:173], v141 offset:19456
	ds_read_b128 v[182:185], v141 offset:20480
	ds_read_b128 v[190:193], v141 offset:21504
	ds_read_b128 v[194:197], v141 offset:22528
	global_load_lds_dwordx4 v132, s[16:17]
	s_mov_b32 m0, s22
	ds_read_b128 v[198:201], v141 offset:23552
	global_load_lds_dwordx4 v130, s[16:17]
	s_barrier
	s_waitcnt lgkmcnt(7)
	v_mfma_f32_16x16x32_bf16 v[60:63], v[142:145], v[158:161], v[60:63]
	v_mfma_f32_16x16x32_bf16 v[56:59], v[150:153], v[158:161], v[56:59]
	s_waitcnt lgkmcnt(5)
	v_mfma_f32_16x16x32_bf16 v[52:55], v[142:145], v[166:169], v[52:55]
	v_mfma_f32_16x16x32_bf16 v[48:51], v[150:153], v[166:169], v[48:51]
	s_waitcnt lgkmcnt(3)
	v_mfma_f32_16x16x32_bf16 v[36:39], v[142:145], v[182:185], v[36:39]
	v_mfma_f32_16x16x32_bf16 v[32:35], v[150:153], v[182:185], v[32:35]
	s_waitcnt lgkmcnt(1)
	v_mfma_f32_16x16x32_bf16 v[20:23], v[142:145], v[194:197], v[20:23]
	v_mfma_f32_16x16x32_bf16 v[16:19], v[150:153], v[194:197], v[16:19]
	v_mfma_f32_16x16x32_bf16 v[60:63], v[146:149], v[162:165], v[60:63]
	v_mfma_f32_16x16x32_bf16 v[56:59], v[154:157], v[162:165], v[56:59]
	v_mfma_f32_16x16x32_bf16 v[52:55], v[146:149], v[170:173], v[52:55]
	v_mfma_f32_16x16x32_bf16 v[48:51], v[154:157], v[170:173], v[48:51]
	v_mfma_f32_16x16x32_bf16 v[36:39], v[146:149], v[190:193], v[36:39]
	v_mfma_f32_16x16x32_bf16 v[32:35], v[154:157], v[190:193], v[32:35]
	s_waitcnt lgkmcnt(0)
	v_mfma_f32_16x16x32_bf16 v[20:23], v[146:149], v[198:201], v[20:23]
	v_mfma_f32_16x16x32_bf16 v[16:19], v[154:157], v[198:201], v[16:19]
	s_barrier
	s_add_u32 s46, s14, 0x40000
	s_addc_u32 s47, s15, 0
	s_add_i32 m0, s20, 0x14000
	s_nop 0
	global_load_lds_dwordx4 v176, s[46:47]
	s_add_i32 m0, s20, 0x16000
	s_nop 0
	global_load_lds_dwordx4 v128, s[46:47]
	s_waitcnt vmcnt(6)
	s_barrier
	v_mfma_f32_16x16x32_bf16 v[44:47], v[202:205], v[158:161], v[44:47]
	v_mfma_f32_16x16x32_bf16 v[40:43], v[210:213], v[158:161], v[40:43]
	v_mfma_f32_16x16x32_bf16 v[28:31], v[202:205], v[166:169], v[28:31]
	v_mfma_f32_16x16x32_bf16 v[24:27], v[210:213], v[166:169], v[24:27]
	v_mfma_f32_16x16x32_bf16 v[12:15], v[202:205], v[182:185], v[12:15]
	v_mfma_f32_16x16x32_bf16 v[8:11], v[210:213], v[182:185], v[8:11]
	v_mfma_f32_16x16x32_bf16 v[4:7], v[202:205], v[194:197], v[4:7]
	v_mfma_f32_16x16x32_bf16 v[0:3], v[210:213], v[194:197], v[0:3]
	v_mfma_f32_16x16x32_bf16 v[44:47], v[206:209], v[162:165], v[44:47]
	v_mfma_f32_16x16x32_bf16 v[40:43], v[214:217], v[162:165], v[40:43]
	v_mfma_f32_16x16x32_bf16 v[28:31], v[206:209], v[170:173], v[28:31]
	v_mfma_f32_16x16x32_bf16 v[24:27], v[214:217], v[170:173], v[24:27]
	v_mfma_f32_16x16x32_bf16 v[12:15], v[206:209], v[190:193], v[12:15]
	v_mfma_f32_16x16x32_bf16 v[8:11], v[214:217], v[190:193], v[8:11]
	v_mfma_f32_16x16x32_bf16 v[4:7], v[206:209], v[198:201], v[4:7]
	v_mfma_f32_16x16x32_bf16 v[0:3], v[214:217], v[198:201], v[0:3]
	v_add_u32_e32 v154, 0x18000, v139
	s_barrier
	ds_read_b128 v[142:145], v154
	ds_read_b128 v[146:149], v154 offset:1024
	ds_read_b128 v[150:153], v154 offset:2048
	ds_read_b128 v[154:157], v154 offset:3072
	s_add_u32 s16, s16, 0x40000
	s_addc_u32 s17, s17, 0
	s_mov_b32 m0, s23
	ds_read_b128 v[158:161], v141 offset:32768
	ds_read_b128 v[162:165], v141 offset:33792
	ds_read_b128 v[166:169], v141 offset:34816
	ds_read_b128 v[170:173], v141 offset:35840
	ds_read_b128 v[182:185], v141 offset:36864
	ds_read_b128 v[190:193], v141 offset:37888
	ds_read_b128 v[194:197], v141 offset:38912
	global_load_lds_dwordx4 v132, s[16:17]
	s_mov_b32 m0, s26
	ds_read_b128 v[198:201], v141 offset:39936
	global_load_lds_dwordx4 v130, s[16:17]
	s_waitcnt lgkmcnt(8)
	s_barrier
; #define PG8_STAGE(bufoff, gbase, voff) do { _Pragma("unroll") for (int _i = 0; _i < 2; ++_i) \
;         __builtin_amdgcn_global_load_lds((const unsigned*)((const char*)(gbase) + (voff)[_i]), (PG8_LAS unsigned*)(lds + (bufoff) + ldsw + _i * 8192), 16, 0, 0); } while (0)
; #define PG8_LDA(dst, b, h) do { _Pragma("unroll") for (int m = 0; m < 4; ++m) _Pragma("unroll") for (int k = 0; k < 2; ++k) dst[m][k] = *(const PG8_LAS bf16x8*)(lds + PG8_SA(b, h) + aoff + m * 2048 + k * 1024); } while (0)
; #define PG8_LDB(dst, b, h) do { _Pragma("unroll") for (int n = 0; n < 2; ++n) _Pragma("unroll") for (int k = 0; k < 2; ++k) dst[n][k] = *(const PG8_LAS bf16x8*)(lds + PG8_SB(b, h) + boff + n * 2048 + k * 1024); } while (0)
; #define PG8_MMA(ai, bj, At, Bt) do { __builtin_amdgcn_s_setprio(1); _Pragma("unroll") for (int m = 0; m < 4; ++m) _Pragma("unroll") for (int n = 0; n < 2; ++n) _Pragma("unroll") for (int k = 0; k < 2; ++k) \
;         acc[ai][bj][m][n] = __builtin_amdgcn_mfma_f32_16x16x32_bf16(Bt[n][k], At[m][k], acc[ai][bj][m][n], 0, 0, 0); __builtin_amdgcn_s_setprio(0); } while (0)
; #define PG8_WAIT_V(n) asm volatile("s_waitcnt vmcnt(" #n ")" ::: "memory")
; #define PG8_WAIT_L(n) asm volatile("s_waitcnt lgkmcnt(" #n ")" ::: "memory")
; #define PG8_BAR __builtin_amdgcn_s_barrier()
; #define PG8_SCHED __builtin_amdgcn_sched_barrier(0)
; template <class Epi, class Sched>
; __device__ __forceinline__ void gemm_phase(PG8_LAS unsigned char* lds, const Gemm g, const Sched& S, const Epi& E) {
;     ...
;             PG8_WAIT_L(8); PG8_BAR; PG8_WAIT_L(0); PG8_MMA(0, 0, At, B0); PG8_BAR; PG8_SCHED;
;             PG8_LDB(B1, 1, 1); PG8_STAGE(PG8_SB(1, 0), b3, voffB);
;             PG8_BAR; PG8_WAIT_L(0); PG8_MMA(0, 1, At, B1); PG8_BAR;
;             PG8_LDA(At, 1, 1); PG8_STAGE(PG8_SA(1, 0), a3, voffA);
;             PG8_BAR; PG8_WAIT_L(0); PG8_MMA(1, 0, At, B0); PG8_BAR; PG8_SCHED;
;             PG8_STAGE(PG8_SB(1, 1), b3 + hstep, voffB);
;             PG8_WAIT_V(6); PG8_BAR; PG8_MMA(1, 1, At, B1); PG8_BAR;
	s_waitcnt lgkmcnt(7)
	v_mfma_f32_16x16x32_bf16 v[124:127], v[142:145], v[158:161], v[124:127]
	v_mfma_f32_16x16x32_bf16 v[120:123], v[150:153], v[158:161], v[120:123]
	s_waitcnt lgkmcnt(5)
	v_mfma_f32_16x16x32_bf16 v[116:119], v[142:145], v[166:169], v[116:119]
	v_mfma_f32_16x16x32_bf16 v[112:115], v[150:153], v[166:169], v[112:115]
	s_waitcnt lgkmcnt(3)
	v_mfma_f32_16x16x32_bf16 v[100:103], v[142:145], v[182:185], v[100:103]
	v_mfma_f32_16x16x32_bf16 v[96:99], v[150:153], v[182:185], v[96:99]
	s_waitcnt lgkmcnt(1)
	v_mfma_f32_16x16x32_bf16 v[84:87], v[142:145], v[194:197], v[84:87]
	v_mfma_f32_16x16x32_bf16 v[80:83], v[150:153], v[194:197], v[80:83]
	v_mfma_f32_16x16x32_bf16 v[124:127], v[146:149], v[162:165], v[124:127]
	v_mfma_f32_16x16x32_bf16 v[120:123], v[154:157], v[162:165], v[120:123]
	v_mfma_f32_16x16x32_bf16 v[116:119], v[146:149], v[170:173], v[116:119]
	v_mfma_f32_16x16x32_bf16 v[112:115], v[154:157], v[170:173], v[112:115]
	v_mfma_f32_16x16x32_bf16 v[100:103], v[146:149], v[190:193], v[100:103]
	v_mfma_f32_16x16x32_bf16 v[96:99], v[154:157], v[190:193], v[96:99]
	s_waitcnt lgkmcnt(0)
	v_mfma_f32_16x16x32_bf16 v[84:87], v[146:149], v[198:201], v[84:87]
	v_mfma_f32_16x16x32_bf16 v[80:83], v[154:157], v[198:201], v[80:83]
	v_add_u32_e32 v188, 0x1c000, v139
	s_barrier
	s_add_i32 m0, s20, 0x18000
	ds_read_b128 v[202:205], v188
	ds_read_b128 v[206:209], v188 offset:1024
	ds_read_b128 v[210:213], v188 offset:2048
	global_load_lds_dwordx4 v176, s[98:99]
	s_add_i32 m0, s20, 0x1a000
	ds_read_b128 v[214:217], v188 offset:3072
	global_load_lds_dwordx4 v128, s[98:99]
	s_barrier
	s_waitcnt lgkmcnt(3)
	v_mfma_f32_16x16x32_bf16 v[108:111], v[202:205], v[158:161], v[108:111]
	s_waitcnt lgkmcnt(1)
	v_mfma_f32_16x16x32_bf16 v[104:107], v[210:213], v[158:161], v[104:107]
	v_mfma_f32_16x16x32_bf16 v[92:95], v[202:205], v[166:169], v[92:95]
	v_mfma_f32_16x16x32_bf16 v[88:91], v[210:213], v[166:169], v[88:91]
	v_mfma_f32_16x16x32_bf16 v[76:79], v[202:205], v[182:185], v[76:79]
	v_mfma_f32_16x16x32_bf16 v[72:75], v[210:213], v[182:185], v[72:75]
	v_mfma_f32_16x16x32_bf16 v[68:71], v[202:205], v[194:197], v[68:71]
	v_mfma_f32_16x16x32_bf16 v[64:67], v[210:213], v[194:197], v[64:67]
	v_mfma_f32_16x16x32_bf16 v[108:111], v[206:209], v[162:165], v[108:111]
	s_waitcnt lgkmcnt(0)
	v_mfma_f32_16x16x32_bf16 v[104:107], v[214:217], v[162:165], v[104:107]
	v_mfma_f32_16x16x32_bf16 v[92:95], v[206:209], v[170:173], v[92:95]
	v_mfma_f32_16x16x32_bf16 v[88:91], v[214:217], v[170:173], v[88:91]
	v_mfma_f32_16x16x32_bf16 v[76:79], v[206:209], v[190:193], v[76:79]
	v_mfma_f32_16x16x32_bf16 v[72:75], v[214:217], v[190:193], v[72:75]
	v_mfma_f32_16x16x32_bf16 v[68:71], v[206:209], v[198:201], v[68:71]
	v_mfma_f32_16x16x32_bf16 v[64:67], v[214:217], v[198:201], v[64:67]
	s_mov_b32 m0, s28
	s_barrier
	ds_read_b128 v[158:161], v141 offset:49152
	ds_read_b128 v[162:165], v141 offset:50176
	ds_read_b128 v[166:169], v141 offset:51200
	ds_read_b128 v[170:173], v141 offset:52224
	ds_read_b128 v[182:185], v141 offset:53248
	ds_read_b128 v[190:193], v141 offset:54272
	ds_read_b128 v[194:197], v141 offset:55296
	global_load_lds_dwordx4 v132, s[100:101]
	s_mov_b32 m0, s29
	ds_read_b128 v[198:201], v141 offset:56320
	global_load_lds_dwordx4 v130, s[100:101]
	s_barrier
	s_waitcnt lgkmcnt(7)
	v_mfma_f32_16x16x32_bf16 v[60:63], v[142:145], v[158:161], v[60:63]
	v_mfma_f32_16x16x32_bf16 v[56:59], v[150:153], v[158:161], v[56:59]
	s_waitcnt lgkmcnt(5)
	v_mfma_f32_16x16x32_bf16 v[52:55], v[142:145], v[166:169], v[52:55]
	v_mfma_f32_16x16x32_bf16 v[48:51], v[150:153], v[166:169], v[48:51]
	s_waitcnt lgkmcnt(3)
	v_mfma_f32_16x16x32_bf16 v[36:39], v[142:145], v[182:185], v[36:39]
	v_mfma_f32_16x16x32_bf16 v[32:35], v[150:153], v[182:185], v[32:35]
	s_waitcnt lgkmcnt(1)
	v_mfma_f32_16x16x32_bf16 v[20:23], v[142:145], v[194:197], v[20:23]
	v_mfma_f32_16x16x32_bf16 v[16:19], v[150:153], v[194:197], v[16:19]
	v_mfma_f32_16x16x32_bf16 v[60:63], v[146:149], v[162:165], v[60:63]
	v_mfma_f32_16x16x32_bf16 v[56:59], v[154:157], v[162:165], v[56:59]
	v_mfma_f32_16x16x32_bf16 v[52:55], v[146:149], v[170:173], v[52:55]
	v_mfma_f32_16x16x32_bf16 v[48:51], v[154:157], v[170:173], v[48:51]
	v_mfma_f32_16x16x32_bf16 v[36:39], v[146:149], v[190:193], v[36:39]
	v_mfma_f32_16x16x32_bf16 v[32:35], v[154:157], v[190:193], v[32:35]
	s_waitcnt lgkmcnt(0)
	v_mfma_f32_16x16x32_bf16 v[20:23], v[146:149], v[198:201], v[20:23]
	v_mfma_f32_16x16x32_bf16 v[16:19], v[154:157], v[198:201], v[16:19]
	s_barrier
	s_add_u32 s14, s14, 0x40080
	s_addc_u32 s15, s15, 0
	s_add_i32 m0, s20, 0x1c000
	s_nop 0
	global_load_lds_dwordx4 v176, s[14:15]
	s_add_i32 m0, s20, 0x1e000
	s_nop 0
	global_load_lds_dwordx4 v128, s[14:15]
	s_waitcnt vmcnt(6)
	s_barrier
; __device__ __forceinline__ unsigned cvtpk(float lo, float hi) { const f32x2 v = (f32x2){lo, hi}; const bf16v2 b = __builtin_convertvector(v, bf16v2); return __builtin_bit_cast(unsigned, b); }
; #define PG8_MMA(ai, bj, At, Bt) do { __builtin_amdgcn_s_setprio(1); _Pragma("unroll") for (int m = 0; m < 4; ++m) _Pragma("unroll") for (int n = 0; n < 2; ++n) _Pragma("unroll") for (int k = 0; k < 2; ++k) \
;         acc[ai][bj][m][n] = __builtin_amdgcn_mfma_f32_16x16x32_bf16(Bt[n][k], At[m][k], acc[ai][bj][m][n], 0, 0, 0); __builtin_amdgcn_s_setprio(0); } while (0)
; #define PG8_WAIT_V(n) asm volatile("s_waitcnt vmcnt(" #n ")" ::: "memory")
; #define PG8_BAR __builtin_amdgcn_s_barrier()
; template <class Epi, class Sched>
; __device__ __forceinline__ void gemm_phase(PG8_LAS unsigned char* lds, const Gemm g, const Sched& S, const Epi& E) {
;     ...
;             PG8_WAIT_V(6); PG8_BAR; PG8_MMA(1, 1, At, B1); PG8_BAR;
;         }
;     __device__ __forceinline__ void operator()(const f32x4 (&acc)[2][2][4][2], const pg8::Unit& u, int wr, int wc, int fr, int fq) const {
;         const int row0 = u.pm * 256 + wr * 64 + fr, col0 = u.pn * 256 + wc * 32 + 8 * fq;
; #pragma unroll
;         for (int ai = 0; ai < 2; ++ai)
; #pragma unroll
;             for (int m = 0; m < 4; ++m) { bf16_t* rowp = O + (size_t)(row0 + ai * 128 + m * 16) * ldc + col0;
; #pragma unroll
;                 for (int bj = 0; bj < 2; ++bj) { const f32x4 v0 = acc[ai][bj][m][0], v1 = acc[ai][bj][m][1];
;                     u32x4 w; w.x = cvtpk(v0[0], v0[1]); w.y = cvtpk(v0[2], v0[3]); w.z = cvtpk(v1[0], v1[1]); w.w = cvtpk(v1[2], v1[3]);
;                     *(u32x4*)(rowp + bj * 128) = w; } }
;     }
	v_mfma_f32_16x16x32_bf16 v[44:47], v[202:205], v[158:161], v[44:47]
	v_mfma_f32_16x16x32_bf16 v[40:43], v[210:213], v[158:161], v[40:43]
	v_mfma_f32_16x16x32_bf16 v[28:31], v[202:205], v[166:169], v[28:31]
	v_mfma_f32_16x16x32_bf16 v[24:27], v[210:213], v[166:169], v[24:27]
	v_mfma_f32_16x16x32_bf16 v[12:15], v[202:205], v[182:185], v[12:15]
	v_mfma_f32_16x16x32_bf16 v[8:11], v[210:213], v[182:185], v[8:11]
	v_mfma_f32_16x16x32_bf16 v[4:7], v[202:205], v[194:197], v[4:7]
	v_mfma_f32_16x16x32_bf16 v[0:3], v[210:213], v[194:197], v[0:3]
	v_mfma_f32_16x16x32_bf16 v[44:47], v[206:209], v[162:165], v[44:47]
	v_mfma_f32_16x16x32_bf16 v[40:43], v[214:217], v[162:165], v[40:43]
	v_mfma_f32_16x16x32_bf16 v[28:31], v[206:209], v[170:173], v[28:31]
	v_mfma_f32_16x16x32_bf16 v[24:27], v[214:217], v[170:173], v[24:27]
	v_mfma_f32_16x16x32_bf16 v[12:15], v[206:209], v[190:193], v[12:15]
	v_mfma_f32_16x16x32_bf16 v[8:11], v[214:217], v[190:193], v[8:11]
	v_mfma_f32_16x16x32_bf16 v[4:7], v[206:209], v[198:201], v[4:7]
	v_mfma_f32_16x16x32_bf16 v[0:3], v[214:217], v[198:201], v[0:3]
	s_add_i32 s45, s45, 2
	s_add_u32 s12, s12, 0x100
	s_addc_u32 s13, s13, 0
	s_add_u32 s43, s43, 0x100
	s_addc_u32 s44, s44, 0
	s_cmp_gt_u32 s45, 13
	v_add_u32_e32 v154, 0x10000, v139
	s_barrier
	s_cbranch_scc0 .LBB0_358
	v_readlane_b32 s12, v253, 16
	v_lshl_add_u32 v148, s0, 8, v138
	v_lshl_or_b32 v142, s34, 8, v140
	v_readlane_b32 s13, v253, 17
	v_ashrrev_i32_e32 v143, 31, v142
	v_cvt_pk_bf16_f32 v68, v68, v69
	v_mov_b64_e32 v[144:145], s[12:13]
	v_cvt_pk_bf16_f32 v69, v70, v71
	v_cvt_pk_bf16_f32 v70, v64, v65
	v_add_u32_e32 v64, 0x80, v148
	v_mad_i64_i32 v[146:147], s[12:13], v148, s81, v[144:145]
	v_lshlrev_b64 v[142:143], 1, v[142:143]
	v_cvt_pk_bf16_f32 v108, v108, v109
	v_cvt_pk_bf16_f32 v109, v110, v111
	v_cvt_pk_bf16_f32 v110, v104, v105
	v_or_b32_e32 v104, 16, v148
	v_mad_i64_i32 v[64:65], s[12:13], v64, s81, v[144:145]
	v_cvt_pk_bf16_f32 v44, v44, v45
	v_cvt_pk_bf16_f32 v45, v46, v47
	v_cvt_pk_bf16_f32 v46, v40, v41
	v_add_u32_e32 v40, 0x90, v148
	v_lshl_add_u64 v[146:147], v[146:147], 0, v[142:143]
	v_cvt_pk_bf16_f32 v111, v106, v107
	v_mad_i64_i32 v[104:105], s[12:13], v104, s81, v[144:145]
	v_cvt_pk_bf16_f32 v92, v92, v93
	v_cvt_pk_bf16_f32 v93, v94, v95
	v_cvt_pk_bf16_f32 v94, v88, v89
	v_or_b32_e32 v88, 32, v148
	v_lshl_add_u64 v[64:65], v[64:65], 0, v[142:143]
	v_cvt_pk_bf16_f32 v47, v42, v43
	v_mad_i64_i32 v[40:41], s[12:13], v40, s81, v[144:145]
	v_cvt_pk_bf16_f32 v28, v28, v29
	v_cvt_pk_bf16_f32 v29, v30, v31
	v_cvt_pk_bf16_f32 v30, v24, v25
	v_add_u32_e32 v24, 0xa0, v148
	global_store_dwordx4 v[146:147], v[108:111], off offset:256
	v_cvt_pk_bf16_f32 v95, v90, v91
	v_mad_i64_i32 v[88:89], s[12:13], v88, s81, v[144:145]
	v_lshl_add_u64 v[108:109], v[104:105], 0, v[142:143]
	v_cvt_pk_bf16_f32 v76, v76, v77
	v_cvt_pk_bf16_f32 v77, v78, v79
	v_cvt_pk_bf16_f32 v78, v72, v73
	v_or_b32_e32 v72, 48, v148
	global_store_dwordx4 v[64:65], v[44:47], off offset:256
	v_cvt_pk_bf16_f32 v31, v26, v27
	v_mad_i64_i32 v[24:25], s[12:13], v24, s81, v[144:145]
	v_lshl_add_u64 v[44:45], v[40:41], 0, v[142:143]
	v_cvt_pk_bf16_f32 v12, v12, v13
	v_cvt_pk_bf16_f32 v13, v14, v15
	v_cvt_pk_bf16_f32 v14, v8, v9
	v_add_u32_e32 v8, 0xb0, v148
	global_store_dwordx4 v[108:109], v[92:95], off offset:256
	v_cvt_pk_bf16_f32 v79, v74, v75
	v_mad_i64_i32 v[72:73], s[12:13], v72, s81, v[144:145]
	v_lshl_add_u64 v[92:93], v[88:89], 0, v[142:143]
	global_store_dwordx4 v[44:45], v[28:31], off offset:256
	v_cvt_pk_bf16_f32 v15, v10, v11
	v_mad_i64_i32 v[8:9], s[12:13], v8, s81, v[144:145]
	v_lshl_add_u64 v[28:29], v[24:25], 0, v[142:143]
	v_cvt_pk_bf16_f32 v124, v124, v125
	v_cvt_pk_bf16_f32 v125, v126, v127
	v_cvt_pk_bf16_f32 v126, v120, v121
	v_cvt_pk_bf16_f32 v127, v122, v123
	v_cvt_pk_bf16_f32 v104, v116, v117
	v_cvt_pk_bf16_f32 v105, v118, v119
	v_cvt_pk_bf16_f32 v106, v112, v113
	v_cvt_pk_bf16_f32 v107, v114, v115
	v_cvt_pk_bf16_f32 v88, v100, v101
	v_cvt_pk_bf16_f32 v89, v102, v103
	v_cvt_pk_bf16_f32 v90, v96, v97
	v_cvt_pk_bf16_f32 v91, v98, v99
	global_store_dwordx4 v[92:93], v[76:79], off offset:256
	v_cvt_pk_bf16_f32 v74, v80, v81
	v_cvt_pk_bf16_f32 v75, v82, v83
	v_lshl_add_u64 v[76:77], v[72:73], 0, v[142:143]
	v_cvt_pk_bf16_f32 v72, v84, v85
	v_cvt_pk_bf16_f32 v73, v86, v87
	v_cvt_pk_bf16_f32 v71, v66, v67
	v_cvt_pk_bf16_f32 v60, v60, v61
	v_cvt_pk_bf16_f32 v61, v62, v63
	v_cvt_pk_bf16_f32 v62, v56, v57
	v_cvt_pk_bf16_f32 v63, v58, v59
	v_cvt_pk_bf16_f32 v40, v52, v53
	v_cvt_pk_bf16_f32 v41, v54, v55
	v_cvt_pk_bf16_f32 v42, v48, v49
	v_cvt_pk_bf16_f32 v43, v50, v51
	v_cvt_pk_bf16_f32 v24, v36, v37
	v_cvt_pk_bf16_f32 v25, v38, v39
	v_cvt_pk_bf16_f32 v26, v32, v33
	v_cvt_pk_bf16_f32 v27, v34, v35
	global_store_dwordx4 v[28:29], v[12:15], off offset:256
	v_cvt_pk_bf16_f32 v10, v16, v17
	v_cvt_pk_bf16_f32 v11, v18, v19
	v_lshl_add_u64 v[12:13], v[8:9], 0, v[142:143]
	v_cvt_pk_bf16_f32 v8, v20, v21
	v_cvt_pk_bf16_f32 v9, v22, v23
	v_cvt_pk_bf16_f32 v4, v4, v5
	v_cvt_pk_bf16_f32 v5, v6, v7
	v_cvt_pk_bf16_f32 v6, v0, v1
	v_cvt_pk_bf16_f32 v7, v2, v3
	s_and_b64 vcc, exec, s[38:39]
	s_mov_b32 s34, s4
	s_mov_b32 s0, s6
	s_mov_b64 s[14:15], s[10:11]
	s_mov_b64 s[12:13], s[8:9]
	global_store_dwordx4 v[146:147], v[124:127], off
	global_store_dwordx4 v[108:109], v[104:107], off
	global_store_dwordx4 v[92:93], v[88:91], off
	global_store_dwordx4 v[76:77], v[72:75], off
	global_store_dwordx4 v[76:77], v[68:71], off offset:256
	global_store_dwordx4 v[64:65], v[60:63], off
	global_store_dwordx4 v[44:45], v[40:43], off
	global_store_dwordx4 v[28:29], v[24:27], off
	global_store_dwordx4 v[12:13], v[8:11], off
	global_store_dwordx4 v[12:13], v[4:7], off offset:256
	s_cbranch_vccz .LBB0_355
	s_waitcnt vmcnt(0)
	v_readlane_b32 s22, v255, 14
	s_cmpk_gt_u32 s19, 0xff
	v_readlane_b32 s23, v255, 15
	s_mov_b64 s[28:29], s[54:55]
	s_cbranch_scc1 .LBB0_362
	s_barrier
